# GEMM epilogue bulk stores write-through (sc1) to lighten the L2 write-back at the grid barriers
# baseline (speedup 1.0000x reference)
.LBB0_69:
	s_or_b64 exec, exec, s[2:3]
	s_barrier
	global_load_dwordx2 v[2:3], v[114:115], off sc1
	v_readlane_b32 s2, v255, 6
	s_add_i32 s0, s2, 1
	s_mul_hi_i32 s1, s0, 0x22000
	s_mul_i32 s0, s0, 0x22000
	s_add_u32 s0, s50, s0
	s_addc_u32 s1, s51, s1
	v_readlane_b32 s3, v255, 7
	s_add_u32 s20, s0, 0x2edf1000
	s_addc_u32 s21, s1, 0
	s_lshl_b64 s[0:1], s[2:3], 12
	s_add_u32 s18, s18, s0
	s_addc_u32 s19, s19, s1
	global_load_dwordx2 v[242:243], v[114:115], off offset:128 sc1
	global_load_dwordx2 v[244:245], v[114:115], off offset:256 sc1
	global_load_dwordx2 v[246:247], v[114:115], off offset:384 sc1
	global_load_dwordx2 v[248:249], v[114:115], off offset:1024 sc1
	global_load_dwordx2 v[180:181], v[114:115], off offset:1152 sc1
	global_load_dwordx2 v[182:183], v[114:115], off offset:1280 sc1
	global_load_dwordx2 v[172:173], v[114:115], off offset:1408 sc1
	v_lshl_add_u64 v[170:171], v[130:131], 2, s[18:19]
	global_load_dwordx4 v[196:199], v[170:171], off
	global_load_dwordx4 v[200:203], v[170:171], off offset:16
	global_load_dwordx4 v[204:207], v[170:171], off offset:512
	global_load_dwordx4 v[208:211], v[170:171], off offset:528
	s_mov_b64 s[98:99], s[94:95]
	global_load_dwordx4 v[188:191], v250, s[98:99]
	global_load_dwordx4 v[212:215], v250, s[98:99] offset:256
	s_add_u32 s98, s98, 0x8000
	s_addc_u32 s99, s99, 0
	global_load_dwordx4 v[218:221], v250, s[98:99]
	global_load_dwordx4 v[222:225], v250, s[98:99] offset:256
	s_add_u32 s98, s98, 0x8000
	s_addc_u32 s99, s99, 0
	global_load_dwordx4 v[226:229], v250, s[98:99]
	global_load_dwordx4 v[230:233], v250, s[98:99] offset:256
	s_add_u32 s98, s98, 0x8000
	s_addc_u32 s99, s99, 0
	global_load_dwordx4 v[234:237], v250, s[98:99]
	global_load_dwordx4 v[238:241], v250, s[98:99] offset:256
	s_waitcnt vmcnt(0)
	v_ffbh_u32_e32 v4, v3
	v_min_u32_e32 v4, 32, v4
	v_lshlrev_b64 v[2:3], v4, v[2:3]
	v_min_u32_e32 v2, 1, v2
	v_or_b32_e32 v2, v3, v2
	v_cvt_f32_u32_e32 v2, v2
	v_sub_u32_e32 v3, 32, v4
	v_ldexp_f32 v2, v2, v3
	v_fmamk_f32 v2, v2, 0x2e800000, v143
	v_cmp_gt_f32_e32 vcc, s90, v2
	v_mul_f32_e32 v3, 0x4b800000, v2
	s_nop 0
	v_cndmask_b32_e32 v2, v2, v3, vcc
	v_rsq_f32_e32 v2, v2
	s_nop 0
	v_mul_f32_e32 v3, 0x45800000, v2
	v_cndmask_b32_e32 v6, v2, v3, vcc
	v_lshl_add_u64 v[2:3], s[94:95], 0, v[134:135]
	v_lshl_add_u64 v[4:5], v[130:131], 1, v[2:3]
	v_lshl_add_u64 v[2:3], v[130:131], 2, s[18:19]
	s_nop 1
	v_mov_b64_e32 v[192:193], v[196:197]
	v_mov_b64_e32 v[194:195], v[198:199]
	v_mul_f32_e32 v134, v153, v6
	v_mul_f32_e32 v135, v141, v6
	v_mul_f32_e32 v140, v140, v6
	v_mul_f32_e32 v129, v129, v6
	v_mul_f32_e32 v128, v128, v6
	v_mul_f32_e32 v127, v127, v6
	v_mul_f32_e32 v126, v126, v6
	v_mul_f32_e32 v0, v0, v6
	v_mul_f32_e32 v122, v122, v6
	v_mul_f32_e32 v120, v120, v6
	v_lshlrev_b32_e32 v7, 16, v188
	v_fmac_f32_e32 v7, v192, v134
	v_and_b32_e32 v134, 0xffff0000, v188
	v_fmac_f32_e32 v134, v193, v135
	v_lshlrev_b32_e32 v135, 16, v189
	v_fmac_f32_e32 v135, v194, v140
	v_and_b32_e32 v140, 0xffff0000, v189
	v_fmac_f32_e32 v140, v195, v129
	v_cvt_pk_bf16_f32 v188, v7, v134
	v_cvt_pk_bf16_f32 v189, v135, v140
	s_nop 1
	v_mov_b64_e32 v[192:193], v[200:201]
	v_mov_b64_e32 v[194:195], v[202:203]
	v_mul_f32_e32 v129, v134, v134
	v_fmac_f32_e32 v129, v7, v7
	v_lshlrev_b32_e32 v7, 16, v190
	v_fmac_f32_e32 v129, v135, v135
	v_fmac_f32_e32 v129, v140, v140
	v_mul_f32_e32 v134, v136, v6
	v_fmac_f32_e32 v7, v192, v128
	v_and_b32_e32 v128, 0xffff0000, v190
	v_fmac_f32_e32 v128, v193, v127
	v_lshlrev_b32_e32 v127, 16, v191
	v_fmac_f32_e32 v127, v194, v126
	v_and_b32_e32 v126, 0xffff0000, v191
	v_fmac_f32_e32 v126, v195, v0
	v_mul_f32_e32 v0, v128, v128
	v_fmac_f32_e32 v0, v7, v7
	v_fmac_f32_e32 v0, v127, v127
	v_fmac_f32_e32 v0, v126, v126
	v_cvt_pk_bf16_f32 v190, v7, v128
	v_cvt_pk_bf16_f32 v191, v127, v126
	global_store_dwordx4 v[4:5], v[188:191], off sc1
	v_add_f32_e32 v0, v129, v0
	s_nop 1
	v_mov_b64_e32 v[126:127], v[212:213]
	v_mov_b64_e32 v[128:129], v[214:215]
	s_nop 1
	v_mov_b64_e32 v[188:189], v[204:205]
	v_mov_b64_e32 v[190:191], v[206:207]
	v_lshlrev_b32_e32 v7, 16, v126
	v_and_b32_e32 v126, 0xffff0000, v126
	v_fmac_f32_e32 v126, v122, v189
	v_lshlrev_b32_e32 v122, 16, v127
	v_fmac_f32_e32 v122, v120, v190
	v_and_b32_e32 v120, 0xffff0000, v127
	v_mul_f32_e32 v127, v156, v6
	v_fmac_f32_e32 v7, v134, v188
	v_fmac_f32_e32 v120, v127, v191
	v_mul_f32_e32 v127, v126, v126
	v_fmac_f32_e32 v127, v7, v7
	v_fmac_f32_e32 v127, v122, v122
	v_fmac_f32_e32 v127, v120, v120
	v_add_f32_e32 v0, v0, v127
	v_cvt_pk_bf16_f32 v126, v7, v126
	v_cvt_pk_bf16_f32 v127, v122, v120
	s_nop 1
	v_mov_b64_e32 v[188:189], v[208:209]
	v_mov_b64_e32 v[190:191], v[210:211]
	v_lshlrev_b32_e32 v7, 16, v128
	v_mul_f32_e32 v120, v137, v6
	v_mul_f32_e32 v122, v155, v6
	v_fmac_f32_e32 v7, v120, v188
	v_and_b32_e32 v120, 0xffff0000, v128
	v_fmac_f32_e32 v120, v122, v189
	v_lshlrev_b32_e32 v122, 16, v129
	v_mul_f32_e32 v128, v154, v6
	v_and_b32_e32 v129, 0xffff0000, v129
	v_mul_f32_e32 v6, v157, v6
	v_fmac_f32_e32 v129, v6, v191
	v_mul_f32_e32 v6, v120, v120
	v_fmac_f32_e32 v122, v128, v190
	v_fmac_f32_e32 v6, v7, v7
	v_fmac_f32_e32 v6, v122, v122
	v_fmac_f32_e32 v6, v129, v129
	v_add_f32_e32 v0, v0, v6
	v_cvt_pk_bf16_f32 v128, v7, v120
	v_cvt_pk_bf16_f32 v129, v122, v129
	global_store_dwordx4 v[4:5], v[126:129], off offset:256 sc1
	ds_bpermute_b32 v4, v138, v0
	s_waitcnt lgkmcnt(0)
	v_add_f32_e32 v0, v0, v4
	ds_bpermute_b32 v6, v139, v0
	v_lshl_add_u64 v[4:5], v[132:133], 3, s[20:21]
	s_and_saveexec_b64 s[2:3], s[6:7]
	s_cbranch_execz .LBB0_71
	s_waitcnt lgkmcnt(0)
	v_add_f32_e32 v0, v0, v6
	v_mul_f32_e32 v0, 0x4b800000, v0
	v_trunc_f32_e32 v0, v0
	v_mul_f32_e32 v6, 0x2f800000, v0
	v_floor_f32_e32 v7, v6
	v_fmac_f32_e32 v0, 0xcf800000, v7
	v_cvt_u32_f32_e32 v6, v0
	v_cvt_u32_f32_e32 v7, v7
	global_atomic_add_x2 v[4:5], v[6:7], off
.LBB0_71:
	s_or_b64 exec, exec, s[2:3]
	s_waitcnt lgkmcnt(0)
	s_nop 1
	v_mov_b64_e32 v[6:7], v[242:243]
	v_ffbh_u32_e32 v0, v7
	v_min_u32_e32 v0, 32, v0
	v_lshlrev_b64 v[6:7], v0, v[6:7]
	v_min_u32_e32 v6, 1, v6
	v_or_b32_e32 v6, v7, v6
	v_cvt_f32_u32_e32 v6, v6
	v_sub_u32_e32 v0, 32, v0
	v_ldexp_f32 v0, v6, v0
	v_fmamk_f32 v0, v0, 0x2e800000, v143
	v_cmp_gt_f32_e32 vcc, s90, v0
	v_mul_f32_e32 v6, 0x4b800000, v0
	s_nop 0
	v_cndmask_b32_e32 v0, v0, v6, vcc
	v_rsq_f32_e32 v0, v0
	s_nop 0
	v_mul_f32_e32 v6, 0x45800000, v0
	v_cndmask_b32_e32 v0, v0, v6, vcc
	v_lshl_add_u64 v[6:7], s[94:95], 0, v[116:117]
	v_lshl_add_u64 v[6:7], v[130:131], 1, v[6:7]
	s_nop 1
	v_mov_b64_e32 v[126:127], v[218:219]
	v_mov_b64_e32 v[128:129], v[220:221]
	s_nop 1
	v_mov_b64_e32 v[132:133], v[196:197]
	v_mov_b64_e32 v[134:135], v[198:199]
	v_mul_f32_e32 v117, v125, v0
	v_mul_f32_e32 v120, v124, v0
	v_mul_f32_e32 v113, v113, v0
	v_mul_f32_e32 v112, v112, v0
	v_mul_f32_e32 v111, v111, v0
	v_mul_f32_e32 v110, v110, v0
	v_mul_f32_e32 v102, v102, v0
	v_mul_f32_e32 v103, v103, v0
	v_mul_f32_e32 v104, v104, v0
	v_mul_f32_e32 v105, v105, v0
	v_lshlrev_b32_e32 v116, 16, v126
	v_fmac_f32_e32 v116, v132, v117
	v_and_b32_e32 v117, 0xffff0000, v126
	v_fmac_f32_e32 v117, v133, v120
	v_lshlrev_b32_e32 v122, 16, v127
	v_mul_f32_e32 v120, v123, v0
	v_mul_f32_e32 v126, v117, v117
	v_fmac_f32_e32 v122, v134, v120
	v_and_b32_e32 v123, 0xffff0000, v127
	v_mul_f32_e32 v120, v121, v0
	v_fmac_f32_e32 v126, v116, v116
	v_fmac_f32_e32 v123, v135, v120
	v_fmac_f32_e32 v126, v122, v122
	v_fmac_f32_e32 v126, v123, v123
	v_cvt_pk_bf16_f32 v120, v116, v117
	v_cvt_pk_bf16_f32 v121, v122, v123
	s_nop 1
	v_mov_b64_e32 v[122:123], v[200:201]
	v_mov_b64_e32 v[124:125], v[202:203]
	v_lshlrev_b32_e32 v116, 16, v128
	v_fmac_f32_e32 v116, v122, v113
	v_and_b32_e32 v113, 0xffff0000, v128
	v_fmac_f32_e32 v113, v123, v112
	v_lshlrev_b32_e32 v112, 16, v129
	v_fmac_f32_e32 v112, v124, v111
	v_and_b32_e32 v111, 0xffff0000, v129
	v_fmac_f32_e32 v111, v125, v110
	v_mul_f32_e32 v110, v113, v113
	v_fmac_f32_e32 v110, v116, v116
	v_fmac_f32_e32 v110, v112, v112
	v_fmac_f32_e32 v110, v111, v111
	v_cvt_pk_bf16_f32 v122, v116, v113
	v_cvt_pk_bf16_f32 v123, v112, v111
	global_store_dwordx4 v[6:7], v[120:123], off sc1
	v_add_f32_e32 v117, v126, v110
	s_nop 1
	v_mov_b64_e32 v[110:111], v[222:223]
	v_mov_b64_e32 v[112:113], v[224:225]
	s_nop 1
	v_mov_b64_e32 v[120:121], v[204:205]
	v_mov_b64_e32 v[122:123], v[206:207]
	v_lshlrev_b32_e32 v116, 16, v110
	v_fmac_f32_e32 v116, v102, v120
	v_and_b32_e32 v102, 0xffff0000, v110
	v_fmac_f32_e32 v102, v103, v121
	v_lshlrev_b32_e32 v103, 16, v111
	v_fmac_f32_e32 v103, v104, v122
	v_and_b32_e32 v104, 0xffff0000, v111
	v_fmac_f32_e32 v104, v105, v123
	v_mul_f32_e32 v105, v102, v102
	v_fmac_f32_e32 v105, v116, v116
	v_fmac_f32_e32 v105, v103, v103
	v_cvt_pk_bf16_f32 v102, v116, v102
	v_cvt_pk_bf16_f32 v103, v103, v104
	s_nop 1
	v_mov_b64_e32 v[120:121], v[208:209]
	v_mov_b64_e32 v[122:123], v[210:211]
	v_fmac_f32_e32 v105, v104, v104
	v_lshlrev_b32_e32 v104, 16, v112
	v_mul_f32_e32 v110, v118, v0
	v_mul_f32_e32 v111, v158, v0
	v_add_f32_e32 v105, v117, v105
	v_fmac_f32_e32 v104, v110, v120
	v_and_b32_e32 v110, 0xffff0000, v112
	v_fmac_f32_e32 v110, v111, v121
	v_lshlrev_b32_e32 v111, 16, v113
	v_mul_f32_e32 v112, v119, v0
	v_fmac_f32_e32 v111, v112, v122
	v_and_b32_e32 v112, 0xffff0000, v113
	v_mul_f32_e32 v0, v159, v0
	v_fmac_f32_e32 v112, v0, v123
	v_mul_f32_e32 v0, v110, v110
	v_fmac_f32_e32 v0, v104, v104
	v_fmac_f32_e32 v0, v111, v111
	v_fmac_f32_e32 v0, v112, v112
	v_add_f32_e32 v0, v105, v0
	v_cvt_pk_bf16_f32 v104, v104, v110
	v_cvt_pk_bf16_f32 v105, v111, v112
	global_store_dwordx4 v[6:7], v[102:105], off offset:256 sc1
	ds_bpermute_b32 v6, v138, v0
	s_waitcnt lgkmcnt(0)
	v_add_f32_e32 v0, v0, v6
	ds_bpermute_b32 v6, v139, v0
	s_and_saveexec_b64 s[2:3], s[6:7]
	s_cbranch_execz .LBB0_73
	s_waitcnt lgkmcnt(0)
	v_add_f32_e32 v0, v0, v6
	v_mul_f32_e32 v0, 0x4b800000, v0
	v_trunc_f32_e32 v0, v0
	v_mul_f32_e32 v6, 0x2f800000, v0
	v_floor_f32_e32 v7, v6
	v_fmac_f32_e32 v0, 0xcf800000, v7
	v_cvt_u32_f32_e32 v6, v0
	v_cvt_u32_f32_e32 v7, v7
	global_atomic_add_x2 v[4:5], v[6:7], off offset:128
.LBB0_73:
	s_or_b64 exec, exec, s[2:3]
	s_waitcnt lgkmcnt(0)
	s_nop 1
	v_mov_b64_e32 v[6:7], v[244:245]
	v_ffbh_u32_e32 v0, v7
	v_min_u32_e32 v0, 32, v0
	v_lshlrev_b64 v[6:7], v0, v[6:7]
	v_min_u32_e32 v6, 1, v6
	v_or_b32_e32 v6, v7, v6
	v_cvt_f32_u32_e32 v6, v6
	v_sub_u32_e32 v0, 32, v0
	v_ldexp_f32 v0, v6, v0
	v_fmamk_f32 v0, v0, 0x2e800000, v143
	v_cmp_gt_f32_e32 vcc, s90, v0
	v_mul_f32_e32 v6, 0x4b800000, v0
	s_nop 0
	v_cndmask_b32_e32 v0, v0, v6, vcc
	v_rsq_f32_e32 v0, v0
	s_nop 0
	v_mul_f32_e32 v6, 0x45800000, v0
	v_cndmask_b32_e32 v0, v0, v6, vcc
	v_lshl_add_u64 v[6:7], s[94:95], 0, v[98:99]
	v_lshl_add_u64 v[6:7], v[130:131], 1, v[6:7]
	s_nop 1
	v_mov_b64_e32 v[102:103], v[226:227]
	v_mov_b64_e32 v[104:105], v[228:229]
	s_nop 1
	v_mov_b64_e32 v[110:111], v[196:197]
	v_mov_b64_e32 v[112:113], v[198:199]
	v_mul_f32_e32 v99, v109, v0
	v_mul_f32_e32 v97, v97, v0
	v_mul_f32_e32 v96, v96, v0
	v_mul_f32_e32 v95, v95, v0
	v_mul_f32_e32 v94, v94, v0
	v_mul_f32_e32 v86, v86, v0
	v_mul_f32_e32 v87, v87, v0
	v_mul_f32_e32 v88, v88, v0
	v_mul_f32_e32 v89, v89, v0
	v_lshlrev_b32_e32 v98, 16, v102
	v_fmac_f32_e32 v98, v110, v99
	v_and_b32_e32 v99, 0xffff0000, v102
	v_mul_f32_e32 v102, v108, v0
	v_fmac_f32_e32 v99, v111, v102
	v_lshlrev_b32_e32 v108, 16, v103
	v_mul_f32_e32 v102, v107, v0
	v_mul_f32_e32 v110, v99, v99
	v_fmac_f32_e32 v108, v112, v102
	v_and_b32_e32 v103, 0xffff0000, v103
	v_mul_f32_e32 v102, v106, v0
	v_fmac_f32_e32 v110, v98, v98
	v_fmac_f32_e32 v103, v113, v102
	v_fmac_f32_e32 v110, v108, v108
	v_fmac_f32_e32 v110, v103, v103
	v_cvt_pk_bf16_f32 v102, v98, v99
	v_cvt_pk_bf16_f32 v103, v108, v103
	s_nop 1
	v_mov_b64_e32 v[106:107], v[200:201]
	v_mov_b64_e32 v[108:109], v[202:203]
	v_lshlrev_b32_e32 v98, 16, v104
	v_fmac_f32_e32 v98, v106, v97
	v_and_b32_e32 v97, 0xffff0000, v104
	v_fmac_f32_e32 v97, v107, v96
	v_lshlrev_b32_e32 v96, 16, v105
	v_fmac_f32_e32 v96, v108, v95
	v_and_b32_e32 v95, 0xffff0000, v105
	v_fmac_f32_e32 v95, v109, v94
	v_mul_f32_e32 v94, v97, v97
	v_fmac_f32_e32 v94, v98, v98
	v_fmac_f32_e32 v94, v96, v96
	v_fmac_f32_e32 v94, v95, v95
	v_cvt_pk_bf16_f32 v104, v98, v97
	v_cvt_pk_bf16_f32 v105, v96, v95
	global_store_dwordx4 v[6:7], v[102:105], off sc1
	v_add_f32_e32 v99, v110, v94
	s_nop 1
	v_mov_b64_e32 v[94:95], v[230:231]
	v_mov_b64_e32 v[96:97], v[232:233]
	s_nop 1
	v_mov_b64_e32 v[102:103], v[204:205]
	v_mov_b64_e32 v[104:105], v[206:207]
	v_lshlrev_b32_e32 v98, 16, v94
	v_fmac_f32_e32 v98, v86, v102
	v_and_b32_e32 v86, 0xffff0000, v94
	v_fmac_f32_e32 v86, v87, v103
	v_lshlrev_b32_e32 v87, 16, v95
	v_fmac_f32_e32 v87, v88, v104
	v_and_b32_e32 v88, 0xffff0000, v95
	v_fmac_f32_e32 v88, v89, v105
	v_mul_f32_e32 v89, v86, v86
	v_fmac_f32_e32 v89, v98, v98
	v_fmac_f32_e32 v89, v87, v87
	v_cvt_pk_bf16_f32 v86, v98, v86
	v_cvt_pk_bf16_f32 v87, v87, v88
	s_nop 1
	v_mov_b64_e32 v[102:103], v[208:209]
	v_mov_b64_e32 v[104:105], v[210:211]
	v_fmac_f32_e32 v89, v88, v88
	v_lshlrev_b32_e32 v88, 16, v96
	v_mul_f32_e32 v94, v100, v0
	v_mul_f32_e32 v95, v160, v0
	v_add_f32_e32 v89, v99, v89
	v_fmac_f32_e32 v88, v94, v102
	v_and_b32_e32 v94, 0xffff0000, v96
	v_fmac_f32_e32 v94, v95, v103
	v_lshlrev_b32_e32 v95, 16, v97
	v_mul_f32_e32 v96, v101, v0
	v_fmac_f32_e32 v95, v96, v104
	v_and_b32_e32 v96, 0xffff0000, v97
	v_mul_f32_e32 v0, v161, v0
	v_fmac_f32_e32 v96, v0, v105
	v_mul_f32_e32 v0, v94, v94
	v_fmac_f32_e32 v0, v88, v88
	v_fmac_f32_e32 v0, v95, v95
	v_fmac_f32_e32 v0, v96, v96
	v_add_f32_e32 v0, v89, v0
	v_cvt_pk_bf16_f32 v88, v88, v94
	v_cvt_pk_bf16_f32 v89, v95, v96
	global_store_dwordx4 v[6:7], v[86:89], off offset:256 sc1
	ds_bpermute_b32 v6, v138, v0
	s_waitcnt lgkmcnt(0)
	v_add_f32_e32 v0, v0, v6
	ds_bpermute_b32 v6, v139, v0
	s_and_saveexec_b64 s[2:3], s[6:7]
	s_cbranch_execz .LBB0_75
	s_waitcnt lgkmcnt(0)
	v_add_f32_e32 v0, v0, v6
	v_mul_f32_e32 v0, 0x4b800000, v0
	v_trunc_f32_e32 v0, v0
	v_mul_f32_e32 v6, 0x2f800000, v0
	v_floor_f32_e32 v7, v6
	v_fmac_f32_e32 v0, 0xcf800000, v7
	v_cvt_u32_f32_e32 v6, v0
	v_cvt_u32_f32_e32 v7, v7
	global_atomic_add_x2 v[4:5], v[6:7], off offset:256
.LBB0_75:
	s_or_b64 exec, exec, s[2:3]
	s_waitcnt lgkmcnt(0)
	s_nop 1
	v_mov_b64_e32 v[6:7], v[246:247]
	v_ffbh_u32_e32 v0, v7
	v_min_u32_e32 v0, 32, v0
	v_lshlrev_b64 v[6:7], v0, v[6:7]
	v_min_u32_e32 v6, 1, v6
	v_or_b32_e32 v6, v7, v6
	v_cvt_f32_u32_e32 v6, v6
	v_sub_u32_e32 v0, 32, v0
	v_ldexp_f32 v0, v6, v0
	v_fmamk_f32 v0, v0, 0x2e800000, v143
	v_cmp_gt_f32_e32 vcc, s90, v0
	v_mul_f32_e32 v6, 0x4b800000, v0
	s_nop 0
	v_cndmask_b32_e32 v0, v0, v6, vcc
	v_rsq_f32_e32 v0, v0
	s_nop 0
	v_mul_f32_e32 v6, 0x45800000, v0
	v_cndmask_b32_e32 v0, v0, v6, vcc
	v_lshl_add_u64 v[6:7], s[94:95], 0, v[82:83]
	v_lshl_add_u64 v[6:7], v[130:131], 1, v[6:7]
	s_nop 1
	v_mov_b64_e32 v[86:87], v[234:235]
	v_mov_b64_e32 v[88:89], v[236:237]
	s_nop 1
	v_mov_b64_e32 v[94:95], v[196:197]
	v_mov_b64_e32 v[96:97], v[198:199]
	v_mul_f32_e32 v83, v93, v0
	v_mul_f32_e32 v81, v81, v0
	v_mul_f32_e32 v80, v80, v0
	v_mul_f32_e32 v79, v79, v0
	v_mul_f32_e32 v78, v78, v0
	v_mul_f32_e32 v70, v70, v0
	v_mul_f32_e32 v71, v71, v0
	v_mul_f32_e32 v72, v72, v0
	v_mul_f32_e32 v73, v73, v0
	v_lshlrev_b32_e32 v82, 16, v86
	v_fmac_f32_e32 v82, v94, v83
	v_and_b32_e32 v83, 0xffff0000, v86
	v_mul_f32_e32 v86, v92, v0
	v_fmac_f32_e32 v83, v95, v86
	v_lshlrev_b32_e32 v92, 16, v87
	v_mul_f32_e32 v86, v91, v0
	v_mul_f32_e32 v94, v83, v83
	v_fmac_f32_e32 v92, v96, v86
	v_and_b32_e32 v87, 0xffff0000, v87
	v_mul_f32_e32 v86, v90, v0
	v_fmac_f32_e32 v94, v82, v82
	v_fmac_f32_e32 v87, v97, v86
	v_fmac_f32_e32 v94, v92, v92
	v_fmac_f32_e32 v94, v87, v87
	v_cvt_pk_bf16_f32 v86, v82, v83
	v_cvt_pk_bf16_f32 v87, v92, v87
	s_nop 1
	v_mov_b64_e32 v[90:91], v[200:201]
	v_mov_b64_e32 v[92:93], v[202:203]
	v_lshlrev_b32_e32 v82, 16, v88
	v_fmac_f32_e32 v82, v90, v81
	v_and_b32_e32 v81, 0xffff0000, v88
	v_fmac_f32_e32 v81, v91, v80
	v_lshlrev_b32_e32 v80, 16, v89
	v_fmac_f32_e32 v80, v92, v79
	v_and_b32_e32 v79, 0xffff0000, v89
	v_fmac_f32_e32 v79, v93, v78
	v_mul_f32_e32 v78, v81, v81
	v_fmac_f32_e32 v78, v82, v82
	v_fmac_f32_e32 v78, v80, v80
	v_fmac_f32_e32 v78, v79, v79
	v_cvt_pk_bf16_f32 v88, v82, v81
	v_cvt_pk_bf16_f32 v89, v80, v79
	global_store_dwordx4 v[6:7], v[86:89], off sc1
	v_add_f32_e32 v83, v94, v78
	s_nop 1
	v_mov_b64_e32 v[78:79], v[238:239]
	v_mov_b64_e32 v[80:81], v[240:241]
	s_nop 1
	v_mov_b64_e32 v[86:87], v[204:205]
	v_mov_b64_e32 v[88:89], v[206:207]
	v_lshlrev_b32_e32 v82, 16, v78
	v_fmac_f32_e32 v82, v70, v86
	v_and_b32_e32 v70, 0xffff0000, v78
	v_fmac_f32_e32 v70, v71, v87
	v_lshlrev_b32_e32 v71, 16, v79
	v_fmac_f32_e32 v71, v72, v88
	v_and_b32_e32 v72, 0xffff0000, v79
	v_fmac_f32_e32 v72, v73, v89
	v_mul_f32_e32 v73, v70, v70
	v_fmac_f32_e32 v73, v82, v82
	v_fmac_f32_e32 v73, v71, v71
	v_cvt_pk_bf16_f32 v70, v82, v70
	v_cvt_pk_bf16_f32 v71, v71, v72
	s_nop 1
	v_mov_b64_e32 v[86:87], v[208:209]
	v_mov_b64_e32 v[88:89], v[210:211]
	v_fmac_f32_e32 v73, v72, v72
	v_lshlrev_b32_e32 v72, 16, v80
	v_mul_f32_e32 v78, v84, v0
	v_mul_f32_e32 v79, v162, v0
	v_add_f32_e32 v73, v83, v73
	v_fmac_f32_e32 v72, v78, v86
	v_and_b32_e32 v78, 0xffff0000, v80
	v_fmac_f32_e32 v78, v79, v87
	v_lshlrev_b32_e32 v79, 16, v81
	v_mul_f32_e32 v80, v85, v0
	v_fmac_f32_e32 v79, v80, v88
	v_and_b32_e32 v80, 0xffff0000, v81
	v_mul_f32_e32 v0, v163, v0
	v_fmac_f32_e32 v80, v0, v89
	v_mul_f32_e32 v0, v78, v78
	v_fmac_f32_e32 v0, v72, v72
	v_fmac_f32_e32 v0, v79, v79
	v_fmac_f32_e32 v0, v80, v80
	v_add_f32_e32 v0, v73, v0
	v_cvt_pk_bf16_f32 v72, v72, v78
	v_cvt_pk_bf16_f32 v73, v79, v80
	global_store_dwordx4 v[6:7], v[70:73], off offset:256 sc1
	s_mov_b64 s[98:99], s[94:95]
	s_add_u32 s98, s98, 0x40000
	s_addc_u32 s99, s99, 0
	global_load_dwordx4 v[188:191], v250, s[98:99]
	global_load_dwordx4 v[212:215], v250, s[98:99] offset:256
	s_add_u32 s98, s98, 0x8000
	s_addc_u32 s99, s99, 0
	global_load_dwordx4 v[218:221], v250, s[98:99]
	global_load_dwordx4 v[222:225], v250, s[98:99] offset:256
	s_add_u32 s98, s98, 0x8000
	s_addc_u32 s99, s99, 0
	global_load_dwordx4 v[226:229], v250, s[98:99]
	global_load_dwordx4 v[230:233], v250, s[98:99] offset:256
	s_add_u32 s98, s98, 0x8000
	s_addc_u32 s99, s99, 0
	global_load_dwordx4 v[234:237], v250, s[98:99]
	global_load_dwordx4 v[238:241], v250, s[98:99] offset:256
	s_waitcnt vmcnt(0)
	ds_bpermute_b32 v6, v138, v0
	s_waitcnt lgkmcnt(0)
	v_add_f32_e32 v0, v0, v6
	ds_bpermute_b32 v6, v139, v0
	s_and_saveexec_b64 s[2:3], s[6:7]
	s_cbranch_execz .LBB0_77
	s_waitcnt lgkmcnt(0)
	v_add_f32_e32 v0, v0, v6
	v_mul_f32_e32 v0, 0x4b800000, v0
	v_trunc_f32_e32 v0, v0
	v_mul_f32_e32 v6, 0x2f800000, v0
	v_floor_f32_e32 v7, v6
	v_fmac_f32_e32 v0, 0xcf800000, v7
	v_cvt_u32_f32_e32 v6, v0
	v_cvt_u32_f32_e32 v7, v7
	global_atomic_add_x2 v[4:5], v[6:7], off offset:384
.LBB0_77:
	s_or_b64 exec, exec, s[2:3]
	s_waitcnt lgkmcnt(0)
	s_nop 1
	v_mov_b64_e32 v[6:7], v[248:249]
	v_ffbh_u32_e32 v0, v7
	v_min_u32_e32 v0, 32, v0
	v_lshlrev_b64 v[6:7], v0, v[6:7]
	v_min_u32_e32 v6, 1, v6
	v_or_b32_e32 v6, v7, v6
	v_cvt_f32_u32_e32 v6, v6
	v_sub_u32_e32 v0, 32, v0
	v_ldexp_f32 v0, v6, v0
	v_fmamk_f32 v0, v0, 0x2e800000, v143
	v_cmp_gt_f32_e32 vcc, s90, v0
	v_mul_f32_e32 v6, 0x4b800000, v0
	s_nop 0
	v_cndmask_b32_e32 v0, v0, v6, vcc
	v_rsq_f32_e32 v0, v0
	s_nop 0
	v_mul_f32_e32 v6, 0x45800000, v0
	v_cndmask_b32_e32 v0, v0, v6, vcc
	v_lshl_add_u64 v[6:7], s[94:95], 0, v[66:67]
	v_lshl_add_u64 v[6:7], v[130:131], 1, v[6:7]
	s_nop 1
	v_mov_b64_e32 v[70:71], v[188:189]
	v_mov_b64_e32 v[72:73], v[190:191]
	s_nop 1
	v_mov_b64_e32 v[78:79], v[196:197]
	v_mov_b64_e32 v[80:81], v[198:199]
	v_mul_f32_e32 v67, v77, v0
	v_mul_f32_e32 v65, v65, v0
	v_mul_f32_e32 v64, v64, v0
	v_mul_f32_e32 v63, v63, v0
	v_mul_f32_e32 v62, v62, v0
	v_mul_f32_e32 v54, v54, v0
	v_mul_f32_e32 v55, v55, v0
	v_mul_f32_e32 v56, v56, v0
	v_mul_f32_e32 v57, v57, v0
	v_lshlrev_b32_e32 v66, 16, v70
	v_fmac_f32_e32 v66, v78, v67
	v_and_b32_e32 v67, 0xffff0000, v70
	v_mul_f32_e32 v70, v76, v0
	v_fmac_f32_e32 v67, v79, v70
	v_lshlrev_b32_e32 v76, 16, v71
	v_mul_f32_e32 v70, v75, v0
	v_mul_f32_e32 v78, v67, v67
	v_fmac_f32_e32 v76, v80, v70
	v_and_b32_e32 v71, 0xffff0000, v71
	v_mul_f32_e32 v70, v74, v0
	v_fmac_f32_e32 v78, v66, v66
	v_fmac_f32_e32 v71, v81, v70
	v_fmac_f32_e32 v78, v76, v76
	v_fmac_f32_e32 v78, v71, v71
	v_cvt_pk_bf16_f32 v70, v66, v67
	v_cvt_pk_bf16_f32 v71, v76, v71
	s_nop 1
	v_mov_b64_e32 v[74:75], v[200:201]
	v_mov_b64_e32 v[76:77], v[202:203]
	v_lshlrev_b32_e32 v66, 16, v72
	v_fmac_f32_e32 v66, v74, v65
	v_and_b32_e32 v65, 0xffff0000, v72
	v_fmac_f32_e32 v65, v75, v64
	v_lshlrev_b32_e32 v64, 16, v73
	v_fmac_f32_e32 v64, v76, v63
	v_and_b32_e32 v63, 0xffff0000, v73
	v_fmac_f32_e32 v63, v77, v62
	v_mul_f32_e32 v62, v65, v65
	v_fmac_f32_e32 v62, v66, v66
	v_fmac_f32_e32 v62, v64, v64
	v_fmac_f32_e32 v62, v63, v63
	v_cvt_pk_bf16_f32 v72, v66, v65
	v_cvt_pk_bf16_f32 v73, v64, v63
	global_store_dwordx4 v[6:7], v[70:73], off sc1
	v_add_f32_e32 v67, v78, v62
	s_nop 1
	v_mov_b64_e32 v[62:63], v[212:213]
	v_mov_b64_e32 v[64:65], v[214:215]
	s_nop 1
	v_mov_b64_e32 v[70:71], v[204:205]
	v_mov_b64_e32 v[72:73], v[206:207]
	v_lshlrev_b32_e32 v66, 16, v62
	v_fmac_f32_e32 v66, v54, v70
	v_and_b32_e32 v54, 0xffff0000, v62
	v_fmac_f32_e32 v54, v55, v71
	v_lshlrev_b32_e32 v55, 16, v63
	v_fmac_f32_e32 v55, v56, v72
	v_and_b32_e32 v56, 0xffff0000, v63
	v_fmac_f32_e32 v56, v57, v73
	v_mul_f32_e32 v57, v54, v54
	v_fmac_f32_e32 v57, v66, v66
	v_fmac_f32_e32 v57, v55, v55
	v_cvt_pk_bf16_f32 v54, v66, v54
	v_cvt_pk_bf16_f32 v55, v55, v56
	s_nop 1
	v_mov_b64_e32 v[70:71], v[208:209]
	v_mov_b64_e32 v[72:73], v[210:211]
	v_fmac_f32_e32 v57, v56, v56
	v_lshlrev_b32_e32 v56, 16, v64
	v_mul_f32_e32 v62, v68, v0
	v_mul_f32_e32 v63, v164, v0
	v_add_f32_e32 v57, v67, v57
	v_fmac_f32_e32 v56, v62, v70
	v_and_b32_e32 v62, 0xffff0000, v64
	v_fmac_f32_e32 v62, v63, v71
	v_lshlrev_b32_e32 v63, 16, v65
	v_mul_f32_e32 v64, v69, v0
	v_fmac_f32_e32 v63, v64, v72
	v_and_b32_e32 v64, 0xffff0000, v65
	v_mul_f32_e32 v0, v165, v0
	v_fmac_f32_e32 v64, v0, v73
	v_mul_f32_e32 v0, v62, v62
	v_fmac_f32_e32 v0, v56, v56
	v_fmac_f32_e32 v0, v63, v63
	v_fmac_f32_e32 v0, v64, v64
	v_add_f32_e32 v0, v57, v0
	v_cvt_pk_bf16_f32 v56, v56, v62
	v_cvt_pk_bf16_f32 v57, v63, v64
	global_store_dwordx4 v[6:7], v[54:57], off offset:256 sc1
	ds_bpermute_b32 v6, v138, v0
	s_waitcnt lgkmcnt(0)
	v_add_f32_e32 v0, v0, v6
	ds_bpermute_b32 v6, v139, v0
	s_and_saveexec_b64 s[2:3], s[6:7]
	s_cbranch_execz .LBB0_79
	s_waitcnt lgkmcnt(0)
	v_add_f32_e32 v0, v0, v6
	v_mul_f32_e32 v0, 0x4b800000, v0
	v_trunc_f32_e32 v0, v0
	v_mul_f32_e32 v6, 0x2f800000, v0
	v_floor_f32_e32 v7, v6
	v_fmac_f32_e32 v0, 0xcf800000, v7
	v_cvt_u32_f32_e32 v6, v0
	v_cvt_u32_f32_e32 v7, v7
	global_atomic_add_x2 v[4:5], v[6:7], off offset:1024
.LBB0_79:
	s_or_b64 exec, exec, s[2:3]
	s_waitcnt lgkmcnt(0)
	s_nop 1
	v_mov_b64_e32 v[6:7], v[180:181]
	v_ffbh_u32_e32 v0, v7
	v_min_u32_e32 v0, 32, v0
	v_lshlrev_b64 v[6:7], v0, v[6:7]
	v_min_u32_e32 v6, 1, v6
	v_or_b32_e32 v6, v7, v6
	v_cvt_f32_u32_e32 v6, v6
	v_sub_u32_e32 v0, 32, v0
	v_ldexp_f32 v0, v6, v0
	v_fmamk_f32 v0, v0, 0x2e800000, v143
	v_cmp_gt_f32_e32 vcc, s90, v0
	v_mul_f32_e32 v6, 0x4b800000, v0
	s_nop 0
	v_cndmask_b32_e32 v0, v0, v6, vcc
	v_rsq_f32_e32 v0, v0
	s_nop 0
	v_mul_f32_e32 v6, 0x45800000, v0
	v_cndmask_b32_e32 v0, v0, v6, vcc
	v_lshl_add_u64 v[6:7], s[94:95], 0, v[50:51]
	v_lshl_add_u64 v[6:7], v[130:131], 1, v[6:7]
	s_nop 1
	v_mov_b64_e32 v[54:55], v[218:219]
	v_mov_b64_e32 v[56:57], v[220:221]
	s_nop 1
	v_mov_b64_e32 v[62:63], v[196:197]
	v_mov_b64_e32 v[64:65], v[198:199]
	v_mul_f32_e32 v51, v61, v0
	v_mul_f32_e32 v49, v49, v0
	v_mul_f32_e32 v48, v48, v0
	v_mul_f32_e32 v47, v47, v0
	v_mul_f32_e32 v46, v46, v0
	v_mul_f32_e32 v38, v38, v0
	v_mul_f32_e32 v39, v39, v0
	v_mul_f32_e32 v40, v40, v0
	v_mul_f32_e32 v41, v41, v0
	v_lshlrev_b32_e32 v50, 16, v54
	v_fmac_f32_e32 v50, v62, v51
	v_and_b32_e32 v51, 0xffff0000, v54
	v_mul_f32_e32 v54, v60, v0
	v_fmac_f32_e32 v51, v63, v54
	v_lshlrev_b32_e32 v60, 16, v55
	v_mul_f32_e32 v54, v59, v0
	v_mul_f32_e32 v62, v51, v51
	v_fmac_f32_e32 v60, v64, v54
	v_and_b32_e32 v55, 0xffff0000, v55
	v_mul_f32_e32 v54, v58, v0
	v_fmac_f32_e32 v62, v50, v50
	v_fmac_f32_e32 v55, v65, v54
	v_fmac_f32_e32 v62, v60, v60
	v_fmac_f32_e32 v62, v55, v55
	v_cvt_pk_bf16_f32 v54, v50, v51
	v_cvt_pk_bf16_f32 v55, v60, v55
	s_nop 1
	v_mov_b64_e32 v[58:59], v[200:201]
	v_mov_b64_e32 v[60:61], v[202:203]
	v_lshlrev_b32_e32 v50, 16, v56
	v_fmac_f32_e32 v50, v58, v49
	v_and_b32_e32 v49, 0xffff0000, v56
	v_fmac_f32_e32 v49, v59, v48
	v_lshlrev_b32_e32 v48, 16, v57
	v_fmac_f32_e32 v48, v60, v47
	v_and_b32_e32 v47, 0xffff0000, v57
	v_fmac_f32_e32 v47, v61, v46
	v_mul_f32_e32 v46, v49, v49
	v_fmac_f32_e32 v46, v50, v50
	v_fmac_f32_e32 v46, v48, v48
	v_fmac_f32_e32 v46, v47, v47
	v_cvt_pk_bf16_f32 v56, v50, v49
	v_cvt_pk_bf16_f32 v57, v48, v47
	global_store_dwordx4 v[6:7], v[54:57], off sc1
	v_add_f32_e32 v51, v62, v46
	s_nop 1
	v_mov_b64_e32 v[46:47], v[222:223]
	v_mov_b64_e32 v[48:49], v[224:225]
	s_nop 1
	v_mov_b64_e32 v[54:55], v[204:205]
	v_mov_b64_e32 v[56:57], v[206:207]
	v_lshlrev_b32_e32 v50, 16, v46
	v_fmac_f32_e32 v50, v38, v54
	v_and_b32_e32 v38, 0xffff0000, v46
	v_fmac_f32_e32 v38, v39, v55
	v_lshlrev_b32_e32 v39, 16, v47
	v_fmac_f32_e32 v39, v40, v56
	v_and_b32_e32 v40, 0xffff0000, v47
	v_fmac_f32_e32 v40, v41, v57
	v_mul_f32_e32 v41, v38, v38
	v_fmac_f32_e32 v41, v50, v50
	v_fmac_f32_e32 v41, v39, v39
	v_cvt_pk_bf16_f32 v38, v50, v38
	v_cvt_pk_bf16_f32 v39, v39, v40
	s_nop 1
	v_mov_b64_e32 v[54:55], v[208:209]
	v_mov_b64_e32 v[56:57], v[210:211]
	v_fmac_f32_e32 v41, v40, v40
	v_lshlrev_b32_e32 v40, 16, v48
	v_mul_f32_e32 v46, v52, v0
	v_mul_f32_e32 v47, v166, v0
	v_add_f32_e32 v41, v51, v41
	v_fmac_f32_e32 v40, v46, v54
	v_and_b32_e32 v46, 0xffff0000, v48
	v_fmac_f32_e32 v46, v47, v55
	v_lshlrev_b32_e32 v47, 16, v49
	v_mul_f32_e32 v48, v53, v0
	v_fmac_f32_e32 v47, v48, v56
	v_and_b32_e32 v48, 0xffff0000, v49
	v_mul_f32_e32 v0, v167, v0
	v_fmac_f32_e32 v48, v0, v57
	v_mul_f32_e32 v0, v46, v46
	v_fmac_f32_e32 v0, v40, v40
	v_fmac_f32_e32 v0, v47, v47
	v_fmac_f32_e32 v0, v48, v48
	v_add_f32_e32 v0, v41, v0
	v_cvt_pk_bf16_f32 v40, v40, v46
	v_cvt_pk_bf16_f32 v41, v47, v48
	global_store_dwordx4 v[6:7], v[38:41], off offset:256 sc1
	ds_bpermute_b32 v6, v138, v0
	s_waitcnt lgkmcnt(0)
	v_add_f32_e32 v0, v0, v6
	ds_bpermute_b32 v6, v139, v0
	s_and_saveexec_b64 s[2:3], s[6:7]
	s_cbranch_execz .LBB0_81
	s_waitcnt lgkmcnt(0)
	v_add_f32_e32 v0, v0, v6
	v_mul_f32_e32 v0, 0x4b800000, v0
	v_trunc_f32_e32 v0, v0
	v_mul_f32_e32 v6, 0x2f800000, v0
	v_floor_f32_e32 v7, v6
	v_fmac_f32_e32 v0, 0xcf800000, v7
	v_cvt_u32_f32_e32 v6, v0
	v_cvt_u32_f32_e32 v7, v7
	global_atomic_add_x2 v[4:5], v[6:7], off offset:1152
.LBB0_81:
	s_or_b64 exec, exec, s[2:3]
	s_waitcnt lgkmcnt(0)
	s_nop 1
	v_mov_b64_e32 v[6:7], v[182:183]
	v_ffbh_u32_e32 v0, v7
	v_min_u32_e32 v0, 32, v0
	v_lshlrev_b64 v[6:7], v0, v[6:7]
	v_min_u32_e32 v6, 1, v6
	v_or_b32_e32 v6, v7, v6
	v_cvt_f32_u32_e32 v6, v6
	v_sub_u32_e32 v0, 32, v0
	v_ldexp_f32 v0, v6, v0
	v_fmamk_f32 v0, v0, 0x2e800000, v143
	v_cmp_gt_f32_e32 vcc, s90, v0
	v_mul_f32_e32 v6, 0x4b800000, v0
	s_nop 0
	v_cndmask_b32_e32 v0, v0, v6, vcc
	v_rsq_f32_e32 v0, v0
	s_nop 0
	v_mul_f32_e32 v6, 0x45800000, v0
	v_cndmask_b32_e32 v0, v0, v6, vcc
	v_lshl_add_u64 v[6:7], s[94:95], 0, v[34:35]
	v_lshl_add_u64 v[6:7], v[130:131], 1, v[6:7]
	s_nop 1
	v_mov_b64_e32 v[38:39], v[226:227]
	v_mov_b64_e32 v[40:41], v[228:229]
	s_nop 1
	v_mov_b64_e32 v[46:47], v[196:197]
	v_mov_b64_e32 v[48:49], v[198:199]
	v_mul_f32_e32 v35, v45, v0
	v_mul_f32_e32 v33, v33, v0
	v_mul_f32_e32 v32, v32, v0
	v_mul_f32_e32 v31, v31, v0
	v_mul_f32_e32 v30, v30, v0
	v_mul_f32_e32 v22, v22, v0
	v_mul_f32_e32 v23, v23, v0
	v_mul_f32_e32 v24, v24, v0
	v_mul_f32_e32 v25, v25, v0
	v_lshlrev_b32_e32 v34, 16, v38
	v_fmac_f32_e32 v34, v46, v35
	v_and_b32_e32 v35, 0xffff0000, v38
	v_mul_f32_e32 v38, v44, v0
	v_fmac_f32_e32 v35, v47, v38
	v_lshlrev_b32_e32 v44, 16, v39
	v_mul_f32_e32 v38, v43, v0
	v_mul_f32_e32 v46, v35, v35
	v_fmac_f32_e32 v44, v48, v38
	v_and_b32_e32 v39, 0xffff0000, v39
	v_mul_f32_e32 v38, v42, v0
	v_fmac_f32_e32 v46, v34, v34
	v_fmac_f32_e32 v39, v49, v38
	v_fmac_f32_e32 v46, v44, v44
	v_fmac_f32_e32 v46, v39, v39
	v_cvt_pk_bf16_f32 v38, v34, v35
	v_cvt_pk_bf16_f32 v39, v44, v39
	s_nop 1
	v_mov_b64_e32 v[42:43], v[200:201]
	v_mov_b64_e32 v[44:45], v[202:203]
	v_lshlrev_b32_e32 v34, 16, v40
	v_fmac_f32_e32 v34, v42, v33
	v_and_b32_e32 v33, 0xffff0000, v40
	v_fmac_f32_e32 v33, v43, v32
	v_lshlrev_b32_e32 v32, 16, v41
	v_fmac_f32_e32 v32, v44, v31
	v_and_b32_e32 v31, 0xffff0000, v41
	v_fmac_f32_e32 v31, v45, v30
	v_mul_f32_e32 v30, v33, v33
	v_fmac_f32_e32 v30, v34, v34
	v_fmac_f32_e32 v30, v32, v32
	v_fmac_f32_e32 v30, v31, v31
	v_cvt_pk_bf16_f32 v40, v34, v33
	v_cvt_pk_bf16_f32 v41, v32, v31
	global_store_dwordx4 v[6:7], v[38:41], off sc1
	v_add_f32_e32 v35, v46, v30
	s_nop 1
	v_mov_b64_e32 v[30:31], v[230:231]
	v_mov_b64_e32 v[32:33], v[232:233]
	s_nop 1
	v_mov_b64_e32 v[38:39], v[204:205]
	v_mov_b64_e32 v[40:41], v[206:207]
	v_lshlrev_b32_e32 v34, 16, v30
	v_fmac_f32_e32 v34, v22, v38
	v_and_b32_e32 v22, 0xffff0000, v30
	v_fmac_f32_e32 v22, v23, v39
	v_lshlrev_b32_e32 v23, 16, v31
	v_fmac_f32_e32 v23, v24, v40
	v_and_b32_e32 v24, 0xffff0000, v31
	v_fmac_f32_e32 v24, v25, v41
	v_mul_f32_e32 v25, v22, v22
	v_fmac_f32_e32 v25, v34, v34
	v_fmac_f32_e32 v25, v23, v23
	v_cvt_pk_bf16_f32 v22, v34, v22
	v_cvt_pk_bf16_f32 v23, v23, v24
	s_nop 1
	v_mov_b64_e32 v[38:39], v[208:209]
	v_mov_b64_e32 v[40:41], v[210:211]
	v_fmac_f32_e32 v25, v24, v24
	v_lshlrev_b32_e32 v24, 16, v32
	v_mul_f32_e32 v30, v36, v0
	v_mul_f32_e32 v31, v168, v0
	v_add_f32_e32 v25, v35, v25
	v_fmac_f32_e32 v24, v30, v38
	v_and_b32_e32 v30, 0xffff0000, v32
	v_fmac_f32_e32 v30, v31, v39
	v_lshlrev_b32_e32 v31, 16, v33
	v_mul_f32_e32 v32, v37, v0
	v_fmac_f32_e32 v31, v32, v40
	v_and_b32_e32 v32, 0xffff0000, v33
	v_mul_f32_e32 v0, v169, v0
	v_fmac_f32_e32 v32, v0, v41
	v_mul_f32_e32 v0, v30, v30
	v_fmac_f32_e32 v0, v24, v24
	v_fmac_f32_e32 v0, v31, v31
	v_fmac_f32_e32 v0, v32, v32
	v_add_f32_e32 v0, v25, v0
	v_cvt_pk_bf16_f32 v24, v24, v30
	v_cvt_pk_bf16_f32 v25, v31, v32
	global_store_dwordx4 v[6:7], v[22:25], off offset:256 sc1
	ds_bpermute_b32 v6, v138, v0
	s_waitcnt lgkmcnt(0)
	v_add_f32_e32 v0, v0, v6
	ds_bpermute_b32 v6, v139, v0
	s_and_saveexec_b64 s[2:3], s[6:7]
	s_cbranch_execz .LBB0_83
	s_waitcnt lgkmcnt(0)
	v_add_f32_e32 v0, v0, v6
	v_mul_f32_e32 v0, 0x4b800000, v0
	v_trunc_f32_e32 v0, v0
	v_mul_f32_e32 v6, 0x2f800000, v0
	v_floor_f32_e32 v7, v6
	v_fmac_f32_e32 v0, 0xcf800000, v7
	v_cvt_u32_f32_e32 v6, v0
	v_cvt_u32_f32_e32 v7, v7
	global_atomic_add_x2 v[4:5], v[6:7], off offset:1280
.LBB0_83:
	s_or_b64 exec, exec, s[2:3]
	s_waitcnt lgkmcnt(0)
	s_nop 1
	v_mov_b64_e32 v[6:7], v[172:173]
	v_ffbh_u32_e32 v0, v7
	v_min_u32_e32 v0, 32, v0
	v_lshlrev_b64 v[6:7], v0, v[6:7]
	v_min_u32_e32 v6, 1, v6
	v_or_b32_e32 v6, v7, v6
	v_cvt_f32_u32_e32 v6, v6
	v_sub_u32_e32 v0, 32, v0
	v_ldexp_f32 v0, v6, v0
	v_fmamk_f32 v0, v0, 0x2e800000, v143
	v_cmp_gt_f32_e32 vcc, s90, v0
	v_mul_f32_e32 v6, 0x4b800000, v0
	s_nop 0
	v_cndmask_b32_e32 v0, v0, v6, vcc
	v_rsq_f32_e32 v0, v0
	s_nop 0
	v_mul_f32_e32 v6, 0x45800000, v0
	v_cndmask_b32_e32 v0, v0, v6, vcc
	v_lshl_add_u64 v[6:7], s[94:95], 0, v[18:19]
	v_lshl_add_u64 v[6:7], v[130:131], 1, v[6:7]
	s_nop 1
	v_mov_b64_e32 v[22:23], v[234:235]
	v_mov_b64_e32 v[24:25], v[236:237]
	s_nop 1
	v_mov_b64_e32 v[30:31], v[196:197]
	v_mov_b64_e32 v[32:33], v[198:199]
	v_mul_f32_e32 v19, v29, v0
	v_mul_f32_e32 v17, v17, v0
	v_mul_f32_e32 v16, v16, v0
	v_mul_f32_e32 v15, v15, v0
	v_mul_f32_e32 v14, v14, v0
	v_mul_f32_e32 v10, v10, v0
	v_mul_f32_e32 v8, v8, v0
	v_mul_f32_e32 v20, v20, v0
	v_lshlrev_b32_e32 v18, 16, v22
	v_fmac_f32_e32 v18, v30, v19
	v_and_b32_e32 v19, 0xffff0000, v22
	v_mul_f32_e32 v22, v28, v0
	v_fmac_f32_e32 v19, v31, v22
	v_lshlrev_b32_e32 v28, 16, v23
	v_mul_f32_e32 v22, v27, v0
	v_mul_f32_e32 v30, v19, v19
	v_fmac_f32_e32 v28, v32, v22
	v_and_b32_e32 v23, 0xffff0000, v23
	v_mul_f32_e32 v22, v26, v0
	v_fmac_f32_e32 v30, v18, v18
	v_fmac_f32_e32 v23, v33, v22
	v_fmac_f32_e32 v30, v28, v28
	v_fmac_f32_e32 v30, v23, v23
	v_cvt_pk_bf16_f32 v22, v18, v19
	v_cvt_pk_bf16_f32 v23, v28, v23
	s_nop 1
	v_mov_b64_e32 v[26:27], v[200:201]
	v_mov_b64_e32 v[28:29], v[202:203]
	v_lshlrev_b32_e32 v18, 16, v24
	v_fmac_f32_e32 v18, v26, v17
	v_and_b32_e32 v17, 0xffff0000, v24
	v_fmac_f32_e32 v17, v27, v16
	v_lshlrev_b32_e32 v16, 16, v25
	v_fmac_f32_e32 v16, v28, v15
	v_and_b32_e32 v15, 0xffff0000, v25
	v_fmac_f32_e32 v15, v29, v14
	v_mul_f32_e32 v14, v17, v17
	v_fmac_f32_e32 v14, v18, v18
	v_fmac_f32_e32 v14, v16, v16
	v_fmac_f32_e32 v14, v15, v15
	v_cvt_pk_bf16_f32 v24, v18, v17
	v_cvt_pk_bf16_f32 v25, v16, v15
	global_store_dwordx4 v[6:7], v[22:25], off sc1
	v_add_f32_e32 v19, v30, v14
	s_nop 1
	v_mov_b64_e32 v[14:15], v[238:239]
	v_mov_b64_e32 v[16:17], v[240:241]
	s_nop 1
	v_mov_b64_e32 v[22:23], v[204:205]
	v_mov_b64_e32 v[24:25], v[206:207]
	v_lshlrev_b32_e32 v18, 16, v14
	v_and_b32_e32 v14, 0xffff0000, v14
	v_fmac_f32_e32 v14, v10, v23
	v_lshlrev_b32_e32 v10, 16, v15
	v_fmac_f32_e32 v10, v8, v24
	v_and_b32_e32 v15, 0xffff0000, v15
	v_mul_f32_e32 v8, v9, v0
	v_fmac_f32_e32 v18, v20, v22
	v_fmac_f32_e32 v15, v8, v25
	v_mul_f32_e32 v8, v14, v14
	v_fmac_f32_e32 v8, v18, v18
	v_fmac_f32_e32 v8, v10, v10
	v_fmac_f32_e32 v8, v15, v15
	v_add_f32_e32 v19, v19, v8
	v_cvt_pk_bf16_f32 v8, v18, v14
	v_cvt_pk_bf16_f32 v9, v10, v15
	s_nop 1
	v_mov_b64_e32 v[22:23], v[208:209]
	v_mov_b64_e32 v[24:25], v[210:211]
	v_lshlrev_b32_e32 v2, 16, v16
	v_mul_f32_e32 v3, v11, v0
	v_mul_f32_e32 v10, v21, v0
	v_lshlrev_b32_e32 v11, 16, v17
	v_fmac_f32_e32 v2, v3, v22
	v_and_b32_e32 v3, 0xffff0000, v16
	v_fmac_f32_e32 v3, v10, v23
	v_mul_f32_e32 v10, v12, v0
	v_and_b32_e32 v12, 0xffff0000, v17
	v_mul_f32_e32 v0, v13, v0
	v_fmac_f32_e32 v12, v0, v25
	v_mul_f32_e32 v0, v3, v3
	v_fmac_f32_e32 v11, v10, v24
	v_fmac_f32_e32 v0, v2, v2
	v_fmac_f32_e32 v0, v11, v11
	v_fmac_f32_e32 v0, v12, v12
	v_add_f32_e32 v0, v19, v0
	v_cvt_pk_bf16_f32 v10, v2, v3
	ds_bpermute_b32 v2, v138, v0
	v_cvt_pk_bf16_f32 v11, v11, v12
	global_store_dwordx4 v[6:7], v[8:11], off offset:256 sc1
	s_waitcnt lgkmcnt(0)
	v_add_f32_e32 v0, v0, v2
	ds_bpermute_b32 v2, v139, v0
	s_and_saveexec_b64 s[2:3], s[6:7]
	s_cbranch_execz .LBB0_85
	s_waitcnt lgkmcnt(0)
	v_add_f32_e32 v0, v0, v2
	v_mul_f32_e32 v0, 0x4b800000, v0
	v_trunc_f32_e32 v0, v0
	v_mul_f32_e32 v2, 0x2f800000, v0
	v_floor_f32_e32 v3, v2
	v_fmac_f32_e32 v0, 0xcf800000, v3
	v_cvt_u32_f32_e32 v2, v0
	v_cvt_u32_f32_e32 v3, v3
	global_atomic_add_x2 v[4:5], v[2:3], off offset:1408

.LBB0_125:
	v_add_u32_e32 v140, s3, v158
	ds_read_b128 v[154:157], v140
	ds_read_b128 v[162:165], v140 offset:1024
	ds_read_b128 v[166:169], v140 offset:2048
	ds_read_b128 v[188:191], v140 offset:3072
	s_add_u32 s22, s20, 0xfffc0080
	s_addc_u32 s23, s21, -1
	s_cmp_eq_u32 s55, 12
	s_cselect_b32 s25, s5, s23
	s_cselect_b32 s24, s13, s22
	s_cselect_b32 s23, s9, s33
	s_cselect_b32 s22, s14, s15
	v_lshl_add_u64 v[140:141], s[20:21], 0, v[136:137]
	s_add_i32 m0, s34, 0xc000
	ds_read_b128 v[192:195], v160
	ds_read_b128 v[196:199], v160 offset:1024
	ds_read_b128 v[200:203], v160 offset:2048
	ds_read_b128 v[204:207], v160 offset:3072
	ds_read_b128 v[208:211], v160 offset:4096
	ds_read_b128 v[212:215], v160 offset:5120
	ds_read_b128 v[218:221], v160 offset:6144
	ds_read_b128 v[222:225], v160 offset:7168
	global_load_lds_dwordx4 v[140:141], off
	v_lshl_add_u64 v[140:141], s[20:21], 0, v[138:139]
	s_add_i32 m0, s34, 0xe000
	s_nop 0
	global_load_lds_dwordx4 v[140:141], off
	s_waitcnt lgkmcnt(8)
	s_barrier
	s_waitcnt lgkmcnt(0)
	s_setprio 1
	s_waitcnt lgkmcnt(0)
	v_mfma_f32_16x16x32_bf16 v[126:129], v[154:157], v[192:195], v[126:129]
	v_mfma_f32_16x16x32_bf16 v[122:125], v[166:169], v[192:195], v[122:125]
	v_mfma_f32_16x16x32_bf16 v[110:113], v[154:157], v[200:203], v[110:113]
	v_mfma_f32_16x16x32_bf16 v[106:109], v[166:169], v[200:203], v[106:109]
	v_mfma_f32_16x16x32_bf16 v[94:97], v[154:157], v[208:211], v[94:97]
	v_mfma_f32_16x16x32_bf16 v[90:93], v[166:169], v[208:211], v[90:93]
	v_mfma_f32_16x16x32_bf16 v[78:81], v[154:157], v[218:221], v[78:81]
	v_mfma_f32_16x16x32_bf16 v[74:77], v[166:169], v[218:221], v[74:77]
	v_mfma_f32_16x16x32_bf16 v[126:129], v[162:165], v[196:199], v[126:129]
	v_mfma_f32_16x16x32_bf16 v[122:125], v[188:191], v[196:199], v[122:125]
	v_mfma_f32_16x16x32_bf16 v[110:113], v[162:165], v[204:207], v[110:113]
	v_mfma_f32_16x16x32_bf16 v[106:109], v[188:191], v[204:207], v[106:109]
	v_mfma_f32_16x16x32_bf16 v[94:97], v[162:165], v[212:215], v[94:97]
	v_mfma_f32_16x16x32_bf16 v[90:93], v[188:191], v[212:215], v[90:93]
	v_mfma_f32_16x16x32_bf16 v[78:81], v[162:165], v[222:225], v[78:81]
	v_mfma_f32_16x16x32_bf16 v[74:77], v[188:191], v[222:225], v[74:77]
	s_setprio 0
	s_barrier
	v_add_u32_e32 v140, s36, v158
	s_mov_b32 m0, s30
	ds_read_b128 v[226:229], v140
	ds_read_b128 v[230:233], v140 offset:1024
	ds_read_b128 v[234:237], v140 offset:2048
	ds_read_b128 v[238:241], v140 offset:3072
	v_lshl_add_u64 v[140:141], s[22:23], 0, v[0:1]
	global_load_lds_dwordx4 v[140:141], off
	v_lshl_add_u64 v[144:145], s[22:23], 0, v[130:131]
	s_mov_b32 m0, s31
	s_nop 0
	global_load_lds_dwordx4 v[144:145], off
	s_barrier
	s_waitcnt lgkmcnt(0)
	s_setprio 1
	s_waitcnt lgkmcnt(0)
	v_mfma_f32_16x16x32_bf16 v[118:121], v[226:229], v[192:195], v[118:121]
	v_mfma_f32_16x16x32_bf16 v[114:117], v[234:237], v[192:195], v[114:117]
	v_mfma_f32_16x16x32_bf16 v[102:105], v[226:229], v[200:203], v[102:105]
	v_mfma_f32_16x16x32_bf16 v[98:101], v[234:237], v[200:203], v[98:101]
	v_mfma_f32_16x16x32_bf16 v[86:89], v[226:229], v[208:211], v[86:89]
	v_mfma_f32_16x16x32_bf16 v[82:85], v[234:237], v[208:211], v[82:85]
	v_mfma_f32_16x16x32_bf16 v[70:73], v[226:229], v[218:221], v[70:73]
	v_mfma_f32_16x16x32_bf16 v[66:69], v[234:237], v[218:221], v[66:69]
	v_mfma_f32_16x16x32_bf16 v[118:121], v[230:233], v[196:199], v[118:121]
	v_mfma_f32_16x16x32_bf16 v[114:117], v[238:241], v[196:199], v[114:117]
	v_mfma_f32_16x16x32_bf16 v[102:105], v[230:233], v[204:207], v[102:105]
	v_mfma_f32_16x16x32_bf16 v[98:101], v[238:241], v[204:207], v[98:101]
	v_mfma_f32_16x16x32_bf16 v[86:89], v[230:233], v[212:215], v[86:89]
	v_mfma_f32_16x16x32_bf16 v[82:85], v[238:241], v[212:215], v[82:85]
	v_mfma_f32_16x16x32_bf16 v[70:73], v[230:233], v[222:225], v[70:73]
	v_mfma_f32_16x16x32_bf16 v[66:69], v[238:241], v[222:225], v[66:69]
	s_setprio 0
	s_mov_b32 m0, s34
	v_lshl_add_u64 v[146:147], s[24:25], 0, v[134:135]
	s_barrier
	ds_read_b128 v[192:195], v160 offset:16384
	ds_read_b128 v[196:199], v160 offset:17408
	ds_read_b128 v[200:203], v160 offset:18432
	ds_read_b128 v[204:207], v160 offset:19456
	ds_read_b128 v[208:211], v160 offset:20480
	ds_read_b128 v[212:215], v160 offset:21504
	ds_read_b128 v[218:221], v160 offset:22528
	ds_read_b128 v[222:225], v160 offset:23552
	global_load_lds_dwordx4 v[146:147], off
	v_lshl_add_u64 v[170:171], s[24:25], 0, v[132:133]
	s_mov_b32 m0, s35
	s_nop 0
	global_load_lds_dwordx4 v[170:171], off
	s_barrier
	s_waitcnt lgkmcnt(0)
	s_setprio 1
	s_waitcnt lgkmcnt(0)
	v_mfma_f32_16x16x32_bf16 v[62:65], v[154:157], v[192:195], v[62:65]
	v_mfma_f32_16x16x32_bf16 v[58:61], v[166:169], v[192:195], v[58:61]
	v_mfma_f32_16x16x32_bf16 v[46:49], v[154:157], v[200:203], v[46:49]
	v_mfma_f32_16x16x32_bf16 v[42:45], v[166:169], v[200:203], v[42:45]
	v_mfma_f32_16x16x32_bf16 v[30:33], v[154:157], v[208:211], v[30:33]
	v_mfma_f32_16x16x32_bf16 v[26:29], v[166:169], v[208:211], v[26:29]
	v_mfma_f32_16x16x32_bf16 v[14:17], v[154:157], v[218:221], v[14:17]
	v_mfma_f32_16x16x32_bf16 v[10:13], v[166:169], v[218:221], v[10:13]
	v_mfma_f32_16x16x32_bf16 v[62:65], v[162:165], v[196:199], v[62:65]
	v_mfma_f32_16x16x32_bf16 v[58:61], v[188:191], v[196:199], v[58:61]
	v_mfma_f32_16x16x32_bf16 v[46:49], v[162:165], v[204:207], v[46:49]
	v_mfma_f32_16x16x32_bf16 v[42:45], v[188:191], v[204:207], v[42:45]
	v_mfma_f32_16x16x32_bf16 v[30:33], v[162:165], v[212:215], v[30:33]
	v_mfma_f32_16x16x32_bf16 v[26:29], v[188:191], v[212:215], v[26:29]
	v_mfma_f32_16x16x32_bf16 v[14:17], v[162:165], v[222:225], v[14:17]
	v_mfma_f32_16x16x32_bf16 v[10:13], v[188:191], v[222:225], v[10:13]
	s_setprio 0
	s_barrier
	s_add_u32 s56, s22, 0x40000
	s_addc_u32 s57, s23, 0
	s_mov_b32 m0, s37
	v_lshl_add_u64 v[154:155], s[56:57], 0, v[0:1]
	global_load_lds_dwordx4 v[154:155], off
	v_lshl_add_u64 v[154:155], s[56:57], 0, v[130:131]
	s_mov_b32 m0, s38
	s_nop 0
	global_load_lds_dwordx4 v[154:155], off
	s_waitcnt vmcnt(6)
	s_barrier
	s_setprio 1
	v_mfma_f32_16x16x32_bf16 v[54:57], v[226:229], v[192:195], v[54:57]
	v_mfma_f32_16x16x32_bf16 v[50:53], v[234:237], v[192:195], v[50:53]
	v_mfma_f32_16x16x32_bf16 v[38:41], v[226:229], v[200:203], v[38:41]
	v_mfma_f32_16x16x32_bf16 v[34:37], v[234:237], v[200:203], v[34:37]
	v_mfma_f32_16x16x32_bf16 v[22:25], v[226:229], v[208:211], v[22:25]
	v_mfma_f32_16x16x32_bf16 v[18:21], v[234:237], v[208:211], v[18:21]
	v_mfma_f32_16x16x32_bf16 v[6:9], v[226:229], v[218:221], v[6:9]
	v_mfma_f32_16x16x32_bf16 v[2:5], v[234:237], v[218:221], v[2:5]
	v_mfma_f32_16x16x32_bf16 v[54:57], v[230:233], v[196:199], v[54:57]
	v_mfma_f32_16x16x32_bf16 v[50:53], v[238:241], v[196:199], v[50:53]
	v_mfma_f32_16x16x32_bf16 v[38:41], v[230:233], v[204:207], v[38:41]
	v_mfma_f32_16x16x32_bf16 v[34:37], v[238:241], v[204:207], v[34:37]
	v_mfma_f32_16x16x32_bf16 v[22:25], v[230:233], v[212:215], v[22:25]
	v_mfma_f32_16x16x32_bf16 v[18:21], v[238:241], v[212:215], v[18:21]
	v_mfma_f32_16x16x32_bf16 v[6:9], v[230:233], v[222:225], v[6:9]
	v_mfma_f32_16x16x32_bf16 v[2:5], v[238:241], v[222:225], v[2:5]
	s_setprio 0
	v_add_u32_e32 v161, s41, v158
	s_barrier
	ds_read_b128 v[154:157], v161
	ds_read_b128 v[162:165], v161 offset:1024
	ds_read_b128 v[166:169], v161 offset:2048
	ds_read_b128 v[188:191], v161 offset:3072
	s_add_u32 s24, s24, 0x40000
	s_addc_u32 s25, s25, 0
	s_mov_b32 m0, s39
	v_lshl_add_u64 v[172:173], s[24:25], 0, v[134:135]
	ds_read_b128 v[192:195], v160 offset:32768
	ds_read_b128 v[196:199], v160 offset:33792
	ds_read_b128 v[200:203], v160 offset:34816
	ds_read_b128 v[204:207], v160 offset:35840
	ds_read_b128 v[208:211], v160 offset:36864
	ds_read_b128 v[212:215], v160 offset:37888
	ds_read_b128 v[218:221], v160 offset:38912
	ds_read_b128 v[222:225], v160 offset:39936
	global_load_lds_dwordx4 v[172:173], off
	v_lshl_add_u64 v[172:173], s[24:25], 0, v[132:133]
	s_mov_b32 m0, s40
	s_nop 0
	global_load_lds_dwordx4 v[172:173], off
	s_waitcnt lgkmcnt(8)
	s_barrier
	s_waitcnt lgkmcnt(0)
	s_setprio 1
	s_waitcnt lgkmcnt(0)
	v_mfma_f32_16x16x32_bf16 v[126:129], v[154:157], v[192:195], v[126:129]
	v_mfma_f32_16x16x32_bf16 v[122:125], v[166:169], v[192:195], v[122:125]
	v_mfma_f32_16x16x32_bf16 v[110:113], v[154:157], v[200:203], v[110:113]
	v_mfma_f32_16x16x32_bf16 v[106:109], v[166:169], v[200:203], v[106:109]
	v_mfma_f32_16x16x32_bf16 v[94:97], v[154:157], v[208:211], v[94:97]
	v_mfma_f32_16x16x32_bf16 v[90:93], v[166:169], v[208:211], v[90:93]
	v_mfma_f32_16x16x32_bf16 v[78:81], v[154:157], v[218:221], v[78:81]
	v_mfma_f32_16x16x32_bf16 v[74:77], v[166:169], v[218:221], v[74:77]
	v_mfma_f32_16x16x32_bf16 v[126:129], v[162:165], v[196:199], v[126:129]
	v_mfma_f32_16x16x32_bf16 v[122:125], v[188:191], v[196:199], v[122:125]
	v_mfma_f32_16x16x32_bf16 v[110:113], v[162:165], v[204:207], v[110:113]
	v_mfma_f32_16x16x32_bf16 v[106:109], v[188:191], v[204:207], v[106:109]
	v_mfma_f32_16x16x32_bf16 v[94:97], v[162:165], v[212:215], v[94:97]
	v_mfma_f32_16x16x32_bf16 v[90:93], v[188:191], v[212:215], v[90:93]
	v_mfma_f32_16x16x32_bf16 v[78:81], v[162:165], v[222:225], v[78:81]
	v_mfma_f32_16x16x32_bf16 v[74:77], v[188:191], v[222:225], v[74:77]
	s_setprio 0
	s_barrier
	s_mov_b32 m0, s42
	v_add_u32_e32 v161, s48, v158
	v_lshl_add_u64 v[140:141], v[140:141], 0, s[66:67]
	ds_read_b128 v[226:229], v161
	ds_read_b128 v[230:233], v161 offset:1024
	ds_read_b128 v[234:237], v161 offset:2048
	ds_read_b128 v[238:241], v161 offset:3072
	global_load_lds_dwordx4 v[140:141], off
	v_lshl_add_u64 v[140:141], v[144:145], 0, s[66:67]
	s_mov_b32 m0, s43
	s_nop 0
	global_load_lds_dwordx4 v[140:141], off
	s_barrier
	s_waitcnt lgkmcnt(0)
	s_setprio 1
	s_waitcnt lgkmcnt(0)
	v_mfma_f32_16x16x32_bf16 v[118:121], v[226:229], v[192:195], v[118:121]
	v_mfma_f32_16x16x32_bf16 v[114:117], v[234:237], v[192:195], v[114:117]
	v_mfma_f32_16x16x32_bf16 v[102:105], v[226:229], v[200:203], v[102:105]
	v_mfma_f32_16x16x32_bf16 v[98:101], v[234:237], v[200:203], v[98:101]
	v_mfma_f32_16x16x32_bf16 v[86:89], v[226:229], v[208:211], v[86:89]
	v_mfma_f32_16x16x32_bf16 v[82:85], v[234:237], v[208:211], v[82:85]
	v_mfma_f32_16x16x32_bf16 v[70:73], v[226:229], v[218:221], v[70:73]
	v_mfma_f32_16x16x32_bf16 v[66:69], v[234:237], v[218:221], v[66:69]
	v_mfma_f32_16x16x32_bf16 v[118:121], v[230:233], v[196:199], v[118:121]
	v_mfma_f32_16x16x32_bf16 v[114:117], v[238:241], v[196:199], v[114:117]
	v_mfma_f32_16x16x32_bf16 v[102:105], v[230:233], v[204:207], v[102:105]
	v_mfma_f32_16x16x32_bf16 v[98:101], v[238:241], v[204:207], v[98:101]
	v_mfma_f32_16x16x32_bf16 v[86:89], v[230:233], v[212:215], v[86:89]
	v_mfma_f32_16x16x32_bf16 v[82:85], v[238:241], v[212:215], v[82:85]
	v_mfma_f32_16x16x32_bf16 v[70:73], v[230:233], v[222:225], v[70:73]
	v_mfma_f32_16x16x32_bf16 v[66:69], v[238:241], v[222:225], v[66:69]
	s_setprio 0
	s_mov_b32 m0, s44
	v_lshl_add_u64 v[140:141], v[146:147], 0, s[66:67]
	s_barrier
	ds_read_b128 v[192:195], v160 offset:49152
	ds_read_b128 v[196:199], v160 offset:50176
	ds_read_b128 v[200:203], v160 offset:51200
	ds_read_b128 v[204:207], v160 offset:52224
	ds_read_b128 v[208:211], v160 offset:53248
	ds_read_b128 v[212:215], v160 offset:54272
	ds_read_b128 v[218:221], v160 offset:55296
	ds_read_b128 v[222:225], v160 offset:56320
	global_load_lds_dwordx4 v[140:141], off
	v_lshl_add_u64 v[140:141], v[170:171], 0, s[66:67]
	s_mov_b32 m0, s45
	s_nop 0
	global_load_lds_dwordx4 v[140:141], off
	s_barrier
	s_waitcnt lgkmcnt(0)
	s_setprio 1
	s_waitcnt lgkmcnt(0)
	v_mfma_f32_16x16x32_bf16 v[62:65], v[154:157], v[192:195], v[62:65]
	v_mfma_f32_16x16x32_bf16 v[58:61], v[166:169], v[192:195], v[58:61]
	v_mfma_f32_16x16x32_bf16 v[46:49], v[154:157], v[200:203], v[46:49]
	v_mfma_f32_16x16x32_bf16 v[42:45], v[166:169], v[200:203], v[42:45]
	v_mfma_f32_16x16x32_bf16 v[30:33], v[154:157], v[208:211], v[30:33]
	v_mfma_f32_16x16x32_bf16 v[26:29], v[166:169], v[208:211], v[26:29]
	v_mfma_f32_16x16x32_bf16 v[14:17], v[154:157], v[218:221], v[14:17]
	v_mfma_f32_16x16x32_bf16 v[10:13], v[166:169], v[218:221], v[10:13]
	v_mfma_f32_16x16x32_bf16 v[62:65], v[162:165], v[196:199], v[62:65]
	v_mfma_f32_16x16x32_bf16 v[58:61], v[188:191], v[196:199], v[58:61]
	v_mfma_f32_16x16x32_bf16 v[46:49], v[162:165], v[204:207], v[46:49]
	v_mfma_f32_16x16x32_bf16 v[42:45], v[188:191], v[204:207], v[42:45]
	v_mfma_f32_16x16x32_bf16 v[30:33], v[162:165], v[212:215], v[30:33]
	v_mfma_f32_16x16x32_bf16 v[26:29], v[188:191], v[212:215], v[26:29]
	v_mfma_f32_16x16x32_bf16 v[14:17], v[162:165], v[222:225], v[14:17]
	v_mfma_f32_16x16x32_bf16 v[10:13], v[188:191], v[222:225], v[10:13]
	s_setprio 0
	s_barrier
	s_add_u32 s22, s22, 0x40080
	s_addc_u32 s23, s23, 0
	s_mov_b32 m0, s52
	v_lshl_add_u64 v[140:141], s[22:23], 0, v[0:1]
	global_load_lds_dwordx4 v[140:141], off
	v_lshl_add_u64 v[140:141], s[22:23], 0, v[130:131]
	s_mov_b32 m0, s53
	s_nop 0
	global_load_lds_dwordx4 v[140:141], off
	s_waitcnt vmcnt(6)
	s_barrier
	s_setprio 1
	v_mfma_f32_16x16x32_bf16 v[54:57], v[226:229], v[192:195], v[54:57]
	v_mfma_f32_16x16x32_bf16 v[50:53], v[234:237], v[192:195], v[50:53]
	v_mfma_f32_16x16x32_bf16 v[38:41], v[226:229], v[200:203], v[38:41]
	v_mfma_f32_16x16x32_bf16 v[34:37], v[234:237], v[200:203], v[34:37]
	v_mfma_f32_16x16x32_bf16 v[22:25], v[226:229], v[208:211], v[22:25]
	v_mfma_f32_16x16x32_bf16 v[18:21], v[234:237], v[208:211], v[18:21]
	v_mfma_f32_16x16x32_bf16 v[6:9], v[226:229], v[218:221], v[6:9]
	v_mfma_f32_16x16x32_bf16 v[2:5], v[234:237], v[218:221], v[2:5]
	v_mfma_f32_16x16x32_bf16 v[54:57], v[230:233], v[196:199], v[54:57]
	v_mfma_f32_16x16x32_bf16 v[50:53], v[238:241], v[196:199], v[50:53]
	v_mfma_f32_16x16x32_bf16 v[38:41], v[230:233], v[204:207], v[38:41]
	v_mfma_f32_16x16x32_bf16 v[34:37], v[238:241], v[204:207], v[34:37]
	v_mfma_f32_16x16x32_bf16 v[22:25], v[230:233], v[212:215], v[22:25]
	v_mfma_f32_16x16x32_bf16 v[18:21], v[238:241], v[212:215], v[18:21]
	v_mfma_f32_16x16x32_bf16 v[6:9], v[230:233], v[222:225], v[6:9]
	v_mfma_f32_16x16x32_bf16 v[2:5], v[238:241], v[222:225], v[2:5]
	s_setprio 0
	s_add_i32 s55, s55, 2
	s_add_u32 s20, s20, 0x100
	s_addc_u32 s21, s21, 0
	s_add_u32 s15, s15, 0x100
	s_addc_u32 s33, s33, 0
	s_cmp_gt_u32 s55, 13
	s_barrier
	s_cbranch_scc0 .LBB0_125
	v_lshl_add_u32 v140, s2, 8, v153
	v_ashrrev_i32_e32 v141, 31, v140
	v_lshl_add_u64 v[154:155], v[140:141], 3, s[0:1]
	global_load_dwordx2 v[144:145], v[154:155], off
	global_load_dwordx2 v[192:193], v[154:155], off offset:128
	global_load_dwordx2 v[194:195], v[154:155], off offset:256
	global_load_dwordx2 v[196:197], v[154:155], off offset:384
	global_load_dwordx2 v[198:199], v[154:155], off offset:1024
	global_load_dwordx2 v[200:201], v[154:155], off offset:1152
	global_load_dwordx2 v[202:203], v[154:155], off offset:1280
	global_load_dwordx2 v[204:205], v[154:155], off offset:1408
	v_lshl_or_b32 v156, s4, 7, v159
	v_ashrrev_i32_e32 v157, 31, v156
	s_movk_i32 s2, 0x1600
	s_mov_b64 s[22:23], s[18:19]
	s_mov_b64 s[20:21], s[16:17]
	s_waitcnt vmcnt(0)
	v_ffbh_u32_e32 v141, v145
	v_min_u32_e32 v141, 32, v141
	v_lshlrev_b64 v[144:145], v141, v[144:145]
	v_min_u32_e32 v144, 1, v144
	v_or_b32_e32 v144, v145, v144
	v_cvt_f32_u32_e32 v144, v144
	v_sub_u32_e32 v141, 32, v141
	v_ldexp_f32 v141, v144, v141
	v_fmamk_f32 v141, v141, 0x2e800000, v143
	v_cmp_gt_f32_e32 vcc, s90, v141
	v_mul_f32_e32 v144, 0x4b800000, v141
	s_nop 0
	v_cndmask_b32_e32 v141, v141, v144, vcc
	v_rsq_f32_e32 v141, v141
	s_nop 0
	v_mul_f32_e32 v144, 0x45800000, v141
	v_cndmask_b32_e32 v144, v141, v144, vcc
	v_pk_mul_f32 v[126:127], v[126:127], v[144:145] op_sel_hi:[1,0]
	v_pk_mul_f32 v[118:119], v[118:119], v[144:145] op_sel_hi:[1,0]
	v_mul_f32_e32 v141, 0xbfb8aa3b, v126
	v_exp_f32_e32 v141, v141
	v_pk_mul_f32 v[128:129], v[128:129], v[144:145] op_sel_hi:[1,0]
	v_pk_mul_f32 v[120:121], v[120:121], v[144:145] op_sel_hi:[1,0]
	v_pk_mul_f32 v[114:115], v[114:115], v[144:145] op_sel_hi:[1,0]
	v_add_f32_e32 v141, 1.0, v141
	v_rcp_f32_e32 v141, v141
	v_pk_mul_f32 v[124:125], v[124:125], v[144:145] op_sel_hi:[1,0]
	v_pk_mul_f32 v[116:117], v[116:117], v[144:145] op_sel_hi:[1,0]
	v_mul_f32_e32 v126, v126, v141
	v_mul_f32_e32 v118, v118, v126
	v_mul_f32_e32 v126, 0xbfb8aa3b, v127
	v_exp_f32_e32 v126, v126
	s_nop 0
	v_add_f32_e32 v126, 1.0, v126
	v_rcp_f32_e32 v126, v126
	s_nop 0
	v_mul_f32_e32 v126, v127, v126
	v_mul_f32_e32 v119, v119, v126
	v_cvt_pk_bf16_f32 v118, v118, v119
	v_mul_f32_e32 v119, 0xbfb8aa3b, v128
	v_exp_f32_e32 v119, v119
	s_nop 0
	v_add_f32_e32 v119, 1.0, v119
	v_rcp_f32_e32 v119, v119
	s_nop 0
	v_mul_f32_e32 v119, v128, v119
	v_mul_f32_e32 v119, v120, v119
	v_mul_f32_e32 v120, 0xbfb8aa3b, v129
	v_exp_f32_e32 v120, v120
	s_nop 0
	v_add_f32_e32 v120, 1.0, v120
	v_rcp_f32_e32 v120, v120
	s_nop 0
	v_mul_f32_e32 v120, v129, v120
	v_mul_f32_e32 v120, v121, v120
	v_cvt_pk_bf16_f32 v119, v119, v120
	v_pk_mul_f32 v[120:121], v[122:123], v[144:145] op_sel_hi:[1,0]
	s_nop 0
	v_mul_f32_e32 v122, 0xbfb8aa3b, v120
	v_exp_f32_e32 v122, v122
	s_nop 0
	v_add_f32_e32 v122, 1.0, v122
	v_rcp_f32_e32 v122, v122
	s_nop 0
	v_mul_f32_e32 v120, v120, v122
	v_mul_f32_e32 v114, v114, v120
	v_mul_f32_e32 v120, 0xbfb8aa3b, v121
	v_exp_f32_e32 v120, v120
	s_nop 0
	v_add_f32_e32 v120, 1.0, v120
	v_rcp_f32_e32 v120, v120
	s_nop 0
	v_mul_f32_e32 v120, v121, v120
	v_mul_f32_e32 v115, v115, v120
	v_cvt_pk_bf16_f32 v120, v114, v115
	v_mul_f32_e32 v114, 0xbfb8aa3b, v124
	v_mul_f32_e32 v115, 0xbfb8aa3b, v125
	v_exp_f32_e32 v114, v114
	v_exp_f32_e32 v115, v115
	v_add_f32_e32 v114, 1.0, v114
	v_add_f32_e32 v115, 1.0, v115
	v_rcp_f32_e32 v114, v114
	v_rcp_f32_e32 v115, v115
	v_mul_f32_e32 v114, v124, v114
	v_mul_f32_e32 v115, v125, v115
	v_mul_f32_e32 v114, v116, v114
	v_mul_f32_e32 v115, v117, v115
	v_cvt_pk_bf16_f32 v121, v114, v115
	v_mov_b64_e32 v[114:115], s[72:73]
	v_mad_i64_i32 v[122:123], s[4:5], v140, s2, v[114:115]
	v_lshlrev_b64 v[116:117], 1, v[156:157]
	v_lshl_add_u64 v[122:123], v[122:123], 0, v[116:117]
	global_store_dwordx4 v[122:123], v[118:121], off sc1
	s_nop 1
	v_mov_b64_e32 v[118:119], v[192:193]
	s_nop 0
	v_or_b32_e32 v120, 16, v140
	v_ffbh_u32_e32 v121, v119
	v_min_u32_e32 v121, 32, v121
	v_lshlrev_b64 v[118:119], v121, v[118:119]
	v_min_u32_e32 v118, 1, v118
	v_or_b32_e32 v118, v119, v118
	v_cvt_f32_u32_e32 v118, v118
	v_sub_u32_e32 v119, 32, v121
	v_ldexp_f32 v118, v118, v119
	v_fmamk_f32 v118, v118, 0x2e800000, v143
	v_cmp_gt_f32_e32 vcc, s90, v118
	v_mul_f32_e32 v119, 0x4b800000, v118
	s_nop 0
	v_cndmask_b32_e32 v118, v118, v119, vcc
	v_rsq_f32_e32 v118, v118
	s_nop 0
	v_mul_f32_e32 v119, 0x45800000, v118
	v_cndmask_b32_e32 v118, v118, v119, vcc
	v_pk_mul_f32 v[110:111], v[110:111], v[118:119] op_sel_hi:[1,0]
	v_pk_mul_f32 v[112:113], v[112:113], v[118:119] op_sel_hi:[1,0]
	v_pk_mul_f32 v[104:105], v[104:105], v[118:119] op_sel_hi:[1,0]
	v_pk_mul_f32 v[102:103], v[102:103], v[118:119] op_sel_hi:[1,0]
	v_mul_f32_e32 v119, 0xbfb8aa3b, v110
	v_exp_f32_e32 v119, v119
	s_nop 0
	v_add_f32_e32 v119, 1.0, v119
	v_rcp_f32_e32 v119, v119
	s_nop 0
	v_mul_f32_e32 v110, v110, v119
	v_mul_f32_e32 v102, v102, v110
	v_mul_f32_e32 v110, 0xbfb8aa3b, v111
	v_exp_f32_e32 v110, v110
	v_pk_mul_f32 v[98:99], v[98:99], v[118:119] op_sel_hi:[1,0]
	v_pk_mul_f32 v[108:109], v[108:109], v[118:119] op_sel_hi:[1,0]
	v_pk_mul_f32 v[100:101], v[100:101], v[118:119] op_sel_hi:[1,0]
	v_add_f32_e32 v110, 1.0, v110
	v_rcp_f32_e32 v110, v110
	s_nop 0
	v_mul_f32_e32 v110, v111, v110
	v_mul_f32_e32 v103, v103, v110
	v_cvt_pk_bf16_f32 v102, v102, v103
	v_mul_f32_e32 v103, 0xbfb8aa3b, v112
	v_exp_f32_e32 v103, v103
	s_nop 0
	v_add_f32_e32 v103, 1.0, v103
	v_rcp_f32_e32 v103, v103
	s_nop 0
	v_mul_f32_e32 v103, v112, v103
	v_mul_f32_e32 v103, v104, v103
	v_mul_f32_e32 v104, 0xbfb8aa3b, v113
	v_exp_f32_e32 v104, v104
	s_nop 0
	v_add_f32_e32 v104, 1.0, v104
	v_rcp_f32_e32 v104, v104
	s_nop 0
	v_mul_f32_e32 v104, v113, v104
	v_mul_f32_e32 v104, v105, v104
	v_cvt_pk_bf16_f32 v103, v103, v104
	v_pk_mul_f32 v[104:105], v[106:107], v[118:119] op_sel_hi:[1,0]
	s_nop 0
	v_mul_f32_e32 v106, 0xbfb8aa3b, v104
	v_exp_f32_e32 v106, v106
	s_nop 0
	v_add_f32_e32 v106, 1.0, v106
	v_rcp_f32_e32 v106, v106
	s_nop 0
	v_mul_f32_e32 v104, v104, v106
	v_mul_f32_e32 v98, v98, v104
	v_mul_f32_e32 v104, 0xbfb8aa3b, v105
	v_exp_f32_e32 v104, v104
	s_nop 0
	v_add_f32_e32 v104, 1.0, v104
	v_rcp_f32_e32 v104, v104
	s_nop 0
	v_mul_f32_e32 v104, v105, v104
	v_mul_f32_e32 v99, v99, v104
	v_cvt_pk_bf16_f32 v104, v98, v99
	v_mul_f32_e32 v98, 0xbfb8aa3b, v108
	v_mul_f32_e32 v99, 0xbfb8aa3b, v109
	v_exp_f32_e32 v98, v98
	v_exp_f32_e32 v99, v99
	v_add_f32_e32 v98, 1.0, v98
	v_add_f32_e32 v99, 1.0, v99
	v_rcp_f32_e32 v98, v98
	v_rcp_f32_e32 v99, v99
	v_mul_f32_e32 v98, v108, v98
	v_mul_f32_e32 v99, v109, v99
	v_mul_f32_e32 v98, v100, v98
	v_mul_f32_e32 v99, v101, v99
	v_cvt_pk_bf16_f32 v105, v98, v99
	v_mad_i64_i32 v[98:99], s[4:5], v120, s2, v[114:115]
	v_lshl_add_u64 v[98:99], v[98:99], 0, v[116:117]
	global_store_dwordx4 v[98:99], v[102:105], off sc1
	s_nop 1
	v_mov_b64_e32 v[98:99], v[194:195]
	v_or_b32_e32 v100, 32, v140
	v_ffbh_u32_e32 v101, v99
	v_min_u32_e32 v101, 32, v101
	v_lshlrev_b64 v[98:99], v101, v[98:99]
	v_min_u32_e32 v98, 1, v98
	v_or_b32_e32 v98, v99, v98
	v_cvt_f32_u32_e32 v98, v98
	v_sub_u32_e32 v99, 32, v101
	v_ldexp_f32 v98, v98, v99
	v_fmamk_f32 v98, v98, 0x2e800000, v143
	v_cmp_gt_f32_e32 vcc, s90, v98
	v_mul_f32_e32 v99, 0x4b800000, v98
	s_nop 0
	v_cndmask_b32_e32 v98, v98, v99, vcc
	v_rsq_f32_e32 v98, v98
	s_nop 0
	v_mul_f32_e32 v99, 0x45800000, v98
	v_cndmask_b32_e32 v98, v98, v99, vcc
	v_pk_mul_f32 v[94:95], v[94:95], v[98:99] op_sel_hi:[1,0]
	v_pk_mul_f32 v[96:97], v[96:97], v[98:99] op_sel_hi:[1,0]
	v_pk_mul_f32 v[88:89], v[88:89], v[98:99] op_sel_hi:[1,0]
	v_pk_mul_f32 v[86:87], v[86:87], v[98:99] op_sel_hi:[1,0]
	v_mul_f32_e32 v99, 0xbfb8aa3b, v94
	v_exp_f32_e32 v99, v99
	s_nop 0
	v_add_f32_e32 v99, 1.0, v99
	v_rcp_f32_e32 v99, v99
	s_nop 0
	v_mul_f32_e32 v94, v94, v99
	v_mul_f32_e32 v86, v86, v94
	v_mul_f32_e32 v94, 0xbfb8aa3b, v95
	v_exp_f32_e32 v94, v94
	v_pk_mul_f32 v[82:83], v[82:83], v[98:99] op_sel_hi:[1,0]
	v_pk_mul_f32 v[92:93], v[92:93], v[98:99] op_sel_hi:[1,0]
	v_pk_mul_f32 v[84:85], v[84:85], v[98:99] op_sel_hi:[1,0]
	v_add_f32_e32 v94, 1.0, v94
	v_rcp_f32_e32 v94, v94
	s_nop 0
	v_mul_f32_e32 v94, v95, v94
	v_mul_f32_e32 v87, v87, v94
	v_cvt_pk_bf16_f32 v86, v86, v87
	v_mul_f32_e32 v87, 0xbfb8aa3b, v96
	v_exp_f32_e32 v87, v87
	s_nop 0
	v_add_f32_e32 v87, 1.0, v87
	v_rcp_f32_e32 v87, v87
	s_nop 0
	v_mul_f32_e32 v87, v96, v87
	v_mul_f32_e32 v87, v88, v87
	v_mul_f32_e32 v88, 0xbfb8aa3b, v97
	v_exp_f32_e32 v88, v88
	s_nop 0
	v_add_f32_e32 v88, 1.0, v88
	v_rcp_f32_e32 v88, v88
	s_nop 0
	v_mul_f32_e32 v88, v97, v88
	v_mul_f32_e32 v88, v89, v88
	v_cvt_pk_bf16_f32 v87, v87, v88
	v_pk_mul_f32 v[88:89], v[90:91], v[98:99] op_sel_hi:[1,0]
	s_nop 0
	v_mul_f32_e32 v90, 0xbfb8aa3b, v88
	v_exp_f32_e32 v90, v90
	s_nop 0
	v_add_f32_e32 v90, 1.0, v90
	v_rcp_f32_e32 v90, v90
	s_nop 0
	v_mul_f32_e32 v88, v88, v90
	v_mul_f32_e32 v82, v82, v88
	v_mul_f32_e32 v88, 0xbfb8aa3b, v89
	v_exp_f32_e32 v88, v88
	s_nop 0
	v_add_f32_e32 v88, 1.0, v88
	v_rcp_f32_e32 v88, v88
	s_nop 0
	v_mul_f32_e32 v88, v89, v88
	v_mul_f32_e32 v83, v83, v88
	v_cvt_pk_bf16_f32 v88, v82, v83
	v_mul_f32_e32 v82, 0xbfb8aa3b, v92
	v_mul_f32_e32 v83, 0xbfb8aa3b, v93
	v_exp_f32_e32 v82, v82
	v_exp_f32_e32 v83, v83
	v_add_f32_e32 v82, 1.0, v82
	v_add_f32_e32 v83, 1.0, v83
	v_rcp_f32_e32 v82, v82
	v_rcp_f32_e32 v83, v83
	v_mul_f32_e32 v82, v92, v82
	v_mul_f32_e32 v83, v93, v83
	v_mul_f32_e32 v82, v84, v82
	v_mul_f32_e32 v83, v85, v83
	v_cvt_pk_bf16_f32 v89, v82, v83
	v_mad_i64_i32 v[82:83], s[4:5], v100, s2, v[114:115]
	v_lshl_add_u64 v[82:83], v[82:83], 0, v[116:117]
	global_store_dwordx4 v[82:83], v[86:89], off sc1
	s_nop 1
	v_mov_b64_e32 v[82:83], v[196:197]
	v_or_b32_e32 v84, 48, v140
	v_ffbh_u32_e32 v85, v83
	v_min_u32_e32 v85, 32, v85
	v_lshlrev_b64 v[82:83], v85, v[82:83]
	v_min_u32_e32 v82, 1, v82
	v_or_b32_e32 v82, v83, v82
	v_cvt_f32_u32_e32 v82, v82
	v_sub_u32_e32 v83, 32, v85
	v_ldexp_f32 v82, v82, v83
	v_fmamk_f32 v82, v82, 0x2e800000, v143
	v_cmp_gt_f32_e32 vcc, s90, v82
	v_mul_f32_e32 v83, 0x4b800000, v82
	s_nop 0
	v_cndmask_b32_e32 v82, v82, v83, vcc
	v_rsq_f32_e32 v82, v82
	s_nop 0
	v_mul_f32_e32 v83, 0x45800000, v82
	v_cndmask_b32_e32 v82, v82, v83, vcc
	v_pk_mul_f32 v[78:79], v[78:79], v[82:83] op_sel_hi:[1,0]
	v_pk_mul_f32 v[80:81], v[80:81], v[82:83] op_sel_hi:[1,0]
	v_pk_mul_f32 v[72:73], v[72:73], v[82:83] op_sel_hi:[1,0]
	v_pk_mul_f32 v[70:71], v[70:71], v[82:83] op_sel_hi:[1,0]
	v_mul_f32_e32 v83, 0xbfb8aa3b, v78
	v_exp_f32_e32 v83, v83
	s_nop 0
	v_add_f32_e32 v83, 1.0, v83
	v_rcp_f32_e32 v83, v83
	s_nop 0
	v_mul_f32_e32 v78, v78, v83
	v_mul_f32_e32 v70, v70, v78
	v_mul_f32_e32 v78, 0xbfb8aa3b, v79
	v_exp_f32_e32 v78, v78
	v_pk_mul_f32 v[66:67], v[66:67], v[82:83] op_sel_hi:[1,0]
	v_pk_mul_f32 v[76:77], v[76:77], v[82:83] op_sel_hi:[1,0]
	v_pk_mul_f32 v[68:69], v[68:69], v[82:83] op_sel_hi:[1,0]
	v_add_f32_e32 v78, 1.0, v78
	v_rcp_f32_e32 v78, v78
	s_nop 0
	v_mul_f32_e32 v78, v79, v78
	v_mul_f32_e32 v71, v71, v78
	v_cvt_pk_bf16_f32 v70, v70, v71
	v_mul_f32_e32 v71, 0xbfb8aa3b, v80
	v_exp_f32_e32 v71, v71
	s_nop 0
	v_add_f32_e32 v71, 1.0, v71
	v_rcp_f32_e32 v71, v71
	s_nop 0
	v_mul_f32_e32 v71, v80, v71
	v_mul_f32_e32 v71, v72, v71
	v_mul_f32_e32 v72, 0xbfb8aa3b, v81
	v_exp_f32_e32 v72, v72
	s_nop 0
	v_add_f32_e32 v72, 1.0, v72
	v_rcp_f32_e32 v72, v72
	s_nop 0
	v_mul_f32_e32 v72, v81, v72
	v_mul_f32_e32 v72, v73, v72
	v_cvt_pk_bf16_f32 v71, v71, v72
	v_pk_mul_f32 v[72:73], v[74:75], v[82:83] op_sel_hi:[1,0]
	s_nop 0
	v_mul_f32_e32 v74, 0xbfb8aa3b, v72
	v_exp_f32_e32 v74, v74
	s_nop 0
	v_add_f32_e32 v74, 1.0, v74
	v_rcp_f32_e32 v74, v74
	s_nop 0
	v_mul_f32_e32 v72, v72, v74
	v_mul_f32_e32 v66, v66, v72
	v_mul_f32_e32 v72, 0xbfb8aa3b, v73
	v_exp_f32_e32 v72, v72
	s_nop 0
	v_add_f32_e32 v72, 1.0, v72
	v_rcp_f32_e32 v72, v72
	s_nop 0
	v_mul_f32_e32 v72, v73, v72
	v_mul_f32_e32 v67, v67, v72
	v_cvt_pk_bf16_f32 v72, v66, v67
	v_mul_f32_e32 v66, 0xbfb8aa3b, v76
	v_mul_f32_e32 v67, 0xbfb8aa3b, v77
	v_exp_f32_e32 v66, v66
	v_exp_f32_e32 v67, v67
	v_add_f32_e32 v66, 1.0, v66
	v_add_f32_e32 v67, 1.0, v67
	v_rcp_f32_e32 v66, v66
	v_rcp_f32_e32 v67, v67
	v_mul_f32_e32 v66, v76, v66
	v_mul_f32_e32 v67, v77, v67
	v_mul_f32_e32 v66, v68, v66
	v_mul_f32_e32 v67, v69, v67
	v_cvt_pk_bf16_f32 v73, v66, v67
	v_mad_i64_i32 v[66:67], s[4:5], v84, s2, v[114:115]
	v_lshl_add_u64 v[66:67], v[66:67], 0, v[116:117]
	global_store_dwordx4 v[66:67], v[70:73], off sc1
	s_nop 1
	v_mov_b64_e32 v[66:67], v[198:199]
	v_add_u32_e32 v68, 0x80, v140
	v_ffbh_u32_e32 v69, v67
	v_min_u32_e32 v69, 32, v69
	v_lshlrev_b64 v[66:67], v69, v[66:67]
	v_min_u32_e32 v66, 1, v66
	v_or_b32_e32 v66, v67, v66
	v_cvt_f32_u32_e32 v66, v66
	v_sub_u32_e32 v67, 32, v69
	v_ldexp_f32 v66, v66, v67
	v_fmamk_f32 v66, v66, 0x2e800000, v143
	v_cmp_gt_f32_e32 vcc, s90, v66
	v_mul_f32_e32 v67, 0x4b800000, v66
	s_nop 0
	v_cndmask_b32_e32 v66, v66, v67, vcc
	v_rsq_f32_e32 v66, v66
	s_nop 0
	v_mul_f32_e32 v67, 0x45800000, v66
	v_cndmask_b32_e32 v66, v66, v67, vcc
	v_pk_mul_f32 v[62:63], v[62:63], v[66:67] op_sel_hi:[1,0]
	v_pk_mul_f32 v[64:65], v[64:65], v[66:67] op_sel_hi:[1,0]
	v_pk_mul_f32 v[56:57], v[56:57], v[66:67] op_sel_hi:[1,0]
	v_pk_mul_f32 v[54:55], v[54:55], v[66:67] op_sel_hi:[1,0]
	v_mul_f32_e32 v67, 0xbfb8aa3b, v62
	v_exp_f32_e32 v67, v67
	s_nop 0
	v_add_f32_e32 v67, 1.0, v67
	v_rcp_f32_e32 v67, v67
	s_nop 0
	v_mul_f32_e32 v62, v62, v67
	v_mul_f32_e32 v54, v54, v62
	v_mul_f32_e32 v62, 0xbfb8aa3b, v63
	v_exp_f32_e32 v62, v62
	v_pk_mul_f32 v[50:51], v[50:51], v[66:67] op_sel_hi:[1,0]
	v_pk_mul_f32 v[60:61], v[60:61], v[66:67] op_sel_hi:[1,0]
	v_pk_mul_f32 v[52:53], v[52:53], v[66:67] op_sel_hi:[1,0]
	v_add_f32_e32 v62, 1.0, v62
	v_rcp_f32_e32 v62, v62
	s_nop 0
	v_mul_f32_e32 v62, v63, v62
	v_mul_f32_e32 v55, v55, v62
	v_cvt_pk_bf16_f32 v54, v54, v55
	v_mul_f32_e32 v55, 0xbfb8aa3b, v64
	v_exp_f32_e32 v55, v55
	s_nop 0
	v_add_f32_e32 v55, 1.0, v55
	v_rcp_f32_e32 v55, v55
	s_nop 0
	v_mul_f32_e32 v55, v64, v55
	v_mul_f32_e32 v55, v56, v55
	v_mul_f32_e32 v56, 0xbfb8aa3b, v65
	v_exp_f32_e32 v56, v56
	s_nop 0
	v_add_f32_e32 v56, 1.0, v56
	v_rcp_f32_e32 v56, v56
	s_nop 0
	v_mul_f32_e32 v56, v65, v56
	v_mul_f32_e32 v56, v57, v56
	v_cvt_pk_bf16_f32 v55, v55, v56
	v_pk_mul_f32 v[56:57], v[58:59], v[66:67] op_sel_hi:[1,0]
	s_nop 0
	v_mul_f32_e32 v58, 0xbfb8aa3b, v56
	v_exp_f32_e32 v58, v58
	s_nop 0
	v_add_f32_e32 v58, 1.0, v58
	v_rcp_f32_e32 v58, v58
	s_nop 0
	v_mul_f32_e32 v56, v56, v58
	v_mul_f32_e32 v50, v50, v56
	v_mul_f32_e32 v56, 0xbfb8aa3b, v57
	v_exp_f32_e32 v56, v56
	s_nop 0
	v_add_f32_e32 v56, 1.0, v56
	v_rcp_f32_e32 v56, v56
	s_nop 0
	v_mul_f32_e32 v56, v57, v56
	v_mul_f32_e32 v51, v51, v56
	v_cvt_pk_bf16_f32 v56, v50, v51
	v_mul_f32_e32 v50, 0xbfb8aa3b, v60
	v_mul_f32_e32 v51, 0xbfb8aa3b, v61
	v_exp_f32_e32 v50, v50
	v_exp_f32_e32 v51, v51
	v_add_f32_e32 v50, 1.0, v50
	v_add_f32_e32 v51, 1.0, v51
	v_rcp_f32_e32 v50, v50
	v_rcp_f32_e32 v51, v51
	v_mul_f32_e32 v50, v60, v50
	v_mul_f32_e32 v51, v61, v51
	v_mul_f32_e32 v50, v52, v50
	v_mul_f32_e32 v51, v53, v51
	v_cvt_pk_bf16_f32 v57, v50, v51
	v_mad_i64_i32 v[50:51], s[4:5], v68, s2, v[114:115]
	v_lshl_add_u64 v[50:51], v[50:51], 0, v[116:117]
	global_store_dwordx4 v[50:51], v[54:57], off sc1
	s_nop 1
	v_mov_b64_e32 v[50:51], v[200:201]
	v_add_u32_e32 v52, 0x90, v140
	v_ffbh_u32_e32 v53, v51
	v_min_u32_e32 v53, 32, v53
	v_lshlrev_b64 v[50:51], v53, v[50:51]
	v_min_u32_e32 v50, 1, v50
	v_or_b32_e32 v50, v51, v50
	v_cvt_f32_u32_e32 v50, v50
	v_sub_u32_e32 v51, 32, v53
	v_ldexp_f32 v50, v50, v51
	v_fmamk_f32 v50, v50, 0x2e800000, v143
	v_cmp_gt_f32_e32 vcc, s90, v50
	v_mul_f32_e32 v51, 0x4b800000, v50
	s_nop 0
	v_cndmask_b32_e32 v50, v50, v51, vcc
	v_rsq_f32_e32 v50, v50
	s_nop 0
	v_mul_f32_e32 v51, 0x45800000, v50
	v_cndmask_b32_e32 v50, v50, v51, vcc
	v_pk_mul_f32 v[46:47], v[46:47], v[50:51] op_sel_hi:[1,0]
	v_pk_mul_f32 v[48:49], v[48:49], v[50:51] op_sel_hi:[1,0]
	v_pk_mul_f32 v[40:41], v[40:41], v[50:51] op_sel_hi:[1,0]
	v_pk_mul_f32 v[38:39], v[38:39], v[50:51] op_sel_hi:[1,0]
	v_mul_f32_e32 v51, 0xbfb8aa3b, v46
	v_exp_f32_e32 v51, v51
	s_nop 0
	v_add_f32_e32 v51, 1.0, v51
	v_rcp_f32_e32 v51, v51
	s_nop 0
	v_mul_f32_e32 v46, v46, v51
	v_mul_f32_e32 v38, v38, v46
	v_mul_f32_e32 v46, 0xbfb8aa3b, v47
	v_exp_f32_e32 v46, v46
	v_pk_mul_f32 v[34:35], v[34:35], v[50:51] op_sel_hi:[1,0]
	v_pk_mul_f32 v[44:45], v[44:45], v[50:51] op_sel_hi:[1,0]
	v_pk_mul_f32 v[36:37], v[36:37], v[50:51] op_sel_hi:[1,0]
	v_add_f32_e32 v46, 1.0, v46
	v_rcp_f32_e32 v46, v46
	s_nop 0
	v_mul_f32_e32 v46, v47, v46
	v_mul_f32_e32 v39, v39, v46
	v_cvt_pk_bf16_f32 v38, v38, v39
	v_mul_f32_e32 v39, 0xbfb8aa3b, v48
	v_exp_f32_e32 v39, v39
	s_nop 0
	v_add_f32_e32 v39, 1.0, v39
	v_rcp_f32_e32 v39, v39
	s_nop 0
	v_mul_f32_e32 v39, v48, v39
	v_mul_f32_e32 v39, v40, v39
	v_mul_f32_e32 v40, 0xbfb8aa3b, v49
	v_exp_f32_e32 v40, v40
	s_nop 0
	v_add_f32_e32 v40, 1.0, v40
	v_rcp_f32_e32 v40, v40
	s_nop 0
	v_mul_f32_e32 v40, v49, v40
	v_mul_f32_e32 v40, v41, v40
	v_cvt_pk_bf16_f32 v39, v39, v40
	v_pk_mul_f32 v[40:41], v[42:43], v[50:51] op_sel_hi:[1,0]
	s_nop 0
	v_mul_f32_e32 v42, 0xbfb8aa3b, v40
	v_exp_f32_e32 v42, v42
	s_nop 0
	v_add_f32_e32 v42, 1.0, v42
	v_rcp_f32_e32 v42, v42
	s_nop 0
	v_mul_f32_e32 v40, v40, v42
	v_mul_f32_e32 v34, v34, v40
	v_mul_f32_e32 v40, 0xbfb8aa3b, v41
	v_exp_f32_e32 v40, v40
	s_nop 0
	v_add_f32_e32 v40, 1.0, v40
	v_rcp_f32_e32 v40, v40
	s_nop 0
	v_mul_f32_e32 v40, v41, v40
	v_mul_f32_e32 v35, v35, v40
	v_cvt_pk_bf16_f32 v40, v34, v35
	v_mul_f32_e32 v34, 0xbfb8aa3b, v44
	v_mul_f32_e32 v35, 0xbfb8aa3b, v45
	v_exp_f32_e32 v34, v34
	v_exp_f32_e32 v35, v35
	v_add_f32_e32 v34, 1.0, v34
	v_add_f32_e32 v35, 1.0, v35
	v_rcp_f32_e32 v34, v34
	v_rcp_f32_e32 v35, v35
	v_mul_f32_e32 v34, v44, v34
	v_mul_f32_e32 v35, v45, v35
	v_mul_f32_e32 v34, v36, v34
	v_mul_f32_e32 v35, v37, v35
	v_cvt_pk_bf16_f32 v41, v34, v35
	v_mad_i64_i32 v[34:35], s[4:5], v52, s2, v[114:115]
	v_lshl_add_u64 v[34:35], v[34:35], 0, v[116:117]
	global_store_dwordx4 v[34:35], v[38:41], off sc1
	s_nop 1
	v_mov_b64_e32 v[34:35], v[202:203]
	v_add_u32_e32 v36, 0xa0, v140
	v_ffbh_u32_e32 v37, v35
	v_min_u32_e32 v37, 32, v37
	v_lshlrev_b64 v[34:35], v37, v[34:35]
	v_min_u32_e32 v34, 1, v34
	v_or_b32_e32 v34, v35, v34
	v_cvt_f32_u32_e32 v34, v34
	v_sub_u32_e32 v35, 32, v37
	v_ldexp_f32 v34, v34, v35
	v_fmamk_f32 v34, v34, 0x2e800000, v143
	v_cmp_gt_f32_e32 vcc, s90, v34
	v_mul_f32_e32 v35, 0x4b800000, v34
	s_nop 0
	v_cndmask_b32_e32 v34, v34, v35, vcc
	v_rsq_f32_e32 v34, v34
	s_nop 0
	v_mul_f32_e32 v35, 0x45800000, v34
	v_cndmask_b32_e32 v34, v34, v35, vcc
	v_pk_mul_f32 v[30:31], v[30:31], v[34:35] op_sel_hi:[1,0]
	v_pk_mul_f32 v[32:33], v[32:33], v[34:35] op_sel_hi:[1,0]
	v_pk_mul_f32 v[24:25], v[24:25], v[34:35] op_sel_hi:[1,0]
	v_pk_mul_f32 v[22:23], v[22:23], v[34:35] op_sel_hi:[1,0]
	v_mul_f32_e32 v35, 0xbfb8aa3b, v30
	v_exp_f32_e32 v35, v35
	s_nop 0
	v_add_f32_e32 v35, 1.0, v35
	v_rcp_f32_e32 v35, v35
	s_nop 0
	v_mul_f32_e32 v30, v30, v35
	v_mul_f32_e32 v22, v22, v30
	v_mul_f32_e32 v30, 0xbfb8aa3b, v31
	v_exp_f32_e32 v30, v30
	v_pk_mul_f32 v[18:19], v[18:19], v[34:35] op_sel_hi:[1,0]
	v_pk_mul_f32 v[28:29], v[28:29], v[34:35] op_sel_hi:[1,0]
	v_pk_mul_f32 v[20:21], v[20:21], v[34:35] op_sel_hi:[1,0]
	v_add_f32_e32 v30, 1.0, v30
	v_rcp_f32_e32 v30, v30
	s_nop 0
	v_mul_f32_e32 v30, v31, v30
	v_mul_f32_e32 v23, v23, v30
	v_cvt_pk_bf16_f32 v22, v22, v23
	v_mul_f32_e32 v23, 0xbfb8aa3b, v32
	v_exp_f32_e32 v23, v23
	s_nop 0
	v_add_f32_e32 v23, 1.0, v23
	v_rcp_f32_e32 v23, v23
	s_nop 0
	v_mul_f32_e32 v23, v32, v23
	v_mul_f32_e32 v23, v24, v23
	v_mul_f32_e32 v24, 0xbfb8aa3b, v33
	v_exp_f32_e32 v24, v24
	s_nop 0
	v_add_f32_e32 v24, 1.0, v24
	v_rcp_f32_e32 v24, v24
	s_nop 0
	v_mul_f32_e32 v24, v33, v24
	v_mul_f32_e32 v24, v25, v24
	v_cvt_pk_bf16_f32 v23, v23, v24
	v_pk_mul_f32 v[24:25], v[26:27], v[34:35] op_sel_hi:[1,0]
	s_nop 0
	v_mul_f32_e32 v26, 0xbfb8aa3b, v24
	v_exp_f32_e32 v26, v26
	s_nop 0
	v_add_f32_e32 v26, 1.0, v26
	v_rcp_f32_e32 v26, v26
	s_nop 0
	v_mul_f32_e32 v24, v24, v26
	v_mul_f32_e32 v18, v18, v24
	v_mul_f32_e32 v24, 0xbfb8aa3b, v25
	v_exp_f32_e32 v24, v24
	s_nop 0
	v_add_f32_e32 v24, 1.0, v24
	v_rcp_f32_e32 v24, v24
	s_nop 0
	v_mul_f32_e32 v24, v25, v24
	v_mul_f32_e32 v19, v19, v24
	v_cvt_pk_bf16_f32 v24, v18, v19
	v_mul_f32_e32 v18, 0xbfb8aa3b, v28
	v_mul_f32_e32 v19, 0xbfb8aa3b, v29
	v_exp_f32_e32 v18, v18
	v_exp_f32_e32 v19, v19
	v_add_f32_e32 v18, 1.0, v18
	v_add_f32_e32 v19, 1.0, v19
	v_rcp_f32_e32 v18, v18
	v_rcp_f32_e32 v19, v19
	v_mul_f32_e32 v18, v28, v18
	v_mul_f32_e32 v19, v29, v19
	v_mul_f32_e32 v18, v20, v18
	v_mul_f32_e32 v19, v21, v19
	v_cvt_pk_bf16_f32 v25, v18, v19
	v_mad_i64_i32 v[18:19], s[4:5], v36, s2, v[114:115]
	v_lshl_add_u64 v[18:19], v[18:19], 0, v[116:117]
	global_store_dwordx4 v[18:19], v[22:25], off sc1
	s_nop 1
	v_mov_b64_e32 v[18:19], v[204:205]
	v_add_u32_e32 v20, 0xb0, v140
	v_ffbh_u32_e32 v21, v19
	v_min_u32_e32 v21, 32, v21
	v_lshlrev_b64 v[18:19], v21, v[18:19]
	v_min_u32_e32 v18, 1, v18
	v_or_b32_e32 v18, v19, v18
	v_cvt_f32_u32_e32 v18, v18
	v_sub_u32_e32 v19, 32, v21
	v_ldexp_f32 v18, v18, v19
	v_fmamk_f32 v18, v18, 0x2e800000, v143
	v_cmp_gt_f32_e32 vcc, s90, v18
	v_mul_f32_e32 v19, 0x4b800000, v18
	s_nop 0
	v_cndmask_b32_e32 v18, v18, v19, vcc
	v_rsq_f32_e32 v18, v18
	s_nop 0
	v_mul_f32_e32 v19, 0x45800000, v18
	v_cndmask_b32_e32 v18, v18, v19, vcc
	v_pk_mul_f32 v[14:15], v[14:15], v[18:19] op_sel_hi:[1,0]
	v_pk_mul_f32 v[16:17], v[16:17], v[18:19] op_sel_hi:[1,0]
	v_pk_mul_f32 v[8:9], v[8:9], v[18:19] op_sel_hi:[1,0]
	v_pk_mul_f32 v[6:7], v[6:7], v[18:19] op_sel_hi:[1,0]
	v_mul_f32_e32 v19, 0xbfb8aa3b, v14
	v_exp_f32_e32 v19, v19
	s_and_b64 vcc, exec, s[6:7]
	v_add_f32_e32 v19, 1.0, v19
	v_rcp_f32_e32 v19, v19
	s_nop 0
	v_mul_f32_e32 v14, v14, v19
	v_mul_f32_e32 v6, v6, v14
	v_mul_f32_e32 v14, 0xbfb8aa3b, v15
	v_exp_f32_e32 v14, v14
	v_pk_mul_f32 v[2:3], v[2:3], v[18:19] op_sel_hi:[1,0]
	v_pk_mul_f32 v[12:13], v[12:13], v[18:19] op_sel_hi:[1,0]
	v_pk_mul_f32 v[4:5], v[4:5], v[18:19] op_sel_hi:[1,0]
	v_add_f32_e32 v14, 1.0, v14
	v_rcp_f32_e32 v14, v14
	s_nop 0
	v_mul_f32_e32 v14, v15, v14
	v_mul_f32_e32 v7, v7, v14
	v_cvt_pk_bf16_f32 v6, v6, v7
	v_mul_f32_e32 v7, 0xbfb8aa3b, v16
	v_exp_f32_e32 v7, v7
	s_nop 0
	v_add_f32_e32 v7, 1.0, v7
	v_rcp_f32_e32 v7, v7
	s_nop 0
	v_mul_f32_e32 v7, v16, v7
	v_mul_f32_e32 v7, v8, v7
	v_mul_f32_e32 v8, 0xbfb8aa3b, v17
	v_exp_f32_e32 v8, v8
	s_nop 0
	v_add_f32_e32 v8, 1.0, v8
	v_rcp_f32_e32 v8, v8
	s_nop 0
	v_mul_f32_e32 v8, v17, v8
	v_mul_f32_e32 v8, v9, v8
	v_cvt_pk_bf16_f32 v7, v7, v8
	v_pk_mul_f32 v[8:9], v[10:11], v[18:19] op_sel_hi:[1,0]
	s_nop 0
	v_mul_f32_e32 v10, 0xbfb8aa3b, v8
	v_exp_f32_e32 v10, v10
	s_nop 0
	v_add_f32_e32 v10, 1.0, v10
	v_rcp_f32_e32 v10, v10
	s_nop 0
	v_mul_f32_e32 v8, v8, v10
	v_mul_f32_e32 v2, v2, v8
	v_mul_f32_e32 v8, 0xbfb8aa3b, v9
	v_exp_f32_e32 v8, v8
	s_nop 0
	v_add_f32_e32 v8, 1.0, v8
	v_rcp_f32_e32 v8, v8
	s_nop 0
	v_mul_f32_e32 v8, v9, v8
	v_mul_f32_e32 v3, v3, v8
	v_cvt_pk_bf16_f32 v8, v2, v3
	v_mul_f32_e32 v2, 0xbfb8aa3b, v12
	v_mul_f32_e32 v3, 0xbfb8aa3b, v13
	v_exp_f32_e32 v2, v2
	v_exp_f32_e32 v3, v3
	v_add_f32_e32 v2, 1.0, v2
	v_add_f32_e32 v3, 1.0, v3
	v_rcp_f32_e32 v2, v2
	v_rcp_f32_e32 v3, v3
	v_mul_f32_e32 v2, v12, v2
	v_mul_f32_e32 v3, v13, v3
	v_mul_f32_e32 v2, v4, v2
	v_mul_f32_e32 v3, v5, v3
	v_cvt_pk_bf16_f32 v9, v2, v3
	v_mad_i64_i32 v[2:3], s[4:5], v20, s2, v[114:115]
	v_lshl_add_u64 v[2:3], v[2:3], 0, v[116:117]
	s_mov_b32 s4, s8
	s_mov_b32 s2, s12
	global_store_dwordx4 v[2:3], v[6:9], off sc1
	s_cbranch_vccz .LBB0_122
	s_waitcnt vmcnt(0)
	s_cmpk_gt_u32 s26, 0xff
	s_cbranch_scc1 .LBB0_129
	s_barrier

.LBB0_177:
	v_lshl_add_u32 v2, s81, 8, v153
	v_ashrrev_i32_e32 v3, 31, v2
	v_lshl_or_b32 v156, s0, 8, v165
	v_lshlrev_b64 v[160:161], 11, v[2:3]
	v_ashrrev_i32_e32 v157, 31, v156
	v_lshl_add_u64 v[160:161], s[94:95], 0, v[160:161]
	v_lshl_add_u64 v[160:161], v[156:157], 1, v[160:161]
	v_lshlrev_b32_e32 v250, 11, v2
	v_lshl_add_u32 v250, v156, 1, v250
	s_mov_b64 s[98:99], s[94:95]
	global_load_dwordx4 v[168:171], v250, s[98:99]
	global_load_dwordx4 v[180:183], v250, s[98:99] offset:256
	s_add_u32 s98, s98, 0x8000
	s_addc_u32 s99, s99, 0
	global_load_dwordx4 v[192:195], v250, s[98:99]
	global_load_dwordx4 v[196:199], v250, s[98:99] offset:256
	s_add_u32 s98, s98, 0x8000
	s_addc_u32 s99, s99, 0
	global_load_dwordx4 v[200:203], v250, s[98:99]
	global_load_dwordx4 v[204:207], v250, s[98:99] offset:256
	s_add_u32 s98, s98, 0x8000
	s_addc_u32 s99, s99, 0
	global_load_dwordx4 v[208:211], v250, s[98:99]
	global_load_dwordx4 v[212:215], v250, s[98:99] offset:256
	s_add_u32 s98, s98, 0x28000
	s_addc_u32 s99, s99, 0
	global_load_dwordx4 v[218:221], v250, s[98:99]
	global_load_dwordx4 v[222:225], v250, s[98:99] offset:256
	s_add_u32 s98, s98, 0x8000
	s_addc_u32 s99, s99, 0
	global_load_dwordx4 v[226:229], v250, s[98:99]
	global_load_dwordx4 v[230:233], v250, s[98:99] offset:256
	s_add_u32 s98, s98, 0x8000
	s_addc_u32 s99, s99, 0
	global_load_dwordx4 v[234:237], v250, s[98:99]
	global_load_dwordx4 v[238:241], v250, s[98:99] offset:256
	s_add_u32 s98, s98, 0x8000
	s_addc_u32 s99, s99, 0
	global_load_dwordx4 v[242:245], v250, s[98:99]
	global_load_dwordx4 v[246:249], v250, s[98:99] offset:256
	s_waitcnt lgkmcnt(0)
	v_pk_mul_f32 v[124:125], v[124:125], v[0:1] op_sel_hi:[1,0]
	v_pk_mul_f32 v[188:189], v[130:131], v[0:1] op_sel_hi:[1,0]
	v_pk_mul_f32 v[128:129], v[128:129], v[0:1] op_sel_hi:[1,0]
	v_pk_mul_f32 v[126:127], v[126:127], v[0:1] op_sel_hi:[1,0]
	v_pk_mul_f32 v[120:121], v[120:121], v[0:1] op_sel_hi:[1,0]
	v_pk_mul_f32 v[116:117], v[116:117], v[0:1] op_sel_hi:[1,0]
	s_andn2_b64 vcc, exec, s[34:35]
	s_waitcnt vmcnt(0)
	v_lshlrev_b32_e32 v144, 16, v170
	v_lshlrev_b32_e32 v130, 16, v168
	v_add_f32_e32 v124, v124, v144
	v_and_b32_e32 v144, 0xffff0000, v170
	v_add_f32_e32 v128, v128, v130
	v_and_b32_e32 v130, 0xffff0000, v168
	v_add_f32_e32 v125, v125, v144
	v_lshlrev_b32_e32 v144, 16, v171
	v_add_f32_e32 v131, v129, v130
	v_lshlrev_b32_e32 v129, 16, v169
	v_and_b32_e32 v130, 0xffff0000, v169
	v_add_f32_e32 v126, v126, v144
	v_and_b32_e32 v144, 0xffff0000, v171
	v_add_f32_e32 v129, v188, v129
	v_add_f32_e32 v130, v189, v130
	v_cvt_pk_bf16_f32 v168, v128, v131
	v_cvt_pk_bf16_f32 v169, v129, v130
	v_add_f32_e32 v127, v127, v144
	v_cvt_pk_bf16_f32 v170, v124, v125
	v_cvt_pk_bf16_f32 v171, v126, v127
	global_store_dwordx4 v[160:161], v[168:171], off sc1
	s_nop 1
	v_mov_b64_e32 v[168:169], v[180:181]
	v_mov_b64_e32 v[170:171], v[182:183]
	v_pk_mul_f32 v[188:189], v[122:123], v[0:1] op_sel_hi:[1,0]
	v_lshlrev_b32_e32 v122, 16, v168
	v_add_f32_e32 v120, v120, v122
	v_and_b32_e32 v122, 0xffff0000, v168
	v_add_f32_e32 v123, v121, v122
	v_lshlrev_b32_e32 v121, 16, v169
	v_and_b32_e32 v122, 0xffff0000, v169
	v_add_f32_e32 v121, v188, v121
	v_add_f32_e32 v122, v189, v122
	v_pk_mul_f32 v[188:189], v[118:119], v[0:1] op_sel_hi:[1,0]
	v_lshlrev_b32_e32 v0, 16, v170
	v_add_f32_e32 v0, v116, v0
	v_and_b32_e32 v116, 0xffff0000, v170
	v_add_f32_e32 v118, v117, v116
	v_lshlrev_b32_e32 v116, 16, v171
	v_and_b32_e32 v117, 0xffff0000, v171
	v_cndmask_b32_e64 v119, 0, 1, s[34:35]
	v_add_f32_e32 v116, v188, v116
	v_add_f32_e32 v117, v189, v117
	v_cmp_ne_u32_e64 s[6:7], 1, v119
	v_cvt_pk_bf16_f32 v168, v120, v123
	v_cvt_pk_bf16_f32 v169, v121, v122
	v_cvt_pk_bf16_f32 v170, v0, v118
	v_cvt_pk_bf16_f32 v171, v116, v117
	global_store_dwordx4 v[160:161], v[168:171], off offset:256 sc1
	s_cbranch_vccnz .LBB0_181
	v_mul_f32_e32 v118, v118, v118
	v_mul_f32_e32 v119, v131, v131
	v_mul_f32_e32 v125, v125, v125
	v_fmac_f32_e32 v118, v0, v0
	v_fmac_f32_e32 v119, v128, v128
	v_fmac_f32_e32 v125, v124, v124
	v_mul_f32_e32 v123, v123, v123
	v_fmac_f32_e32 v118, v116, v116
	v_fmac_f32_e32 v119, v129, v129
	v_fmac_f32_e32 v125, v126, v126
	v_fmac_f32_e32 v123, v120, v120
	v_fmac_f32_e32 v118, v117, v117
	v_and_b32_e32 v117, 64, v177
	v_fmac_f32_e32 v119, v130, v130
	v_fmac_f32_e32 v125, v127, v127
	v_fmac_f32_e32 v123, v121, v121
	v_xor_b32_e32 v116, 16, v177
	v_add_u32_e32 v117, 64, v117
	v_add_f32_e32 v119, v119, v125
	v_fmac_f32_e32 v123, v122, v122
	v_cmp_lt_i32_e32 vcc, v116, v117
	v_add_f32_e32 v119, v119, v123
	v_add_f32_e32 v0, v118, v119
	v_cndmask_b32_e32 v116, v177, v116, vcc
	v_lshlrev_b32_e32 v116, 2, v116
	ds_bpermute_b32 v116, v116, v0
	s_waitcnt lgkmcnt(0)
	v_add_f32_e32 v0, v0, v116
	v_xor_b32_e32 v116, 32, v177
	v_cmp_lt_i32_e32 vcc, v116, v117
	s_nop 1
	v_cndmask_b32_e32 v116, v177, v116, vcc
	v_lshlrev_b32_e32 v116, 2, v116
	ds_bpermute_b32 v116, v116, v0
	s_and_saveexec_b64 s[2:3], s[8:9]
	s_cbranch_execz .LBB0_180
	s_waitcnt lgkmcnt(0)
	v_add_f32_e32 v0, v0, v116
	v_mul_f32_e32 v0, 0x4b800000, v0
	v_trunc_f32_e32 v0, v0
	v_mul_f32_e32 v116, 0x2f800000, v0
	v_floor_f32_e32 v117, v116
	v_fmac_f32_e32 v0, 0xcf800000, v117
	v_cvt_u32_f32_e32 v116, v0
	v_cvt_u32_f32_e32 v117, v117
	v_readlane_b32 s0, v255, 17
	v_readlane_b32 s1, v255, 18
	s_nop 1
	v_lshl_add_u64 v[118:119], v[2:3], 3, s[0:1]
	global_atomic_add_x2 v[118:119], v[116:117], off

.LBB0_183:
	s_waitcnt lgkmcnt(0)
	v_or_b32_e32 v116, 16, v2
	v_ashrrev_i32_e32 v117, 31, v116
	v_lshlrev_b64 v[116:117], 11, v[116:117]
	v_lshl_add_u64 v[116:117], s[94:95], 0, v[116:117]
	v_lshl_add_u64 v[116:117], v[156:157], 1, v[116:117]
	s_nop 1
	v_mov_b64_e32 v[118:119], v[192:193]
	v_mov_b64_e32 v[120:121], v[194:195]
	v_pk_mul_f32 v[122:123], v[114:115], v[0:1] op_sel_hi:[1,0]
	v_pk_mul_f32 v[112:113], v[112:113], v[0:1] op_sel_hi:[1,0]
	v_pk_mul_f32 v[108:109], v[108:109], v[0:1] op_sel_hi:[1,0]
	v_pk_mul_f32 v[110:111], v[110:111], v[0:1] op_sel_hi:[1,0]
	v_pk_mul_f32 v[104:105], v[104:105], v[0:1] op_sel_hi:[1,0]
	v_pk_mul_f32 v[102:103], v[102:103], v[0:1] op_sel_hi:[1,0]
	v_pk_mul_f32 v[100:101], v[100:101], v[0:1] op_sel_hi:[1,0]
	s_and_b64 vcc, exec, s[6:7]
	v_lshlrev_b32_e32 v114, 16, v118
	v_add_f32_e32 v112, v112, v114
	v_and_b32_e32 v114, 0xffff0000, v118
	v_add_f32_e32 v115, v113, v114
	v_lshlrev_b32_e32 v113, 16, v119
	v_add_f32_e32 v113, v122, v113
	v_lshlrev_b32_e32 v122, 16, v120
	v_and_b32_e32 v120, 0xffff0000, v120
	v_add_f32_e32 v109, v109, v120
	v_lshlrev_b32_e32 v120, 16, v121
	v_and_b32_e32 v114, 0xffff0000, v119
	v_add_f32_e32 v110, v110, v120
	v_and_b32_e32 v120, 0xffff0000, v121
	v_add_f32_e32 v114, v123, v114
	v_cvt_pk_bf16_f32 v118, v112, v115
	v_cvt_pk_bf16_f32 v119, v113, v114
	v_add_f32_e32 v108, v108, v122
	v_add_f32_e32 v111, v111, v120
	v_cvt_pk_bf16_f32 v120, v108, v109
	v_cvt_pk_bf16_f32 v121, v110, v111
	global_store_dwordx4 v[116:117], v[118:121], off sc1
	s_nop 1
	v_mov_b64_e32 v[118:119], v[196:197]
	v_mov_b64_e32 v[120:121], v[198:199]
	v_pk_mul_f32 v[122:123], v[106:107], v[0:1] op_sel_hi:[1,0]
	v_lshlrev_b32_e32 v0, 16, v120
	v_lshlrev_b32_e32 v106, 16, v118
	v_add_f32_e32 v0, v100, v0
	v_and_b32_e32 v100, 0xffff0000, v120
	v_add_f32_e32 v104, v104, v106
	v_and_b32_e32 v106, 0xffff0000, v118
	v_add_f32_e32 v100, v101, v100
	v_lshlrev_b32_e32 v101, 16, v121
	v_add_f32_e32 v107, v105, v106
	v_lshlrev_b32_e32 v105, 16, v119
	v_and_b32_e32 v106, 0xffff0000, v119
	v_add_f32_e32 v101, v102, v101
	v_and_b32_e32 v102, 0xffff0000, v121
	v_add_f32_e32 v105, v122, v105
	v_add_f32_e32 v106, v123, v106
	v_add_f32_e32 v102, v103, v102
	v_cvt_pk_bf16_f32 v118, v104, v107
	v_cvt_pk_bf16_f32 v119, v105, v106
	v_cvt_pk_bf16_f32 v120, v0, v100
	v_cvt_pk_bf16_f32 v121, v101, v102
	global_store_dwordx4 v[116:117], v[118:121], off offset:256 sc1
	s_cbranch_vccnz .LBB0_187
	v_mul_f32_e32 v103, v115, v115
	v_mul_f32_e32 v109, v109, v109
	v_fmac_f32_e32 v103, v112, v112
	v_fmac_f32_e32 v109, v108, v108
	v_mul_f32_e32 v107, v107, v107
	v_fmac_f32_e32 v103, v113, v113
	v_fmac_f32_e32 v109, v110, v110
	v_fmac_f32_e32 v107, v104, v104
	v_mul_f32_e32 v100, v100, v100
	v_fmac_f32_e32 v103, v114, v114
	v_fmac_f32_e32 v109, v111, v111
	v_fmac_f32_e32 v107, v105, v105
	v_fmac_f32_e32 v100, v0, v0
	v_add_f32_e32 v103, v103, v109
	v_fmac_f32_e32 v107, v106, v106
	v_fmac_f32_e32 v100, v101, v101
	v_add_f32_e32 v103, v103, v107
	v_fmac_f32_e32 v100, v102, v102
	v_and_b32_e32 v101, 64, v177
	v_add_f32_e32 v0, v100, v103
	v_xor_b32_e32 v100, 16, v177
	v_add_u32_e32 v101, 64, v101
	v_cmp_lt_i32_e32 vcc, v100, v101
	s_nop 1
	v_cndmask_b32_e32 v100, v177, v100, vcc
	v_lshlrev_b32_e32 v100, 2, v100
	ds_bpermute_b32 v100, v100, v0
	s_waitcnt lgkmcnt(0)
	v_add_f32_e32 v0, v0, v100
	v_xor_b32_e32 v100, 32, v177
	v_cmp_lt_i32_e32 vcc, v100, v101
	s_nop 1
	v_cndmask_b32_e32 v100, v177, v100, vcc
	v_lshlrev_b32_e32 v100, 2, v100
	ds_bpermute_b32 v100, v100, v0
	s_and_saveexec_b64 s[2:3], s[8:9]
	s_cbranch_execz .LBB0_186
	s_waitcnt lgkmcnt(0)
	v_add_f32_e32 v0, v0, v100
	v_mul_f32_e32 v0, 0x4b800000, v0
	v_trunc_f32_e32 v0, v0
	v_mul_f32_e32 v100, 0x2f800000, v0
	v_floor_f32_e32 v101, v100
	v_fmac_f32_e32 v0, 0xcf800000, v101
	v_cvt_u32_f32_e32 v100, v0
	v_cvt_u32_f32_e32 v101, v101
	v_readlane_b32 s0, v255, 17
	v_readlane_b32 s1, v255, 18
	s_nop 1
	v_lshl_add_u64 v[102:103], v[2:3], 3, s[0:1]
	global_atomic_add_x2 v[102:103], v[100:101], off offset:128

.LBB0_189:
	s_waitcnt lgkmcnt(0)
	v_or_b32_e32 v100, 32, v2
	v_ashrrev_i32_e32 v101, 31, v100
	v_lshlrev_b64 v[100:101], 11, v[100:101]
	v_lshl_add_u64 v[100:101], s[94:95], 0, v[100:101]
	v_lshl_add_u64 v[100:101], v[156:157], 1, v[100:101]
	s_nop 1
	v_mov_b64_e32 v[102:103], v[200:201]
	v_mov_b64_e32 v[104:105], v[202:203]
	v_pk_mul_f32 v[106:107], v[98:99], v[0:1] op_sel_hi:[1,0]
	v_pk_mul_f32 v[96:97], v[96:97], v[0:1] op_sel_hi:[1,0]
	v_pk_mul_f32 v[92:93], v[92:93], v[0:1] op_sel_hi:[1,0]
	v_pk_mul_f32 v[94:95], v[94:95], v[0:1] op_sel_hi:[1,0]
	v_pk_mul_f32 v[88:89], v[88:89], v[0:1] op_sel_hi:[1,0]
	v_pk_mul_f32 v[86:87], v[86:87], v[0:1] op_sel_hi:[1,0]
	v_pk_mul_f32 v[84:85], v[84:85], v[0:1] op_sel_hi:[1,0]
	s_and_b64 vcc, exec, s[6:7]
	v_lshlrev_b32_e32 v98, 16, v102
	v_add_f32_e32 v96, v96, v98
	v_and_b32_e32 v98, 0xffff0000, v102
	v_add_f32_e32 v99, v97, v98
	v_lshlrev_b32_e32 v97, 16, v103
	v_add_f32_e32 v97, v106, v97
	v_lshlrev_b32_e32 v106, 16, v104
	v_and_b32_e32 v104, 0xffff0000, v104
	v_add_f32_e32 v93, v93, v104
	v_lshlrev_b32_e32 v104, 16, v105
	v_and_b32_e32 v98, 0xffff0000, v103
	v_add_f32_e32 v94, v94, v104
	v_and_b32_e32 v104, 0xffff0000, v105
	v_add_f32_e32 v98, v107, v98
	v_cvt_pk_bf16_f32 v102, v96, v99
	v_cvt_pk_bf16_f32 v103, v97, v98
	v_add_f32_e32 v92, v92, v106
	v_add_f32_e32 v95, v95, v104
	v_cvt_pk_bf16_f32 v104, v92, v93
	v_cvt_pk_bf16_f32 v105, v94, v95
	global_store_dwordx4 v[100:101], v[102:105], off sc1
	s_nop 1
	v_mov_b64_e32 v[102:103], v[204:205]
	v_mov_b64_e32 v[104:105], v[206:207]
	v_pk_mul_f32 v[106:107], v[90:91], v[0:1] op_sel_hi:[1,0]
	v_lshlrev_b32_e32 v0, 16, v104
	v_lshlrev_b32_e32 v90, 16, v102
	v_add_f32_e32 v0, v84, v0
	v_and_b32_e32 v84, 0xffff0000, v104
	v_add_f32_e32 v88, v88, v90
	v_and_b32_e32 v90, 0xffff0000, v102
	v_add_f32_e32 v84, v85, v84
	v_lshlrev_b32_e32 v85, 16, v105
	v_add_f32_e32 v91, v89, v90
	v_lshlrev_b32_e32 v89, 16, v103
	v_and_b32_e32 v90, 0xffff0000, v103
	v_add_f32_e32 v85, v86, v85
	v_and_b32_e32 v86, 0xffff0000, v105
	v_add_f32_e32 v89, v106, v89
	v_add_f32_e32 v90, v107, v90
	v_add_f32_e32 v86, v87, v86
	v_cvt_pk_bf16_f32 v102, v88, v91
	v_cvt_pk_bf16_f32 v103, v89, v90
	v_cvt_pk_bf16_f32 v104, v0, v84
	v_cvt_pk_bf16_f32 v105, v85, v86
	global_store_dwordx4 v[100:101], v[102:105], off offset:256 sc1
	s_cbranch_vccnz .LBB0_193
	v_mul_f32_e32 v87, v99, v99
	v_mul_f32_e32 v93, v93, v93
	v_fmac_f32_e32 v87, v96, v96
	v_fmac_f32_e32 v93, v92, v92
	v_mul_f32_e32 v91, v91, v91
	v_fmac_f32_e32 v87, v97, v97
	v_fmac_f32_e32 v93, v94, v94
	v_fmac_f32_e32 v91, v88, v88
	v_mul_f32_e32 v84, v84, v84
	v_fmac_f32_e32 v87, v98, v98
	v_fmac_f32_e32 v93, v95, v95
	v_fmac_f32_e32 v91, v89, v89
	v_fmac_f32_e32 v84, v0, v0
	v_add_f32_e32 v87, v87, v93
	v_fmac_f32_e32 v91, v90, v90
	v_fmac_f32_e32 v84, v85, v85
	v_add_f32_e32 v87, v87, v91
	v_fmac_f32_e32 v84, v86, v86
	v_and_b32_e32 v85, 64, v177
	v_add_f32_e32 v0, v84, v87
	v_xor_b32_e32 v84, 16, v177
	v_add_u32_e32 v85, 64, v85
	v_cmp_lt_i32_e32 vcc, v84, v85
	s_nop 1
	v_cndmask_b32_e32 v84, v177, v84, vcc
	v_lshlrev_b32_e32 v84, 2, v84
	ds_bpermute_b32 v84, v84, v0
	s_waitcnt lgkmcnt(0)
	v_add_f32_e32 v0, v0, v84
	v_xor_b32_e32 v84, 32, v177
	v_cmp_lt_i32_e32 vcc, v84, v85
	s_nop 1
	v_cndmask_b32_e32 v84, v177, v84, vcc
	v_lshlrev_b32_e32 v84, 2, v84
	ds_bpermute_b32 v84, v84, v0
	s_and_saveexec_b64 s[2:3], s[8:9]
	s_cbranch_execz .LBB0_192
	s_waitcnt lgkmcnt(0)
	v_add_f32_e32 v0, v0, v84
	v_mul_f32_e32 v0, 0x4b800000, v0
	v_trunc_f32_e32 v0, v0
	v_mul_f32_e32 v84, 0x2f800000, v0
	v_floor_f32_e32 v85, v84
	v_fmac_f32_e32 v0, 0xcf800000, v85
	v_cvt_u32_f32_e32 v84, v0
	v_cvt_u32_f32_e32 v85, v85
	v_readlane_b32 s0, v255, 17
	v_readlane_b32 s1, v255, 18
	s_nop 1
	v_lshl_add_u64 v[86:87], v[2:3], 3, s[0:1]
	global_atomic_add_x2 v[86:87], v[84:85], off offset:256

.LBB0_195:
	s_waitcnt lgkmcnt(0)
	v_or_b32_e32 v84, 48, v2
	v_ashrrev_i32_e32 v85, 31, v84
	v_lshlrev_b64 v[84:85], 11, v[84:85]
	v_lshl_add_u64 v[84:85], s[94:95], 0, v[84:85]
	v_lshl_add_u64 v[84:85], v[156:157], 1, v[84:85]
	s_nop 1
	v_mov_b64_e32 v[86:87], v[208:209]
	v_mov_b64_e32 v[88:89], v[210:211]
	v_pk_mul_f32 v[90:91], v[82:83], v[0:1] op_sel_hi:[1,0]
	v_pk_mul_f32 v[80:81], v[80:81], v[0:1] op_sel_hi:[1,0]
	v_pk_mul_f32 v[76:77], v[76:77], v[0:1] op_sel_hi:[1,0]
	v_pk_mul_f32 v[78:79], v[78:79], v[0:1] op_sel_hi:[1,0]
	v_pk_mul_f32 v[72:73], v[72:73], v[0:1] op_sel_hi:[1,0]
	v_pk_mul_f32 v[70:71], v[70:71], v[0:1] op_sel_hi:[1,0]
	v_pk_mul_f32 v[68:69], v[68:69], v[0:1] op_sel_hi:[1,0]
	s_and_b64 vcc, exec, s[6:7]
	v_lshlrev_b32_e32 v82, 16, v86
	v_add_f32_e32 v80, v80, v82
	v_and_b32_e32 v82, 0xffff0000, v86
	v_add_f32_e32 v83, v81, v82
	v_lshlrev_b32_e32 v81, 16, v87
	v_add_f32_e32 v81, v90, v81
	v_lshlrev_b32_e32 v90, 16, v88
	v_and_b32_e32 v88, 0xffff0000, v88
	v_add_f32_e32 v77, v77, v88
	v_lshlrev_b32_e32 v88, 16, v89
	v_and_b32_e32 v82, 0xffff0000, v87
	v_add_f32_e32 v78, v78, v88
	v_and_b32_e32 v88, 0xffff0000, v89
	v_add_f32_e32 v82, v91, v82
	v_cvt_pk_bf16_f32 v86, v80, v83
	v_cvt_pk_bf16_f32 v87, v81, v82
	v_add_f32_e32 v76, v76, v90
	v_add_f32_e32 v79, v79, v88
	v_cvt_pk_bf16_f32 v88, v76, v77
	v_cvt_pk_bf16_f32 v89, v78, v79
	global_store_dwordx4 v[84:85], v[86:89], off sc1
	s_nop 1
	v_mov_b64_e32 v[86:87], v[212:213]
	v_mov_b64_e32 v[88:89], v[214:215]
	v_pk_mul_f32 v[90:91], v[74:75], v[0:1] op_sel_hi:[1,0]
	v_lshlrev_b32_e32 v0, 16, v88
	v_lshlrev_b32_e32 v74, 16, v86
	v_add_f32_e32 v0, v68, v0
	v_and_b32_e32 v68, 0xffff0000, v88
	v_add_f32_e32 v72, v72, v74
	v_and_b32_e32 v74, 0xffff0000, v86
	v_add_f32_e32 v68, v69, v68
	v_lshlrev_b32_e32 v69, 16, v89
	v_add_f32_e32 v75, v73, v74
	v_lshlrev_b32_e32 v73, 16, v87
	v_and_b32_e32 v74, 0xffff0000, v87
	v_add_f32_e32 v69, v70, v69
	v_and_b32_e32 v70, 0xffff0000, v89
	v_add_f32_e32 v73, v90, v73
	v_add_f32_e32 v74, v91, v74
	v_add_f32_e32 v70, v71, v70
	v_cvt_pk_bf16_f32 v86, v72, v75
	v_cvt_pk_bf16_f32 v87, v73, v74
	v_cvt_pk_bf16_f32 v88, v0, v68
	v_cvt_pk_bf16_f32 v89, v69, v70
	global_store_dwordx4 v[84:85], v[86:89], off offset:256 sc1
	s_cbranch_vccnz .LBB0_199
	v_mul_f32_e32 v71, v83, v83
	v_mul_f32_e32 v77, v77, v77
	v_fmac_f32_e32 v71, v80, v80
	v_fmac_f32_e32 v77, v76, v76
	v_mul_f32_e32 v75, v75, v75
	v_fmac_f32_e32 v71, v81, v81
	v_fmac_f32_e32 v77, v78, v78
	v_fmac_f32_e32 v75, v72, v72
	v_mul_f32_e32 v68, v68, v68
	v_fmac_f32_e32 v71, v82, v82
	v_fmac_f32_e32 v77, v79, v79
	v_fmac_f32_e32 v75, v73, v73
	v_fmac_f32_e32 v68, v0, v0
	v_add_f32_e32 v71, v71, v77
	v_fmac_f32_e32 v75, v74, v74
	v_fmac_f32_e32 v68, v69, v69
	v_add_f32_e32 v71, v71, v75
	v_fmac_f32_e32 v68, v70, v70
	v_and_b32_e32 v69, 64, v177
	v_add_f32_e32 v0, v68, v71
	v_xor_b32_e32 v68, 16, v177
	v_add_u32_e32 v69, 64, v69
	v_cmp_lt_i32_e32 vcc, v68, v69
	s_nop 1
	v_cndmask_b32_e32 v68, v177, v68, vcc
	v_lshlrev_b32_e32 v68, 2, v68
	ds_bpermute_b32 v68, v68, v0
	s_waitcnt lgkmcnt(0)
	v_add_f32_e32 v0, v0, v68
	v_xor_b32_e32 v68, 32, v177
	v_cmp_lt_i32_e32 vcc, v68, v69
	s_nop 1
	v_cndmask_b32_e32 v68, v177, v68, vcc
	v_lshlrev_b32_e32 v68, 2, v68
	ds_bpermute_b32 v68, v68, v0
	s_and_saveexec_b64 s[2:3], s[8:9]
	s_cbranch_execz .LBB0_198
	s_waitcnt lgkmcnt(0)
	v_add_f32_e32 v0, v0, v68
	v_mul_f32_e32 v0, 0x4b800000, v0
	v_trunc_f32_e32 v0, v0
	v_mul_f32_e32 v68, 0x2f800000, v0
	v_floor_f32_e32 v69, v68
	v_fmac_f32_e32 v0, 0xcf800000, v69
	v_cvt_u32_f32_e32 v68, v0
	v_cvt_u32_f32_e32 v69, v69
	v_readlane_b32 s0, v255, 17
	v_readlane_b32 s1, v255, 18
	s_nop 1
	v_lshl_add_u64 v[70:71], v[2:3], 3, s[0:1]
	global_atomic_add_x2 v[70:71], v[68:69], off offset:384

.LBB0_201:
	s_waitcnt lgkmcnt(0)
	v_lshlrev_b64 v[68:69], 11, v[2:3]
	v_lshl_add_u64 v[68:69], s[94:95], 0, v[68:69]
	v_lshl_add_u64 v[70:71], v[156:157], 1, v[68:69]
	v_add_co_u32_e32 v74, vcc, 0x40000, v70
	s_mov_b64 s[0:1], 0x40000
	s_nop 0
	v_addc_co_u32_e32 v75, vcc, 0, v71, vcc
	v_lshl_add_u64 v[68:69], v[70:71], 0, s[0:1]
	s_nop 1
	v_mov_b64_e32 v[70:71], v[218:219]
	v_mov_b64_e32 v[72:73], v[220:221]
	v_pk_mul_f32 v[76:77], v[66:67], v[0:1] op_sel_hi:[1,0]
	v_pk_mul_f32 v[64:65], v[64:65], v[0:1] op_sel_hi:[1,0]
	v_pk_mul_f32 v[60:61], v[60:61], v[0:1] op_sel_hi:[1,0]
	v_pk_mul_f32 v[62:63], v[62:63], v[0:1] op_sel_hi:[1,0]
	v_pk_mul_f32 v[56:57], v[56:57], v[0:1] op_sel_hi:[1,0]
	v_pk_mul_f32 v[54:55], v[54:55], v[0:1] op_sel_hi:[1,0]
	v_pk_mul_f32 v[52:53], v[52:53], v[0:1] op_sel_hi:[1,0]
	s_and_b64 vcc, exec, s[6:7]
	v_lshlrev_b32_e32 v66, 16, v70
	v_add_f32_e32 v64, v64, v66
	v_and_b32_e32 v66, 0xffff0000, v70
	v_add_f32_e32 v67, v65, v66
	v_lshlrev_b32_e32 v65, 16, v71
	v_add_f32_e32 v65, v76, v65
	v_lshlrev_b32_e32 v76, 16, v72
	v_and_b32_e32 v72, 0xffff0000, v72
	v_add_f32_e32 v61, v61, v72
	v_lshlrev_b32_e32 v72, 16, v73
	v_and_b32_e32 v66, 0xffff0000, v71
	v_add_f32_e32 v62, v62, v72
	v_and_b32_e32 v72, 0xffff0000, v73
	v_add_f32_e32 v66, v77, v66
	v_cvt_pk_bf16_f32 v70, v64, v67
	v_cvt_pk_bf16_f32 v71, v65, v66
	v_add_f32_e32 v60, v60, v76
	v_add_f32_e32 v63, v63, v72
	v_cvt_pk_bf16_f32 v72, v60, v61
	v_cvt_pk_bf16_f32 v73, v62, v63
	global_store_dwordx4 v[74:75], v[70:73], off sc1
	s_nop 1
	v_mov_b64_e32 v[70:71], v[222:223]
	v_mov_b64_e32 v[72:73], v[224:225]
	v_pk_mul_f32 v[74:75], v[58:59], v[0:1] op_sel_hi:[1,0]
	v_lshlrev_b32_e32 v0, 16, v72
	v_lshlrev_b32_e32 v58, 16, v70
	v_add_f32_e32 v0, v52, v0
	v_and_b32_e32 v52, 0xffff0000, v72
	v_add_f32_e32 v56, v56, v58
	v_and_b32_e32 v58, 0xffff0000, v70
	v_add_f32_e32 v52, v53, v52
	v_lshlrev_b32_e32 v53, 16, v73
	v_add_f32_e32 v59, v57, v58
	v_lshlrev_b32_e32 v57, 16, v71
	v_and_b32_e32 v58, 0xffff0000, v71
	v_add_f32_e32 v53, v54, v53
	v_and_b32_e32 v54, 0xffff0000, v73
	v_add_f32_e32 v57, v74, v57
	v_add_f32_e32 v58, v75, v58
	v_add_f32_e32 v54, v55, v54
	v_cvt_pk_bf16_f32 v70, v56, v59
	v_cvt_pk_bf16_f32 v71, v57, v58
	v_cvt_pk_bf16_f32 v72, v0, v52
	v_cvt_pk_bf16_f32 v73, v53, v54
	global_store_dwordx4 v[68:69], v[70:73], off offset:256 sc1
	s_cbranch_vccnz .LBB0_205
	v_mul_f32_e32 v55, v67, v67
	v_mul_f32_e32 v61, v61, v61
	v_fmac_f32_e32 v55, v64, v64
	v_fmac_f32_e32 v61, v60, v60
	v_mul_f32_e32 v59, v59, v59
	v_fmac_f32_e32 v55, v65, v65
	v_fmac_f32_e32 v61, v62, v62
	v_fmac_f32_e32 v59, v56, v56
	v_mul_f32_e32 v52, v52, v52
	v_fmac_f32_e32 v55, v66, v66
	v_fmac_f32_e32 v61, v63, v63
	v_fmac_f32_e32 v59, v57, v57
	v_fmac_f32_e32 v52, v0, v0
	v_add_f32_e32 v55, v55, v61
	v_fmac_f32_e32 v59, v58, v58
	v_fmac_f32_e32 v52, v53, v53
	v_add_f32_e32 v55, v55, v59
	v_fmac_f32_e32 v52, v54, v54
	v_and_b32_e32 v53, 64, v177
	v_add_f32_e32 v0, v52, v55
	v_xor_b32_e32 v52, 16, v177
	v_add_u32_e32 v53, 64, v53
	v_cmp_lt_i32_e32 vcc, v52, v53
	s_nop 1
	v_cndmask_b32_e32 v52, v177, v52, vcc
	v_lshlrev_b32_e32 v52, 2, v52
	ds_bpermute_b32 v52, v52, v0
	s_waitcnt lgkmcnt(0)
	v_add_f32_e32 v0, v0, v52
	v_xor_b32_e32 v52, 32, v177
	v_cmp_lt_i32_e32 vcc, v52, v53
	s_nop 1
	v_cndmask_b32_e32 v52, v177, v52, vcc
	v_lshlrev_b32_e32 v52, 2, v52
	ds_bpermute_b32 v52, v52, v0
	s_and_saveexec_b64 s[2:3], s[8:9]
	s_cbranch_execz .LBB0_204
	s_waitcnt lgkmcnt(0)
	v_add_f32_e32 v0, v0, v52
	v_mul_f32_e32 v0, 0x4b800000, v0
	v_trunc_f32_e32 v0, v0
	v_mul_f32_e32 v52, 0x2f800000, v0
	v_floor_f32_e32 v53, v52
	v_fmac_f32_e32 v0, 0xcf800000, v53
	v_cvt_u32_f32_e32 v52, v0
	v_cvt_u32_f32_e32 v53, v53
	v_readlane_b32 s0, v255, 17
	v_readlane_b32 s1, v255, 18
	s_nop 1
	v_lshl_add_u64 v[54:55], v[2:3], 3, s[0:1]
	global_atomic_add_x2 v[54:55], v[52:53], off offset:1024

.LBB0_207:
	s_waitcnt lgkmcnt(0)
	v_lshlrev_b64 v[52:53], 11, v[2:3]
	v_lshl_add_u64 v[52:53], s[94:95], 0, v[52:53]
	v_lshl_add_u64 v[54:55], v[156:157], 1, v[52:53]
	v_add_co_u32_e32 v58, vcc, 0x48000, v54
	s_mov_b64 s[0:1], 0x48000
	s_nop 0
	v_addc_co_u32_e32 v59, vcc, 0, v55, vcc
	v_lshl_add_u64 v[52:53], v[54:55], 0, s[0:1]
	s_nop 1
	v_mov_b64_e32 v[54:55], v[226:227]
	v_mov_b64_e32 v[56:57], v[228:229]
	v_pk_mul_f32 v[60:61], v[50:51], v[0:1] op_sel_hi:[1,0]
	v_pk_mul_f32 v[48:49], v[48:49], v[0:1] op_sel_hi:[1,0]
	v_pk_mul_f32 v[44:45], v[44:45], v[0:1] op_sel_hi:[1,0]
	v_pk_mul_f32 v[46:47], v[46:47], v[0:1] op_sel_hi:[1,0]
	v_pk_mul_f32 v[40:41], v[40:41], v[0:1] op_sel_hi:[1,0]
	v_pk_mul_f32 v[38:39], v[38:39], v[0:1] op_sel_hi:[1,0]
	v_pk_mul_f32 v[36:37], v[36:37], v[0:1] op_sel_hi:[1,0]
	s_and_b64 vcc, exec, s[6:7]
	v_lshlrev_b32_e32 v50, 16, v54
	v_add_f32_e32 v48, v48, v50
	v_and_b32_e32 v50, 0xffff0000, v54
	v_add_f32_e32 v51, v49, v50
	v_lshlrev_b32_e32 v49, 16, v55
	v_add_f32_e32 v49, v60, v49
	v_lshlrev_b32_e32 v60, 16, v56
	v_and_b32_e32 v56, 0xffff0000, v56
	v_add_f32_e32 v45, v45, v56
	v_lshlrev_b32_e32 v56, 16, v57
	v_and_b32_e32 v50, 0xffff0000, v55
	v_add_f32_e32 v46, v46, v56
	v_and_b32_e32 v56, 0xffff0000, v57
	v_add_f32_e32 v50, v61, v50
	v_cvt_pk_bf16_f32 v54, v48, v51
	v_cvt_pk_bf16_f32 v55, v49, v50
	v_add_f32_e32 v44, v44, v60
	v_add_f32_e32 v47, v47, v56
	v_cvt_pk_bf16_f32 v56, v44, v45
	v_cvt_pk_bf16_f32 v57, v46, v47
	global_store_dwordx4 v[58:59], v[54:57], off sc1
	s_nop 1
	v_mov_b64_e32 v[54:55], v[230:231]
	v_mov_b64_e32 v[56:57], v[232:233]
	v_pk_mul_f32 v[58:59], v[42:43], v[0:1] op_sel_hi:[1,0]
	v_lshlrev_b32_e32 v0, 16, v56
	v_lshlrev_b32_e32 v42, 16, v54
	v_add_f32_e32 v0, v36, v0
	v_and_b32_e32 v36, 0xffff0000, v56
	v_add_f32_e32 v40, v40, v42
	v_and_b32_e32 v42, 0xffff0000, v54
	v_add_f32_e32 v36, v37, v36
	v_lshlrev_b32_e32 v37, 16, v57
	v_add_f32_e32 v43, v41, v42
	v_lshlrev_b32_e32 v41, 16, v55
	v_and_b32_e32 v42, 0xffff0000, v55
	v_add_f32_e32 v37, v38, v37
	v_and_b32_e32 v38, 0xffff0000, v57
	v_add_f32_e32 v41, v58, v41
	v_add_f32_e32 v42, v59, v42
	v_add_f32_e32 v38, v39, v38
	v_cvt_pk_bf16_f32 v54, v40, v43
	v_cvt_pk_bf16_f32 v55, v41, v42
	v_cvt_pk_bf16_f32 v56, v0, v36
	v_cvt_pk_bf16_f32 v57, v37, v38
	global_store_dwordx4 v[52:53], v[54:57], off offset:256 sc1
	s_cbranch_vccnz .LBB0_211
	v_mul_f32_e32 v39, v51, v51
	v_mul_f32_e32 v45, v45, v45
	v_fmac_f32_e32 v39, v48, v48
	v_fmac_f32_e32 v45, v44, v44
	v_mul_f32_e32 v43, v43, v43
	v_fmac_f32_e32 v39, v49, v49
	v_fmac_f32_e32 v45, v46, v46
	v_fmac_f32_e32 v43, v40, v40
	v_mul_f32_e32 v36, v36, v36
	v_fmac_f32_e32 v39, v50, v50
	v_fmac_f32_e32 v45, v47, v47
	v_fmac_f32_e32 v43, v41, v41
	v_fmac_f32_e32 v36, v0, v0
	v_add_f32_e32 v39, v39, v45
	v_fmac_f32_e32 v43, v42, v42
	v_fmac_f32_e32 v36, v37, v37
	v_add_f32_e32 v39, v39, v43
	v_fmac_f32_e32 v36, v38, v38
	v_and_b32_e32 v37, 64, v177
	v_add_f32_e32 v0, v36, v39
	v_xor_b32_e32 v36, 16, v177
	v_add_u32_e32 v37, 64, v37
	v_cmp_lt_i32_e32 vcc, v36, v37
	s_nop 1
	v_cndmask_b32_e32 v36, v177, v36, vcc
	v_lshlrev_b32_e32 v36, 2, v36
	ds_bpermute_b32 v36, v36, v0
	s_waitcnt lgkmcnt(0)
	v_add_f32_e32 v0, v0, v36
	v_xor_b32_e32 v36, 32, v177
	v_cmp_lt_i32_e32 vcc, v36, v37
	s_nop 1
	v_cndmask_b32_e32 v36, v177, v36, vcc
	v_lshlrev_b32_e32 v36, 2, v36
	ds_bpermute_b32 v36, v36, v0
	s_and_saveexec_b64 s[2:3], s[8:9]
	s_cbranch_execz .LBB0_210
	s_waitcnt lgkmcnt(0)
	v_add_f32_e32 v0, v0, v36
	v_mul_f32_e32 v0, 0x4b800000, v0
	v_trunc_f32_e32 v0, v0
	v_mul_f32_e32 v36, 0x2f800000, v0
	v_floor_f32_e32 v37, v36
	v_fmac_f32_e32 v0, 0xcf800000, v37
	v_cvt_u32_f32_e32 v36, v0
	v_cvt_u32_f32_e32 v37, v37
	v_readlane_b32 s0, v255, 17
	v_readlane_b32 s1, v255, 18
	s_nop 1
	v_lshl_add_u64 v[38:39], v[2:3], 3, s[0:1]
	global_atomic_add_x2 v[38:39], v[36:37], off offset:1152

.LBB0_213:
	s_waitcnt lgkmcnt(0)
	v_lshlrev_b64 v[36:37], 11, v[2:3]
	v_lshl_add_u64 v[36:37], s[94:95], 0, v[36:37]
	v_lshl_add_u64 v[38:39], v[156:157], 1, v[36:37]
	v_add_co_u32_e32 v42, vcc, 0x50000, v38
	s_mov_b64 s[0:1], 0x50000
	s_nop 0
	v_addc_co_u32_e32 v43, vcc, 0, v39, vcc
	v_lshl_add_u64 v[36:37], v[38:39], 0, s[0:1]
	s_nop 1
	v_mov_b64_e32 v[38:39], v[234:235]
	v_mov_b64_e32 v[40:41], v[236:237]
	v_pk_mul_f32 v[44:45], v[34:35], v[0:1] op_sel_hi:[1,0]
	v_pk_mul_f32 v[32:33], v[32:33], v[0:1] op_sel_hi:[1,0]
	v_pk_mul_f32 v[28:29], v[28:29], v[0:1] op_sel_hi:[1,0]
	v_pk_mul_f32 v[30:31], v[30:31], v[0:1] op_sel_hi:[1,0]
	v_pk_mul_f32 v[24:25], v[24:25], v[0:1] op_sel_hi:[1,0]
	v_pk_mul_f32 v[22:23], v[22:23], v[0:1] op_sel_hi:[1,0]
	v_pk_mul_f32 v[20:21], v[20:21], v[0:1] op_sel_hi:[1,0]
	s_and_b64 vcc, exec, s[6:7]
	v_lshlrev_b32_e32 v34, 16, v38
	v_add_f32_e32 v32, v32, v34
	v_and_b32_e32 v34, 0xffff0000, v38
	v_add_f32_e32 v35, v33, v34
	v_lshlrev_b32_e32 v33, 16, v39
	v_add_f32_e32 v33, v44, v33
	v_lshlrev_b32_e32 v44, 16, v40
	v_and_b32_e32 v40, 0xffff0000, v40
	v_add_f32_e32 v29, v29, v40
	v_lshlrev_b32_e32 v40, 16, v41
	v_and_b32_e32 v34, 0xffff0000, v39
	v_add_f32_e32 v30, v30, v40
	v_and_b32_e32 v40, 0xffff0000, v41
	v_add_f32_e32 v34, v45, v34
	v_cvt_pk_bf16_f32 v38, v32, v35
	v_cvt_pk_bf16_f32 v39, v33, v34
	v_add_f32_e32 v28, v28, v44
	v_add_f32_e32 v31, v31, v40
	v_cvt_pk_bf16_f32 v40, v28, v29
	v_cvt_pk_bf16_f32 v41, v30, v31
	global_store_dwordx4 v[42:43], v[38:41], off sc1
	s_nop 1
	v_mov_b64_e32 v[38:39], v[238:239]
	v_mov_b64_e32 v[40:41], v[240:241]
	v_pk_mul_f32 v[42:43], v[26:27], v[0:1] op_sel_hi:[1,0]
	v_lshlrev_b32_e32 v0, 16, v40
	v_lshlrev_b32_e32 v26, 16, v38
	v_add_f32_e32 v0, v20, v0
	v_and_b32_e32 v20, 0xffff0000, v40
	v_add_f32_e32 v24, v24, v26
	v_and_b32_e32 v26, 0xffff0000, v38
	v_add_f32_e32 v20, v21, v20
	v_lshlrev_b32_e32 v21, 16, v41
	v_add_f32_e32 v27, v25, v26
	v_lshlrev_b32_e32 v25, 16, v39
	v_and_b32_e32 v26, 0xffff0000, v39
	v_add_f32_e32 v21, v22, v21
	v_and_b32_e32 v22, 0xffff0000, v41
	v_add_f32_e32 v25, v42, v25
	v_add_f32_e32 v26, v43, v26
	v_add_f32_e32 v22, v23, v22
	v_cvt_pk_bf16_f32 v38, v24, v27
	v_cvt_pk_bf16_f32 v39, v25, v26
	v_cvt_pk_bf16_f32 v40, v0, v20
	v_cvt_pk_bf16_f32 v41, v21, v22
	global_store_dwordx4 v[36:37], v[38:41], off offset:256 sc1
	s_cbranch_vccnz .LBB0_217
	v_mul_f32_e32 v23, v35, v35
	v_mul_f32_e32 v29, v29, v29
	v_fmac_f32_e32 v23, v32, v32
	v_fmac_f32_e32 v29, v28, v28
	v_mul_f32_e32 v27, v27, v27
	v_fmac_f32_e32 v23, v33, v33
	v_fmac_f32_e32 v29, v30, v30
	v_fmac_f32_e32 v27, v24, v24
	v_mul_f32_e32 v20, v20, v20
	v_fmac_f32_e32 v23, v34, v34
	v_fmac_f32_e32 v29, v31, v31
	v_fmac_f32_e32 v27, v25, v25
	v_fmac_f32_e32 v20, v0, v0
	v_add_f32_e32 v23, v23, v29
	v_fmac_f32_e32 v27, v26, v26
	v_fmac_f32_e32 v20, v21, v21
	v_add_f32_e32 v23, v23, v27
	v_fmac_f32_e32 v20, v22, v22
	v_and_b32_e32 v21, 64, v177
	v_add_f32_e32 v0, v20, v23
	v_xor_b32_e32 v20, 16, v177
	v_add_u32_e32 v21, 64, v21
	v_cmp_lt_i32_e32 vcc, v20, v21
	s_nop 1
	v_cndmask_b32_e32 v20, v177, v20, vcc
	v_lshlrev_b32_e32 v20, 2, v20
	ds_bpermute_b32 v20, v20, v0
	s_waitcnt lgkmcnt(0)
	v_add_f32_e32 v0, v0, v20
	v_xor_b32_e32 v20, 32, v177
	v_cmp_lt_i32_e32 vcc, v20, v21
	s_nop 1
	v_cndmask_b32_e32 v20, v177, v20, vcc
	v_lshlrev_b32_e32 v20, 2, v20
	ds_bpermute_b32 v20, v20, v0
	s_and_saveexec_b64 s[2:3], s[8:9]
	s_cbranch_execz .LBB0_216
	s_waitcnt lgkmcnt(0)
	v_add_f32_e32 v0, v0, v20
	v_mul_f32_e32 v0, 0x4b800000, v0
	v_trunc_f32_e32 v0, v0
	v_mul_f32_e32 v20, 0x2f800000, v0
	v_floor_f32_e32 v21, v20
	v_fmac_f32_e32 v0, 0xcf800000, v21
	v_cvt_u32_f32_e32 v20, v0
	v_cvt_u32_f32_e32 v21, v21
	v_readlane_b32 s0, v255, 17
	v_readlane_b32 s1, v255, 18
	s_nop 1
	v_lshl_add_u64 v[22:23], v[2:3], 3, s[0:1]
	global_atomic_add_x2 v[22:23], v[20:21], off offset:1280

.LBB0_219:
	s_waitcnt lgkmcnt(0)
	v_lshlrev_b64 v[20:21], 11, v[2:3]
	v_lshl_add_u64 v[20:21], s[94:95], 0, v[20:21]
	v_lshl_add_u64 v[22:23], v[156:157], 1, v[20:21]
	v_add_co_u32_e32 v26, vcc, 0x58000, v22
	s_mov_b64 s[0:1], 0x58000
	s_nop 0
	v_addc_co_u32_e32 v27, vcc, 0, v23, vcc
	v_lshl_add_u64 v[20:21], v[22:23], 0, s[0:1]
	s_nop 1
	v_mov_b64_e32 v[22:23], v[242:243]
	v_mov_b64_e32 v[24:25], v[244:245]
	v_pk_mul_f32 v[28:29], v[18:19], v[0:1] op_sel_hi:[1,0]
	v_pk_mul_f32 v[16:17], v[16:17], v[0:1] op_sel_hi:[1,0]
	v_pk_mul_f32 v[12:13], v[12:13], v[0:1] op_sel_hi:[1,0]
	v_pk_mul_f32 v[14:15], v[14:15], v[0:1] op_sel_hi:[1,0]
	v_pk_mul_f32 v[8:9], v[8:9], v[0:1] op_sel_hi:[1,0]
	v_pk_mul_f32 v[6:7], v[6:7], v[0:1] op_sel_hi:[1,0]
	v_pk_mul_f32 v[4:5], v[4:5], v[0:1] op_sel_hi:[1,0]
	s_and_b64 vcc, exec, s[6:7]
	v_lshlrev_b32_e32 v18, 16, v22
	v_add_f32_e32 v16, v16, v18
	v_and_b32_e32 v18, 0xffff0000, v22
	v_add_f32_e32 v19, v17, v18
	v_lshlrev_b32_e32 v17, 16, v23
	v_add_f32_e32 v17, v28, v17
	v_lshlrev_b32_e32 v28, 16, v24
	v_and_b32_e32 v24, 0xffff0000, v24
	v_add_f32_e32 v13, v13, v24
	v_lshlrev_b32_e32 v24, 16, v25
	v_and_b32_e32 v18, 0xffff0000, v23
	v_add_f32_e32 v14, v14, v24
	v_and_b32_e32 v24, 0xffff0000, v25
	v_add_f32_e32 v18, v29, v18
	v_cvt_pk_bf16_f32 v22, v16, v19
	v_cvt_pk_bf16_f32 v23, v17, v18
	v_add_f32_e32 v12, v12, v28
	v_add_f32_e32 v15, v15, v24
	v_cvt_pk_bf16_f32 v24, v12, v13
	v_cvt_pk_bf16_f32 v25, v14, v15
	global_store_dwordx4 v[26:27], v[22:25], off sc1
	s_nop 1
	v_mov_b64_e32 v[22:23], v[246:247]
	v_mov_b64_e32 v[24:25], v[248:249]
	v_pk_mul_f32 v[26:27], v[10:11], v[0:1] op_sel_hi:[1,0]
	v_lshlrev_b32_e32 v0, 16, v24
	v_lshlrev_b32_e32 v10, 16, v22
	v_add_f32_e32 v0, v4, v0
	v_and_b32_e32 v4, 0xffff0000, v24
	v_add_f32_e32 v8, v8, v10
	v_and_b32_e32 v10, 0xffff0000, v22
	v_add_f32_e32 v4, v5, v4
	v_lshlrev_b32_e32 v5, 16, v25
	v_add_f32_e32 v11, v9, v10
	v_lshlrev_b32_e32 v9, 16, v23
	v_and_b32_e32 v10, 0xffff0000, v23
	v_add_f32_e32 v5, v6, v5
	v_and_b32_e32 v6, 0xffff0000, v25
	v_add_f32_e32 v9, v26, v9
	v_add_f32_e32 v10, v27, v10
	v_add_f32_e32 v6, v7, v6
	v_cvt_pk_bf16_f32 v22, v8, v11
	v_cvt_pk_bf16_f32 v23, v9, v10
	v_cvt_pk_bf16_f32 v24, v0, v4
	v_cvt_pk_bf16_f32 v25, v5, v6
	global_store_dwordx4 v[20:21], v[22:25], off offset:256 sc1
	s_cbranch_vccnz .LBB0_158
	v_mul_f32_e32 v7, v19, v19
	v_mul_f32_e32 v13, v13, v13
	v_fmac_f32_e32 v7, v16, v16
	v_fmac_f32_e32 v13, v12, v12
	v_mul_f32_e32 v11, v11, v11
	v_fmac_f32_e32 v7, v17, v17
	v_fmac_f32_e32 v13, v14, v14
	v_fmac_f32_e32 v11, v8, v8
	v_mul_f32_e32 v4, v4, v4
	v_fmac_f32_e32 v7, v18, v18
	v_fmac_f32_e32 v13, v15, v15
	v_fmac_f32_e32 v11, v9, v9
	v_fmac_f32_e32 v4, v0, v0
	v_add_f32_e32 v7, v7, v13
	v_fmac_f32_e32 v11, v10, v10
	v_fmac_f32_e32 v4, v5, v5
	v_add_f32_e32 v7, v7, v11
	v_fmac_f32_e32 v4, v6, v6
	v_and_b32_e32 v5, 64, v177
	v_add_f32_e32 v0, v4, v7
	v_xor_b32_e32 v4, 16, v177
	v_add_u32_e32 v5, 64, v5
	v_cmp_lt_i32_e32 vcc, v4, v5
	s_nop 1
	v_cndmask_b32_e32 v4, v177, v4, vcc
	v_lshlrev_b32_e32 v4, 2, v4
	ds_bpermute_b32 v4, v4, v0
	s_waitcnt lgkmcnt(0)
	v_add_f32_e32 v0, v0, v4
	v_xor_b32_e32 v4, 32, v177
	v_cmp_lt_i32_e32 vcc, v4, v5
	s_nop 1
	v_cndmask_b32_e32 v4, v177, v4, vcc
	v_lshlrev_b32_e32 v4, 2, v4
	ds_bpermute_b32 v4, v4, v0
	s_and_saveexec_b64 s[2:3], s[8:9]
	s_cbranch_execz .LBB0_157
	s_waitcnt lgkmcnt(0)
	v_add_f32_e32 v0, v0, v4
	v_mul_f32_e32 v0, 0x4b800000, v0
	v_trunc_f32_e32 v0, v0
	v_mul_f32_e32 v4, 0x2f800000, v0
	v_floor_f32_e32 v5, v4
	v_fmac_f32_e32 v0, 0xcf800000, v5
	v_cvt_u32_f32_e32 v4, v0
	v_cvt_u32_f32_e32 v5, v5
	v_readlane_b32 s0, v255, 17
	v_readlane_b32 s1, v255, 18
	s_nop 1
	v_lshl_add_u64 v[2:3], v[2:3], 3, s[0:1]
	global_atomic_add_x2 v[2:3], v[4:5], off offset:1408
	s_branch .LBB0_157

.LBB0_787:
	v_lshl_or_b32 v154, s18, 8, v161
	v_mad_i64_i32 v[164:165], s[20:21], v140, s4, 0
	v_ashrrev_i32_e32 v155, 31, v154
	v_lshl_add_u64 v[164:165], v[164:165], 1, s[72:73]
	v_lshl_add_u64 v[164:165], v[154:155], 1, v[164:165]
	v_pk_mul_f32 v[128:129], v[128:129], v[160:161] op_sel_hi:[1,0]
	v_pk_mul_f32 v[126:127], v[126:127], v[160:161] op_sel_hi:[1,0]
	v_pk_mul_f32 v[166:167], v[124:125], v[160:161] op_sel_hi:[1,0]
	v_pk_mul_f32 v[124:125], v[122:123], v[160:161] op_sel_hi:[1,0]
	v_cvt_pk_bf16_f32 v122, v126, v127
	v_cvt_pk_bf16_f32 v123, v128, v129
	s_and_b64 vcc, exec, s[8:9]
	v_cvt_pk_bf16_f32 v124, v124, v125
	v_cvt_pk_bf16_f32 v125, v166, v167
	global_store_dwordx4 v[164:165], v[122:125], off sc1
	v_pk_mul_f32 v[120:121], v[120:121], v[160:161] op_sel_hi:[1,0]
	v_pk_mul_f32 v[118:119], v[118:119], v[160:161] op_sel_hi:[1,0]
	v_pk_mul_f32 v[122:123], v[116:117], v[160:161] op_sel_hi:[1,0]
	v_pk_mul_f32 v[116:117], v[114:115], v[160:161] op_sel_hi:[1,0]
	v_cvt_pk_bf16_f32 v114, v118, v119
	v_cvt_pk_bf16_f32 v115, v120, v121
	s_nop 0
	v_cvt_pk_bf16_f32 v116, v116, v117
	v_cvt_pk_bf16_f32 v117, v122, v123
	global_store_dwordx4 v[164:165], v[114:117], off offset:256 sc1
	s_cbranch_vccnz .LBB0_789
	s_nop 1
	v_mov_b64_e32 v[114:115], v[192:193]
	v_ffbh_u32_e32 v116, v115
	v_min_u32_e32 v116, 32, v116
	v_lshlrev_b64 v[114:115], v116, v[114:115]
	v_min_u32_e32 v114, 1, v114
	v_or_b32_e32 v114, v115, v114
	v_cvt_f32_u32_e32 v114, v114
	v_sub_u32_e32 v115, 32, v116
	v_ldexp_f32 v114, v114, v115
	v_fmamk_f32 v114, v114, 0x2e800000, v143
	v_mul_f32_e32 v115, 0x4b800000, v114
	v_cmp_gt_f32_e32 vcc, s90, v114
	s_nop 1
	v_cndmask_b32_e32 v114, v114, v115, vcc
	v_rsq_f32_e32 v114, v114
	s_nop 0
	v_mul_f32_e32 v115, 0x45800000, v114
	v_cndmask_b32_e32 v158, v114, v115, vcc
.LBB0_789:
	s_nop 0
	v_or_b32_e32 v114, 16, v140
	v_mad_i64_i32 v[114:115], s[20:21], v114, s4, 0
	v_lshl_add_u64 v[114:115], v[114:115], 1, s[72:73]
	v_lshl_add_u64 v[114:115], v[154:155], 1, v[114:115]
	v_pk_mul_f32 v[112:113], v[112:113], v[158:159] op_sel_hi:[1,0]
	v_pk_mul_f32 v[110:111], v[110:111], v[158:159] op_sel_hi:[1,0]
	v_pk_mul_f32 v[116:117], v[108:109], v[158:159] op_sel_hi:[1,0]
	v_pk_mul_f32 v[108:109], v[106:107], v[158:159] op_sel_hi:[1,0]
	v_cvt_pk_bf16_f32 v106, v110, v111
	v_cvt_pk_bf16_f32 v107, v112, v113
	v_pk_mul_f32 v[104:105], v[104:105], v[158:159] op_sel_hi:[1,0]
	v_cvt_pk_bf16_f32 v108, v108, v109
	v_cvt_pk_bf16_f32 v109, v116, v117
	global_store_dwordx4 v[114:115], v[106:109], off sc1
	v_pk_mul_f32 v[102:103], v[102:103], v[158:159] op_sel_hi:[1,0]
	s_and_b64 vcc, exec, s[8:9]
	v_pk_mul_f32 v[106:107], v[100:101], v[158:159] op_sel_hi:[1,0]
	v_pk_mul_f32 v[100:101], v[98:99], v[158:159] op_sel_hi:[1,0]
	v_cvt_pk_bf16_f32 v98, v102, v103
	v_cvt_pk_bf16_f32 v99, v104, v105
	s_nop 0
	v_cvt_pk_bf16_f32 v100, v100, v101
	v_cvt_pk_bf16_f32 v101, v106, v107
	global_store_dwordx4 v[114:115], v[98:101], off offset:256 sc1
	s_nop 1
	v_mov_b32_e32 v98, 1.0
	v_mov_b32_e32 v100, 1.0
	s_cbranch_vccnz .LBB0_791
	s_nop 1
	v_mov_b64_e32 v[100:101], v[194:195]
	v_ffbh_u32_e32 v99, v101
	v_min_u32_e32 v99, 32, v99
	v_lshlrev_b64 v[100:101], v99, v[100:101]
	v_min_u32_e32 v100, 1, v100
	v_or_b32_e32 v100, v101, v100
	v_cvt_f32_u32_e32 v100, v100
	v_sub_u32_e32 v99, 32, v99
	v_ldexp_f32 v99, v100, v99
	v_fmamk_f32 v99, v99, 0x2e800000, v143
	v_mul_f32_e32 v100, 0x4b800000, v99
	v_cmp_gt_f32_e32 vcc, s90, v99
	s_nop 1
	v_cndmask_b32_e32 v99, v99, v100, vcc
	v_rsq_f32_e32 v99, v99
	s_nop 0
	v_mul_f32_e32 v100, 0x45800000, v99
	v_cndmask_b32_e32 v100, v99, v100, vcc
.LBB0_791:
	v_or_b32_e32 v99, 32, v140
	v_mad_i64_i32 v[102:103], s[20:21], v99, s4, 0
	v_lshl_add_u64 v[102:103], v[102:103], 1, s[72:73]
	v_lshl_add_u64 v[102:103], v[154:155], 1, v[102:103]
	v_pk_mul_f32 v[96:97], v[96:97], v[100:101] op_sel_hi:[1,0]
	v_pk_mul_f32 v[94:95], v[94:95], v[100:101] op_sel_hi:[1,0]
	v_pk_mul_f32 v[104:105], v[92:93], v[100:101] op_sel_hi:[1,0]
	v_pk_mul_f32 v[92:93], v[90:91], v[100:101] op_sel_hi:[1,0]
	v_cvt_pk_bf16_f32 v90, v94, v95
	v_cvt_pk_bf16_f32 v91, v96, v97
	s_and_b64 vcc, exec, s[8:9]
	v_cvt_pk_bf16_f32 v92, v92, v93
	v_cvt_pk_bf16_f32 v93, v104, v105
	global_store_dwordx4 v[102:103], v[90:93], off sc1
	v_pk_mul_f32 v[88:89], v[88:89], v[100:101] op_sel_hi:[1,0]
	v_pk_mul_f32 v[86:87], v[86:87], v[100:101] op_sel_hi:[1,0]
	v_pk_mul_f32 v[90:91], v[84:85], v[100:101] op_sel_hi:[1,0]
	v_pk_mul_f32 v[84:85], v[82:83], v[100:101] op_sel_hi:[1,0]
	v_cvt_pk_bf16_f32 v82, v86, v87
	v_cvt_pk_bf16_f32 v83, v88, v89
	s_nop 0
	v_cvt_pk_bf16_f32 v84, v84, v85
	v_cvt_pk_bf16_f32 v85, v90, v91
	global_store_dwordx4 v[102:103], v[82:85], off offset:256 sc1
	s_cbranch_vccnz .LBB0_793
	s_nop 1
	v_mov_b64_e32 v[82:83], v[196:197]
	v_ffbh_u32_e32 v84, v83
	v_min_u32_e32 v84, 32, v84
	v_lshlrev_b64 v[82:83], v84, v[82:83]
	v_min_u32_e32 v82, 1, v82
	v_or_b32_e32 v82, v83, v82
	v_cvt_f32_u32_e32 v82, v82
	v_sub_u32_e32 v83, 32, v84
	v_ldexp_f32 v82, v82, v83
	v_fmamk_f32 v82, v82, 0x2e800000, v143
	v_mul_f32_e32 v83, 0x4b800000, v82
	v_cmp_gt_f32_e32 vcc, s90, v82
	s_nop 1
	v_cndmask_b32_e32 v82, v82, v83, vcc
	v_rsq_f32_e32 v82, v82
	s_nop 0
	v_mul_f32_e32 v83, 0x45800000, v82
	v_cndmask_b32_e32 v98, v82, v83, vcc
.LBB0_793:
	s_nop 0
	v_or_b32_e32 v82, 48, v140
	v_mad_i64_i32 v[82:83], s[20:21], v82, s4, 0
	v_lshl_add_u64 v[82:83], v[82:83], 1, s[72:73]
	v_lshl_add_u64 v[82:83], v[154:155], 1, v[82:83]
	v_pk_mul_f32 v[80:81], v[80:81], v[98:99] op_sel_hi:[1,0]
	v_pk_mul_f32 v[78:79], v[78:79], v[98:99] op_sel_hi:[1,0]
	v_pk_mul_f32 v[84:85], v[76:77], v[98:99] op_sel_hi:[1,0]
	v_pk_mul_f32 v[76:77], v[74:75], v[98:99] op_sel_hi:[1,0]
	v_cvt_pk_bf16_f32 v74, v78, v79
	v_cvt_pk_bf16_f32 v75, v80, v81
	v_pk_mul_f32 v[72:73], v[72:73], v[98:99] op_sel_hi:[1,0]
	v_cvt_pk_bf16_f32 v76, v76, v77
	v_cvt_pk_bf16_f32 v77, v84, v85
	global_store_dwordx4 v[82:83], v[74:77], off sc1
	v_pk_mul_f32 v[70:71], v[70:71], v[98:99] op_sel_hi:[1,0]
	s_and_b64 vcc, exec, s[8:9]
	v_pk_mul_f32 v[74:75], v[68:69], v[98:99] op_sel_hi:[1,0]
	v_pk_mul_f32 v[68:69], v[66:67], v[98:99] op_sel_hi:[1,0]
	v_cvt_pk_bf16_f32 v66, v70, v71
	v_cvt_pk_bf16_f32 v67, v72, v73
	s_nop 0
	v_cvt_pk_bf16_f32 v68, v68, v69
	v_cvt_pk_bf16_f32 v69, v74, v75
	global_store_dwordx4 v[82:83], v[66:69], off offset:256 sc1
	s_nop 1
	v_mov_b32_e32 v66, 1.0
	v_mov_b32_e32 v68, 1.0
	s_cbranch_vccnz .LBB0_795
	s_nop 1
	v_mov_b64_e32 v[68:69], v[198:199]
	v_ffbh_u32_e32 v67, v69
	v_min_u32_e32 v67, 32, v67
	v_lshlrev_b64 v[68:69], v67, v[68:69]
	v_min_u32_e32 v68, 1, v68
	v_or_b32_e32 v68, v69, v68
	v_cvt_f32_u32_e32 v68, v68
	v_sub_u32_e32 v67, 32, v67
	v_ldexp_f32 v67, v68, v67
	v_fmamk_f32 v67, v67, 0x2e800000, v143
	v_mul_f32_e32 v68, 0x4b800000, v67
	v_cmp_gt_f32_e32 vcc, s90, v67
	s_nop 1
	v_cndmask_b32_e32 v67, v67, v68, vcc
	v_rsq_f32_e32 v67, v67
	s_nop 0
	v_mul_f32_e32 v68, 0x45800000, v67
	v_cndmask_b32_e32 v68, v67, v68, vcc
.LBB0_795:
	v_add_u32_e32 v67, 0x80, v140
	v_mad_i64_i32 v[70:71], s[20:21], v67, s4, 0
	v_lshl_add_u64 v[70:71], v[70:71], 1, s[72:73]
	v_lshl_add_u64 v[70:71], v[154:155], 1, v[70:71]
	v_pk_mul_f32 v[64:65], v[64:65], v[68:69] op_sel_hi:[1,0]
	v_pk_mul_f32 v[62:63], v[62:63], v[68:69] op_sel_hi:[1,0]
	v_pk_mul_f32 v[72:73], v[60:61], v[68:69] op_sel_hi:[1,0]
	v_pk_mul_f32 v[60:61], v[58:59], v[68:69] op_sel_hi:[1,0]
	v_cvt_pk_bf16_f32 v58, v62, v63
	v_cvt_pk_bf16_f32 v59, v64, v65
	s_and_b64 vcc, exec, s[8:9]
	v_cvt_pk_bf16_f32 v60, v60, v61
	v_cvt_pk_bf16_f32 v61, v72, v73
	global_store_dwordx4 v[70:71], v[58:61], off sc1
	v_pk_mul_f32 v[56:57], v[56:57], v[68:69] op_sel_hi:[1,0]
	v_pk_mul_f32 v[54:55], v[54:55], v[68:69] op_sel_hi:[1,0]
	v_pk_mul_f32 v[58:59], v[52:53], v[68:69] op_sel_hi:[1,0]
	v_pk_mul_f32 v[52:53], v[50:51], v[68:69] op_sel_hi:[1,0]
	v_cvt_pk_bf16_f32 v50, v54, v55
	v_cvt_pk_bf16_f32 v51, v56, v57
	s_nop 0
	v_cvt_pk_bf16_f32 v52, v52, v53
	v_cvt_pk_bf16_f32 v53, v58, v59
	global_store_dwordx4 v[70:71], v[50:53], off offset:256 sc1
	s_cbranch_vccnz .LBB0_797
	s_nop 1
	v_mov_b64_e32 v[50:51], v[200:201]
	v_ffbh_u32_e32 v52, v51
	v_min_u32_e32 v52, 32, v52
	v_lshlrev_b64 v[50:51], v52, v[50:51]
	v_min_u32_e32 v50, 1, v50
	v_or_b32_e32 v50, v51, v50
	v_cvt_f32_u32_e32 v50, v50
	v_sub_u32_e32 v51, 32, v52
	v_ldexp_f32 v50, v50, v51
	v_fmamk_f32 v50, v50, 0x2e800000, v143
	v_mul_f32_e32 v51, 0x4b800000, v50
	v_cmp_gt_f32_e32 vcc, s90, v50
	s_nop 1
	v_cndmask_b32_e32 v50, v50, v51, vcc
	v_rsq_f32_e32 v50, v50
	s_nop 0
	v_mul_f32_e32 v51, 0x45800000, v50
	v_cndmask_b32_e32 v66, v50, v51, vcc
.LBB0_797:
	s_nop 0
	v_add_u32_e32 v50, 0x90, v140
	v_mad_i64_i32 v[50:51], s[20:21], v50, s4, 0
	v_lshl_add_u64 v[50:51], v[50:51], 1, s[72:73]
	v_lshl_add_u64 v[50:51], v[154:155], 1, v[50:51]
	v_pk_mul_f32 v[48:49], v[48:49], v[66:67] op_sel_hi:[1,0]
	v_pk_mul_f32 v[46:47], v[46:47], v[66:67] op_sel_hi:[1,0]
	v_pk_mul_f32 v[52:53], v[44:45], v[66:67] op_sel_hi:[1,0]
	v_pk_mul_f32 v[44:45], v[42:43], v[66:67] op_sel_hi:[1,0]
	v_cvt_pk_bf16_f32 v42, v46, v47
	v_cvt_pk_bf16_f32 v43, v48, v49
	v_pk_mul_f32 v[40:41], v[40:41], v[66:67] op_sel_hi:[1,0]
	v_cvt_pk_bf16_f32 v44, v44, v45
	v_cvt_pk_bf16_f32 v45, v52, v53
	global_store_dwordx4 v[50:51], v[42:45], off sc1
	v_pk_mul_f32 v[38:39], v[38:39], v[66:67] op_sel_hi:[1,0]
	s_and_b64 vcc, exec, s[8:9]
	v_pk_mul_f32 v[42:43], v[36:37], v[66:67] op_sel_hi:[1,0]
	v_pk_mul_f32 v[36:37], v[34:35], v[66:67] op_sel_hi:[1,0]
	v_cvt_pk_bf16_f32 v34, v38, v39
	v_cvt_pk_bf16_f32 v35, v40, v41
	s_nop 0
	v_cvt_pk_bf16_f32 v36, v36, v37
	v_cvt_pk_bf16_f32 v37, v42, v43
	global_store_dwordx4 v[50:51], v[34:37], off offset:256 sc1
	s_nop 1
	v_mov_b32_e32 v34, 1.0
	v_mov_b32_e32 v36, 1.0
	s_cbranch_vccnz .LBB0_799
	s_nop 1
	v_mov_b64_e32 v[36:37], v[202:203]
	v_ffbh_u32_e32 v35, v37
	v_min_u32_e32 v35, 32, v35
	v_lshlrev_b64 v[36:37], v35, v[36:37]
	v_min_u32_e32 v36, 1, v36
	v_or_b32_e32 v36, v37, v36
	v_cvt_f32_u32_e32 v36, v36
	v_sub_u32_e32 v35, 32, v35
	v_ldexp_f32 v35, v36, v35
	v_fmamk_f32 v35, v35, 0x2e800000, v143
	v_mul_f32_e32 v36, 0x4b800000, v35
	v_cmp_gt_f32_e32 vcc, s90, v35
	s_nop 1
	v_cndmask_b32_e32 v35, v35, v36, vcc
	v_rsq_f32_e32 v35, v35
	s_nop 0
	v_mul_f32_e32 v36, 0x45800000, v35
	v_cndmask_b32_e32 v36, v35, v36, vcc
.LBB0_799:
	v_add_u32_e32 v35, 0xa0, v140
	v_mad_i64_i32 v[38:39], s[20:21], v35, s4, 0
	v_lshl_add_u64 v[38:39], v[38:39], 1, s[72:73]
	v_lshl_add_u64 v[38:39], v[154:155], 1, v[38:39]
	v_pk_mul_f32 v[32:33], v[32:33], v[36:37] op_sel_hi:[1,0]
	v_pk_mul_f32 v[30:31], v[30:31], v[36:37] op_sel_hi:[1,0]
	v_pk_mul_f32 v[40:41], v[28:29], v[36:37] op_sel_hi:[1,0]
	v_pk_mul_f32 v[28:29], v[26:27], v[36:37] op_sel_hi:[1,0]
	v_cvt_pk_bf16_f32 v26, v30, v31
	v_cvt_pk_bf16_f32 v27, v32, v33
	s_and_b64 vcc, exec, s[8:9]
	v_cvt_pk_bf16_f32 v28, v28, v29
	v_cvt_pk_bf16_f32 v29, v40, v41
	global_store_dwordx4 v[38:39], v[26:29], off sc1
	v_pk_mul_f32 v[24:25], v[24:25], v[36:37] op_sel_hi:[1,0]
	v_pk_mul_f32 v[22:23], v[22:23], v[36:37] op_sel_hi:[1,0]
	v_pk_mul_f32 v[26:27], v[20:21], v[36:37] op_sel_hi:[1,0]
	v_pk_mul_f32 v[20:21], v[18:19], v[36:37] op_sel_hi:[1,0]
	v_cvt_pk_bf16_f32 v18, v22, v23
	v_cvt_pk_bf16_f32 v19, v24, v25
	s_nop 0
	v_cvt_pk_bf16_f32 v20, v20, v21
	v_cvt_pk_bf16_f32 v21, v26, v27
	global_store_dwordx4 v[38:39], v[18:21], off offset:256 sc1
	s_cbranch_vccnz .LBB0_776
	s_nop 1
	v_mov_b64_e32 v[18:19], v[204:205]
	v_ffbh_u32_e32 v20, v19
	v_min_u32_e32 v20, 32, v20
	v_lshlrev_b64 v[18:19], v20, v[18:19]
	v_min_u32_e32 v18, 1, v18
	v_or_b32_e32 v18, v19, v18
	v_cvt_f32_u32_e32 v18, v18
	v_sub_u32_e32 v19, 32, v20
	v_ldexp_f32 v18, v18, v19
	v_fmamk_f32 v18, v18, 0x2e800000, v143
	v_mul_f32_e32 v19, 0x4b800000, v18
	v_cmp_gt_f32_e32 vcc, s90, v18
	s_nop 1
	v_cndmask_b32_e32 v18, v18, v19, vcc
	v_rsq_f32_e32 v18, v18
	s_nop 0
	v_mul_f32_e32 v19, 0x45800000, v18
	v_cndmask_b32_e32 v34, v18, v19, vcc
	s_branch .LBB0_776

.LBB0_811:
	s_add_u32 s23, s16, s22
	s_addc_u32 s31, s17, 0
	s_add_u32 s26, s23, 0x100
	s_addc_u32 s27, s31, 0
	s_and_b64 s[24:25], s[20:21], exec
	s_cselect_b32 s27, s3, s27
	s_cselect_b32 s26, s65, s26
	s_add_u32 s22, s14, s22
	s_addc_u32 s24, s15, 0
	s_add_u32 s22, s22, 0x100
	s_addc_u32 s24, s24, 0
	s_and_b64 s[20:21], s[20:21], exec
	s_cselect_b32 s29, s1, s24
	s_cselect_b32 s28, s70, s22
	s_add_u32 s30, s23, 0x10080
	v_add_u32_e32 v136, s13, v139
	s_addc_u32 s31, s31, 0
	s_add_i32 m0, s40, 0xc000
	s_add_i32 s71, s40, 0xe000
	ds_read_b128 v[154:157], v136
	ds_read_b128 v[158:161], v136 offset:1024
	ds_read_b128 v[162:165], v136 offset:2048
	ds_read_b128 v[166:169], v136 offset:3072
	s_add_u32 s24, s28, 0x10000
	s_addc_u32 s25, s29, 0
	s_add_u32 s22, s26, 0x10000
	s_addc_u32 s23, s27, 0
	s_add_u32 s20, s28, 0x10080
	s_addc_u32 s21, s29, 0
	v_lshl_add_u64 v[136:137], s[30:31], 0, v[134:135]
	ds_read_b128 v[188:191], v141
	ds_read_b128 v[192:195], v141 offset:1024
	ds_read_b128 v[196:199], v141 offset:2048
	ds_read_b128 v[200:203], v141 offset:3072
	ds_read_b128 v[204:207], v141 offset:4096
	ds_read_b128 v[208:211], v141 offset:5120
	ds_read_b128 v[212:215], v141 offset:6144
	ds_read_b128 v[218:221], v141 offset:7168
	global_load_lds_dwordx4 v[136:137], off
	v_lshl_add_u64 v[136:137], s[30:31], 0, v[132:133]
	s_mov_b32 m0, s71
	s_nop 0
	global_load_lds_dwordx4 v[136:137], off
	s_waitcnt lgkmcnt(8)
	s_barrier
	s_waitcnt lgkmcnt(0)
	s_setprio 1
	s_waitcnt lgkmcnt(0)
	v_mfma_f32_16x16x32_bf16 v[126:129], v[154:157], v[188:191], v[126:129]
	v_mfma_f32_16x16x32_bf16 v[122:125], v[162:165], v[188:191], v[122:125]
	v_mfma_f32_16x16x32_bf16 v[118:121], v[154:157], v[196:199], v[118:121]
	v_mfma_f32_16x16x32_bf16 v[110:113], v[162:165], v[196:199], v[110:113]
	v_mfma_f32_16x16x32_bf16 v[102:105], v[154:157], v[204:207], v[102:105]
	v_mfma_f32_16x16x32_bf16 v[94:97], v[162:165], v[204:207], v[94:97]
	v_mfma_f32_16x16x32_bf16 v[86:89], v[154:157], v[212:215], v[86:89]
	v_mfma_f32_16x16x32_bf16 v[78:81], v[162:165], v[212:215], v[78:81]
	v_mfma_f32_16x16x32_bf16 v[126:129], v[158:161], v[192:195], v[126:129]
	v_mfma_f32_16x16x32_bf16 v[122:125], v[166:169], v[192:195], v[122:125]
	v_mfma_f32_16x16x32_bf16 v[118:121], v[158:161], v[200:203], v[118:121]
	v_mfma_f32_16x16x32_bf16 v[110:113], v[166:169], v[200:203], v[110:113]
	v_mfma_f32_16x16x32_bf16 v[102:105], v[158:161], v[208:211], v[102:105]
	v_mfma_f32_16x16x32_bf16 v[94:97], v[166:169], v[208:211], v[94:97]
	v_mfma_f32_16x16x32_bf16 v[86:89], v[158:161], v[218:221], v[86:89]
	v_mfma_f32_16x16x32_bf16 v[78:81], v[166:169], v[218:221], v[78:81]
	s_setprio 0
	s_barrier
	v_add_u32_e32 v136, s42, v139
	s_mov_b32 m0, s38
	ds_read_b128 v[222:225], v136
	ds_read_b128 v[226:229], v136 offset:1024
	ds_read_b128 v[230:233], v136 offset:2048
	ds_read_b128 v[234:237], v136 offset:3072
	v_lshl_add_u64 v[136:137], s[28:29], 0, v[0:1]
	global_load_lds_dwordx4 v[136:137], off
	v_lshl_add_u64 v[170:171], s[28:29], 0, v[130:131]
	s_mov_b32 m0, s39
	s_nop 0
	global_load_lds_dwordx4 v[170:171], off
	s_barrier
	s_waitcnt lgkmcnt(0)
	s_setprio 1
	s_waitcnt lgkmcnt(0)
	v_mfma_f32_16x16x32_bf16 v[114:117], v[222:225], v[188:191], v[114:117]
	v_mfma_f32_16x16x32_bf16 v[106:109], v[230:233], v[188:191], v[106:109]
	v_mfma_f32_16x16x32_bf16 v[98:101], v[222:225], v[196:199], v[98:101]
	v_mfma_f32_16x16x32_bf16 v[90:93], v[230:233], v[196:199], v[90:93]
	v_mfma_f32_16x16x32_bf16 v[82:85], v[222:225], v[204:207], v[82:85]
	v_mfma_f32_16x16x32_bf16 v[74:77], v[230:233], v[204:207], v[74:77]
	v_mfma_f32_16x16x32_bf16 v[70:73], v[222:225], v[212:215], v[70:73]
	v_mfma_f32_16x16x32_bf16 v[66:69], v[230:233], v[212:215], v[66:69]
	v_mfma_f32_16x16x32_bf16 v[114:117], v[226:229], v[192:195], v[114:117]
	v_mfma_f32_16x16x32_bf16 v[106:109], v[234:237], v[192:195], v[106:109]
	v_mfma_f32_16x16x32_bf16 v[98:101], v[226:229], v[200:203], v[98:101]
	v_mfma_f32_16x16x32_bf16 v[90:93], v[234:237], v[200:203], v[90:93]
	v_mfma_f32_16x16x32_bf16 v[82:85], v[226:229], v[208:211], v[82:85]
	v_mfma_f32_16x16x32_bf16 v[74:77], v[234:237], v[208:211], v[74:77]
	v_mfma_f32_16x16x32_bf16 v[70:73], v[226:229], v[218:221], v[70:73]
	v_mfma_f32_16x16x32_bf16 v[66:69], v[234:237], v[218:221], v[66:69]
	s_setprio 0
	s_mov_b32 m0, s40
	v_lshl_add_u64 v[238:239], s[26:27], 0, v[134:135]
	s_barrier
	ds_read_b128 v[188:191], v141 offset:16384
	ds_read_b128 v[192:195], v141 offset:17408
	ds_read_b128 v[196:199], v141 offset:18432
	ds_read_b128 v[200:203], v141 offset:19456
	ds_read_b128 v[204:207], v141 offset:20480
	ds_read_b128 v[208:211], v141 offset:21504
	ds_read_b128 v[212:215], v141 offset:22528
	ds_read_b128 v[218:221], v141 offset:23552
	global_load_lds_dwordx4 v[238:239], off
	v_lshl_add_u64 v[240:241], s[26:27], 0, v[132:133]
	s_mov_b32 m0, s41
	s_nop 0
	global_load_lds_dwordx4 v[240:241], off
	s_barrier
	s_waitcnt lgkmcnt(0)
	s_setprio 1
	s_waitcnt lgkmcnt(0)
	v_mfma_f32_16x16x32_bf16 v[62:65], v[154:157], v[188:191], v[62:65]
	v_mfma_f32_16x16x32_bf16 v[58:61], v[162:165], v[188:191], v[58:61]
	v_mfma_f32_16x16x32_bf16 v[54:57], v[154:157], v[196:199], v[54:57]
	v_mfma_f32_16x16x32_bf16 v[46:49], v[162:165], v[196:199], v[46:49]
	v_mfma_f32_16x16x32_bf16 v[38:41], v[154:157], v[204:207], v[38:41]
	v_mfma_f32_16x16x32_bf16 v[30:33], v[162:165], v[204:207], v[30:33]
	v_mfma_f32_16x16x32_bf16 v[22:25], v[154:157], v[212:215], v[22:25]
	v_mfma_f32_16x16x32_bf16 v[14:17], v[162:165], v[212:215], v[14:17]
	v_mfma_f32_16x16x32_bf16 v[62:65], v[158:161], v[192:195], v[62:65]
	v_mfma_f32_16x16x32_bf16 v[58:61], v[166:169], v[192:195], v[58:61]
	v_mfma_f32_16x16x32_bf16 v[54:57], v[158:161], v[200:203], v[54:57]
	v_mfma_f32_16x16x32_bf16 v[46:49], v[166:169], v[200:203], v[46:49]
	v_mfma_f32_16x16x32_bf16 v[38:41], v[158:161], v[208:211], v[38:41]
	v_mfma_f32_16x16x32_bf16 v[30:33], v[166:169], v[208:211], v[30:33]
	v_mfma_f32_16x16x32_bf16 v[22:25], v[158:161], v[218:221], v[22:25]
	v_mfma_f32_16x16x32_bf16 v[14:17], v[166:169], v[218:221], v[14:17]
	s_setprio 0
	s_barrier
	s_mov_b32 m0, s43
	v_lshl_add_u64 v[154:155], s[24:25], 0, v[0:1]
	global_load_lds_dwordx4 v[154:155], off
	v_lshl_add_u64 v[154:155], s[24:25], 0, v[130:131]
	s_mov_b32 m0, s44
	s_nop 0
	global_load_lds_dwordx4 v[154:155], off
	s_waitcnt vmcnt(6)
	s_barrier
	s_setprio 1
	v_mfma_f32_16x16x32_bf16 v[50:53], v[222:225], v[188:191], v[50:53]
	v_mfma_f32_16x16x32_bf16 v[42:45], v[230:233], v[188:191], v[42:45]
	v_mfma_f32_16x16x32_bf16 v[34:37], v[222:225], v[196:199], v[34:37]
	v_mfma_f32_16x16x32_bf16 v[26:29], v[230:233], v[196:199], v[26:29]
	v_mfma_f32_16x16x32_bf16 v[18:21], v[222:225], v[204:207], v[18:21]
	v_mfma_f32_16x16x32_bf16 v[10:13], v[230:233], v[204:207], v[10:13]
	v_mfma_f32_16x16x32_bf16 v[6:9], v[222:225], v[212:215], v[6:9]
	v_mfma_f32_16x16x32_bf16 v[2:5], v[230:233], v[212:215], v[2:5]
	v_mfma_f32_16x16x32_bf16 v[50:53], v[226:229], v[192:195], v[50:53]
	v_mfma_f32_16x16x32_bf16 v[42:45], v[234:237], v[192:195], v[42:45]
	v_mfma_f32_16x16x32_bf16 v[34:37], v[226:229], v[200:203], v[34:37]
	v_mfma_f32_16x16x32_bf16 v[26:29], v[234:237], v[200:203], v[26:29]
	v_mfma_f32_16x16x32_bf16 v[18:21], v[226:229], v[208:211], v[18:21]
	v_mfma_f32_16x16x32_bf16 v[10:13], v[234:237], v[208:211], v[10:13]
	v_mfma_f32_16x16x32_bf16 v[6:9], v[226:229], v[218:221], v[6:9]
	v_mfma_f32_16x16x32_bf16 v[2:5], v[234:237], v[218:221], v[2:5]
	s_setprio 0
	v_add_u32_e32 v144, s52, v139
	s_barrier
	ds_read_b128 v[154:157], v144
	ds_read_b128 v[158:161], v144 offset:1024
	ds_read_b128 v[162:165], v144 offset:2048
	ds_read_b128 v[166:169], v144 offset:3072
	s_mov_b32 m0, s45
	v_lshl_add_u64 v[222:223], s[22:23], 0, v[134:135]
	ds_read_b128 v[188:191], v141 offset:32768
	ds_read_b128 v[192:195], v141 offset:33792
	ds_read_b128 v[196:199], v141 offset:34816
	ds_read_b128 v[200:203], v141 offset:35840
	ds_read_b128 v[204:207], v141 offset:36864
	ds_read_b128 v[208:211], v141 offset:37888
	ds_read_b128 v[212:215], v141 offset:38912
	ds_read_b128 v[218:221], v141 offset:39936
	global_load_lds_dwordx4 v[222:223], off
	v_lshl_add_u64 v[222:223], s[22:23], 0, v[132:133]
	s_mov_b32 m0, s48
	s_nop 0
	global_load_lds_dwordx4 v[222:223], off
	s_waitcnt lgkmcnt(8)
	s_barrier
	s_waitcnt lgkmcnt(0)
	s_setprio 1
	s_waitcnt lgkmcnt(0)
	v_mfma_f32_16x16x32_bf16 v[126:129], v[154:157], v[188:191], v[126:129]
	v_mfma_f32_16x16x32_bf16 v[122:125], v[162:165], v[188:191], v[122:125]
	v_mfma_f32_16x16x32_bf16 v[118:121], v[154:157], v[196:199], v[118:121]
	v_mfma_f32_16x16x32_bf16 v[110:113], v[162:165], v[196:199], v[110:113]
	v_mfma_f32_16x16x32_bf16 v[102:105], v[154:157], v[204:207], v[102:105]
	v_mfma_f32_16x16x32_bf16 v[94:97], v[162:165], v[204:207], v[94:97]
	v_mfma_f32_16x16x32_bf16 v[86:89], v[154:157], v[212:215], v[86:89]
	v_mfma_f32_16x16x32_bf16 v[78:81], v[162:165], v[212:215], v[78:81]
	v_mfma_f32_16x16x32_bf16 v[126:129], v[158:161], v[192:195], v[126:129]
	v_mfma_f32_16x16x32_bf16 v[122:125], v[166:169], v[192:195], v[122:125]
	v_mfma_f32_16x16x32_bf16 v[118:121], v[158:161], v[200:203], v[118:121]
	v_mfma_f32_16x16x32_bf16 v[110:113], v[166:169], v[200:203], v[110:113]
	v_mfma_f32_16x16x32_bf16 v[102:105], v[158:161], v[208:211], v[102:105]
	v_mfma_f32_16x16x32_bf16 v[94:97], v[166:169], v[208:211], v[94:97]
	v_mfma_f32_16x16x32_bf16 v[86:89], v[158:161], v[218:221], v[86:89]
	v_mfma_f32_16x16x32_bf16 v[78:81], v[166:169], v[218:221], v[78:81]
	s_setprio 0
	s_barrier
	s_mov_b32 m0, s53
	v_add_u32_e32 v144, s57, v139
	v_lshl_add_u64 v[136:137], v[136:137], 0, s[66:67]
	ds_read_b128 v[222:225], v144
	ds_read_b128 v[226:229], v144 offset:1024
	ds_read_b128 v[230:233], v144 offset:2048
	ds_read_b128 v[234:237], v144 offset:3072
	global_load_lds_dwordx4 v[136:137], off
	v_lshl_add_u64 v[136:137], v[170:171], 0, s[66:67]
	s_mov_b32 m0, s54
	s_nop 0
	global_load_lds_dwordx4 v[136:137], off
	s_barrier
	s_waitcnt lgkmcnt(0)
	s_setprio 1
	s_waitcnt lgkmcnt(0)
	v_mfma_f32_16x16x32_bf16 v[114:117], v[222:225], v[188:191], v[114:117]
	v_mfma_f32_16x16x32_bf16 v[106:109], v[230:233], v[188:191], v[106:109]
	v_mfma_f32_16x16x32_bf16 v[98:101], v[222:225], v[196:199], v[98:101]
	v_mfma_f32_16x16x32_bf16 v[90:93], v[230:233], v[196:199], v[90:93]
	v_mfma_f32_16x16x32_bf16 v[82:85], v[222:225], v[204:207], v[82:85]
	v_mfma_f32_16x16x32_bf16 v[74:77], v[230:233], v[204:207], v[74:77]
	v_mfma_f32_16x16x32_bf16 v[70:73], v[222:225], v[212:215], v[70:73]
	v_mfma_f32_16x16x32_bf16 v[66:69], v[230:233], v[212:215], v[66:69]
	v_mfma_f32_16x16x32_bf16 v[114:117], v[226:229], v[192:195], v[114:117]
	v_mfma_f32_16x16x32_bf16 v[106:109], v[234:237], v[192:195], v[106:109]
	v_mfma_f32_16x16x32_bf16 v[98:101], v[226:229], v[200:203], v[98:101]
	v_mfma_f32_16x16x32_bf16 v[90:93], v[234:237], v[200:203], v[90:93]
	v_mfma_f32_16x16x32_bf16 v[82:85], v[226:229], v[208:211], v[82:85]
	v_mfma_f32_16x16x32_bf16 v[74:77], v[234:237], v[208:211], v[74:77]
	v_mfma_f32_16x16x32_bf16 v[70:73], v[226:229], v[218:221], v[70:73]
	v_mfma_f32_16x16x32_bf16 v[66:69], v[234:237], v[218:221], v[66:69]
	s_setprio 0
	s_mov_b32 m0, s55
	v_lshl_add_u64 v[136:137], v[238:239], 0, s[66:67]
	s_barrier
	ds_read_b128 v[188:191], v141 offset:49152
	ds_read_b128 v[192:195], v141 offset:50176
	ds_read_b128 v[196:199], v141 offset:51200
	ds_read_b128 v[200:203], v141 offset:52224
	ds_read_b128 v[204:207], v141 offset:53248
	ds_read_b128 v[208:211], v141 offset:54272
	ds_read_b128 v[212:215], v141 offset:55296
	ds_read_b128 v[218:221], v141 offset:56320
	global_load_lds_dwordx4 v[136:137], off
	v_lshl_add_u64 v[136:137], v[240:241], 0, s[66:67]
	s_mov_b32 m0, s56
	s_nop 0
	global_load_lds_dwordx4 v[136:137], off
	s_barrier
	s_waitcnt lgkmcnt(0)
	s_setprio 1
	s_waitcnt lgkmcnt(0)
	v_mfma_f32_16x16x32_bf16 v[62:65], v[154:157], v[188:191], v[62:65]
	v_mfma_f32_16x16x32_bf16 v[58:61], v[162:165], v[188:191], v[58:61]
	v_mfma_f32_16x16x32_bf16 v[54:57], v[154:157], v[196:199], v[54:57]
	v_mfma_f32_16x16x32_bf16 v[46:49], v[162:165], v[196:199], v[46:49]
	v_mfma_f32_16x16x32_bf16 v[38:41], v[154:157], v[204:207], v[38:41]
	v_mfma_f32_16x16x32_bf16 v[30:33], v[162:165], v[204:207], v[30:33]
	v_mfma_f32_16x16x32_bf16 v[22:25], v[154:157], v[212:215], v[22:25]
	v_mfma_f32_16x16x32_bf16 v[14:17], v[162:165], v[212:215], v[14:17]
	v_mfma_f32_16x16x32_bf16 v[62:65], v[158:161], v[192:195], v[62:65]
	v_mfma_f32_16x16x32_bf16 v[58:61], v[166:169], v[192:195], v[58:61]
	v_mfma_f32_16x16x32_bf16 v[54:57], v[158:161], v[200:203], v[54:57]
	v_mfma_f32_16x16x32_bf16 v[46:49], v[166:169], v[200:203], v[46:49]
	v_mfma_f32_16x16x32_bf16 v[38:41], v[158:161], v[208:211], v[38:41]
	v_mfma_f32_16x16x32_bf16 v[30:33], v[166:169], v[208:211], v[30:33]
	v_mfma_f32_16x16x32_bf16 v[22:25], v[158:161], v[218:221], v[22:25]
	v_mfma_f32_16x16x32_bf16 v[14:17], v[166:169], v[218:221], v[14:17]
	s_setprio 0
	s_barrier
	s_mov_b32 m0, s58
	v_lshl_add_u64 v[136:137], s[20:21], 0, v[0:1]
	global_load_lds_dwordx4 v[136:137], off
	v_lshl_add_u64 v[136:137], s[20:21], 0, v[130:131]
	s_mov_b32 m0, s62
	s_nop 0
	global_load_lds_dwordx4 v[136:137], off
	s_waitcnt vmcnt(6)
	s_barrier
	s_setprio 1
	v_mfma_f32_16x16x32_bf16 v[50:53], v[222:225], v[188:191], v[50:53]
	v_mfma_f32_16x16x32_bf16 v[42:45], v[230:233], v[188:191], v[42:45]
	v_mfma_f32_16x16x32_bf16 v[34:37], v[222:225], v[196:199], v[34:37]
	v_mfma_f32_16x16x32_bf16 v[26:29], v[230:233], v[196:199], v[26:29]
	v_mfma_f32_16x16x32_bf16 v[18:21], v[222:225], v[204:207], v[18:21]
	v_mfma_f32_16x16x32_bf16 v[10:13], v[230:233], v[204:207], v[10:13]
	v_mfma_f32_16x16x32_bf16 v[6:9], v[222:225], v[212:215], v[6:9]
	v_mfma_f32_16x16x32_bf16 v[2:5], v[230:233], v[212:215], v[2:5]
	v_mfma_f32_16x16x32_bf16 v[50:53], v[226:229], v[192:195], v[50:53]
	v_mfma_f32_16x16x32_bf16 v[42:45], v[234:237], v[192:195], v[42:45]
	v_mfma_f32_16x16x32_bf16 v[34:37], v[226:229], v[200:203], v[34:37]
	v_mfma_f32_16x16x32_bf16 v[26:29], v[234:237], v[200:203], v[26:29]
	v_mfma_f32_16x16x32_bf16 v[18:21], v[226:229], v[208:211], v[18:21]
	v_mfma_f32_16x16x32_bf16 v[10:13], v[234:237], v[208:211], v[10:13]
	v_mfma_f32_16x16x32_bf16 v[6:9], v[226:229], v[218:221], v[6:9]
	v_mfma_f32_16x16x32_bf16 v[2:5], v[234:237], v[218:221], v[2:5]
	s_setprio 0
	s_movk_i32 s22, 0x100
	s_andn2_b64 vcc, exec, s[18:19]
	s_mov_b64 s[20:21], -1
	s_mov_b64 s[18:19], 0
	s_barrier
	s_cbranch_vccz .LBB0_811
	v_lshl_add_u32 v154, s12, 8, v138
	v_lshl_or_b32 v136, s64, 8, v140
	v_ashrrev_i32_e32 v155, 31, v154
	v_ashrrev_i32_e32 v137, 31, v136
	v_lshlrev_b64 v[156:157], 11, v[154:155]
	v_lshl_add_u64 v[156:157], s[72:73], 0, v[156:157]
	v_lshlrev_b64 v[158:159], 1, v[136:137]
	v_lshl_add_u64 v[136:137], v[156:157], 0, v[158:159]
	v_cvt_pk_bf16_f32 v126, v126, v127
	v_cvt_pk_bf16_f32 v127, v128, v129
	v_cvt_pk_bf16_f32 v128, v122, v123
	v_cvt_pk_bf16_f32 v129, v124, v125
	global_store_dwordx4 v[136:137], v[126:129], off sc1
	v_cvt_pk_bf16_f32 v114, v114, v115
	v_cvt_pk_bf16_f32 v115, v116, v117
	v_cvt_pk_bf16_f32 v116, v106, v107
	v_or_b32_e32 v106, 16, v154
	v_ashrrev_i32_e32 v107, 31, v106
	v_lshlrev_b64 v[106:107], 11, v[106:107]
	v_lshl_add_u64 v[106:107], s[72:73], 0, v[106:107]
	v_cvt_pk_bf16_f32 v117, v108, v109
	global_store_dwordx4 v[136:137], v[114:117], off offset:256 sc1
	s_mov_b32 s1, 0x40000
	s_mov_b64 s[14:15], 0x40000
	v_lshl_add_u64 v[114:115], v[106:107], 0, v[158:159]
	v_cvt_pk_bf16_f32 v106, v118, v119
	v_cvt_pk_bf16_f32 v107, v120, v121
	v_cvt_pk_bf16_f32 v108, v110, v111
	v_cvt_pk_bf16_f32 v109, v112, v113
	global_store_dwordx4 v[114:115], v[106:109], off sc1
	v_cvt_pk_bf16_f32 v98, v98, v99
	v_cvt_pk_bf16_f32 v99, v100, v101
	v_cvt_pk_bf16_f32 v100, v90, v91
	v_or_b32_e32 v90, 32, v154
	v_ashrrev_i32_e32 v91, 31, v90
	v_lshlrev_b64 v[90:91], 11, v[90:91]
	v_lshl_add_u64 v[90:91], s[72:73], 0, v[90:91]
	v_cvt_pk_bf16_f32 v101, v92, v93
	global_store_dwordx4 v[114:115], v[98:101], off offset:256 sc1
	s_mov_b32 s64, s0
	s_mov_b32 s12, s2
	v_lshl_add_u64 v[98:99], v[90:91], 0, v[158:159]
	v_cvt_pk_bf16_f32 v90, v102, v103
	v_cvt_pk_bf16_f32 v91, v104, v105
	v_cvt_pk_bf16_f32 v92, v94, v95
	v_cvt_pk_bf16_f32 v93, v96, v97
	global_store_dwordx4 v[98:99], v[90:93], off sc1
	v_cvt_pk_bf16_f32 v82, v82, v83
	v_cvt_pk_bf16_f32 v83, v84, v85
	v_cvt_pk_bf16_f32 v84, v74, v75
	v_or_b32_e32 v74, 48, v154
	v_ashrrev_i32_e32 v75, 31, v74
	v_lshlrev_b64 v[74:75], 11, v[74:75]
	v_lshl_add_u64 v[74:75], s[72:73], 0, v[74:75]
	v_cvt_pk_bf16_f32 v85, v76, v77
	global_store_dwordx4 v[98:99], v[82:85], off offset:256 sc1
	s_mov_b64 s[16:17], s[8:9]
	s_nop 0
	v_lshl_add_u64 v[82:83], v[74:75], 0, v[158:159]
	v_cvt_pk_bf16_f32 v74, v86, v87
	v_cvt_pk_bf16_f32 v75, v88, v89
	v_cvt_pk_bf16_f32 v76, v78, v79
	v_cvt_pk_bf16_f32 v77, v80, v81
	global_store_dwordx4 v[82:83], v[74:77], off sc1
	v_cvt_pk_bf16_f32 v70, v70, v71
	v_cvt_pk_bf16_f32 v71, v72, v73
	v_cvt_pk_bf16_f32 v72, v66, v67
	v_cvt_pk_bf16_f32 v73, v68, v69
	global_store_dwordx4 v[82:83], v[70:73], off offset:256 sc1
	v_cvt_pk_bf16_f32 v62, v62, v63
	v_cvt_pk_bf16_f32 v63, v64, v65
	v_cvt_pk_bf16_f32 v64, v58, v59
	v_add_co_u32_e32 v58, vcc, s1, v136
	v_lshl_add_u64 v[66:67], v[136:137], 0, s[14:15]
	s_nop 0
	v_addc_co_u32_e32 v59, vcc, 0, v137, vcc
	s_mov_b32 s1, 0x48000
	v_cvt_pk_bf16_f32 v65, v60, v61
	global_store_dwordx4 v[58:59], v[62:65], off sc1
	v_cvt_pk_bf16_f32 v50, v50, v51
	v_cvt_pk_bf16_f32 v51, v52, v53
	v_cvt_pk_bf16_f32 v52, v42, v43
	v_cvt_pk_bf16_f32 v53, v44, v45
	global_store_dwordx4 v[66:67], v[50:53], off offset:256 sc1
	s_mov_b64 s[14:15], 0x48000
	v_cvt_pk_bf16_f32 v42, v54, v55
	v_cvt_pk_bf16_f32 v43, v56, v57
	v_cvt_pk_bf16_f32 v44, v46, v47
	v_add_co_u32_e32 v46, vcc, s1, v136
	v_lshl_add_u64 v[50:51], v[136:137], 0, s[14:15]
	s_nop 0
	v_addc_co_u32_e32 v47, vcc, 0, v137, vcc
	s_mov_b32 s1, 0x50000
	v_cvt_pk_bf16_f32 v45, v48, v49
	global_store_dwordx4 v[46:47], v[42:45], off sc1
	v_cvt_pk_bf16_f32 v34, v34, v35
	v_cvt_pk_bf16_f32 v35, v36, v37
	v_cvt_pk_bf16_f32 v36, v26, v27
	v_cvt_pk_bf16_f32 v37, v28, v29
	global_store_dwordx4 v[50:51], v[34:37], off offset:256 sc1
	s_mov_b64 s[14:15], 0x50000
	v_cvt_pk_bf16_f32 v26, v38, v39
	v_cvt_pk_bf16_f32 v27, v40, v41
	v_cvt_pk_bf16_f32 v28, v30, v31
	v_add_co_u32_e32 v30, vcc, s1, v136
	v_lshl_add_u64 v[34:35], v[136:137], 0, s[14:15]
	s_nop 0
	v_addc_co_u32_e32 v31, vcc, 0, v137, vcc
	s_mov_b32 s1, 0x58000
	v_cvt_pk_bf16_f32 v29, v32, v33
	global_store_dwordx4 v[30:31], v[26:29], off sc1
	v_cvt_pk_bf16_f32 v18, v18, v19
	v_cvt_pk_bf16_f32 v19, v20, v21
	v_cvt_pk_bf16_f32 v20, v10, v11
	v_cvt_pk_bf16_f32 v21, v12, v13
	global_store_dwordx4 v[34:35], v[18:21], off offset:256 sc1
	v_cvt_pk_bf16_f32 v10, v22, v23
	v_cvt_pk_bf16_f32 v11, v24, v25
	v_cvt_pk_bf16_f32 v12, v14, v15
	v_add_co_u32_e32 v14, vcc, s1, v136
	s_mov_b64 s[14:15], 0x58000
	s_nop 0
	v_addc_co_u32_e32 v15, vcc, 0, v137, vcc
	v_lshl_add_u64 v[18:19], v[136:137], 0, s[14:15]
	s_and_b64 vcc, exec, s[6:7]
	s_mov_b64 s[14:15], s[10:11]
	v_cvt_pk_bf16_f32 v13, v16, v17
	global_store_dwordx4 v[14:15], v[10:13], off sc1
	v_cvt_pk_bf16_f32 v6, v6, v7
	v_cvt_pk_bf16_f32 v7, v8, v9
	v_cvt_pk_bf16_f32 v8, v2, v3
	v_cvt_pk_bf16_f32 v9, v4, v5
	global_store_dwordx4 v[18:19], v[6:9], off offset:256 sc1
	s_cbranch_vccz .LBB0_808
	s_waitcnt vmcnt(0)
	s_cmpk_gt_u32 s5, 0xff
	v_readlane_b32 s58, v254, 48
	s_cbranch_scc1 .LBB0_815
	s_barrier
